# GEMM phases: per-block s_setprio flips replaced by one static priority raise for the younger wave half (waves 4-7)
# speedup vs baseline: 1.0020x; 1.0020x over previous
; #define PG8_STAGE(bufoff, gbase, voff) do { _Pragma("unroll") for (int _i = 0; _i < 2; ++_i) \
;         __builtin_amdgcn_global_load_lds((const unsigned*)((const char*)(gbase) + (voff)[_i]), (PG8_LAS unsigned*)(lds + (bufoff) + ldsw + _i * 8192), 16, 0, 0); } while (0)
; #define PG8_WAIT_V(n) asm volatile("s_waitcnt vmcnt(" #n ")" ::: "memory")
; #define PG8_BAR __builtin_amdgcn_s_barrier()
; template <class Epi, class Sched, bool ALIGN_EPI = false, bool SP2 = false>
; __device__ __forceinline__ void gemm_phase(PG8_LAS unsigned char* lds, const Gemm g, const Sched& S, const Epi& E) {
;     const int tid = threadIdx.x, wid = __builtin_amdgcn_readfirstlane(tid >> 6), lane = tid & 63, wr = wid >> 2, wc = wid & 3, fr = lane & 15, fq = lane >> 4;
;     const int K = g.K, nt = K / BK;
;     unsigned voffA[2], voffB[2];
; #pragma unroll
;     for (int i = 0; i < 2; ++i) { int R, C; stage_rc(tid * 16 + i * 8192, R, C); const int Rb = Epi::PERM ? ((R & ~31) + perm32(R & 31)) : R;
;         voffA[i] = (unsigned)(R * K + C) * 2u; voffB[i] = (unsigned)(Rb * K + C) * 2u; }
;     const size_t kstep = (size_t)(BK * 2);
;     const size_t hstep = (size_t)HALF * K * 2;
;     const size_t tstep = 2 * hstep;
;     const unsigned ldsw = (unsigned)wid * 1024u;
;     const int aoff = lds_byte(wr * 64 + fr, fq * 8), boff = lds_byte(wc * 32 + fr, fq * 8);
;     ...
;     Unit cur, nxt; int ui = 0;
;     if (!S.next(0, cur)) return;
;     f32x4 acc[2][2][4][2];
; #pragma unroll
;     for (int a = 0; a < 2; ++a)
; #pragma unroll
;         for (int b = 0; b < 2; ++b)
; #pragma unroll
;             for (int m = 0; m < 4; ++m)
; #pragma unroll
;                 for (int n = 0; n < 2; ++n) acc[a][b][m][n] = (f32x4){0.f, 0.f, 0.f, 0.f};
;     bf16x8 At[4][2], B0[2][2], B1[2][2];
;     const char* cA = (const char*)g.A + (size_t)cur.pm * tstep; const char* cB = (const char*)g.Bt + (size_t)cur.pn * tstep;
;     S.a_ready(cur);
;     if constexpr (SP2) {
;         PG8_STAGE(PG8_SB(0, 0), cB, voffB); PG8_STAGE(PG8_SB(0, 1), cB + hstep, voffB); PG8_STAGE(PG8_SA(0, 0), cA, voffA); PG8_STAGE(PG8_SA(0, 1), cA + hstep, voffA);
;         if (wr == 1) PG8_BAR;
;         PG8_WAIT_V(2); PG8_BAR;
.LBB0_129:
	s_cmp_lt_i32 s80, 2
	s_cselect_b64 s[0:1], -1, 0
	s_add_u32 s24, s22, 0xb800000
	s_addc_u32 s25, s23, 0
	s_and_b64 s[4:5], s[0:1], s[4:5]
	s_mov_b32 s19, s84
	s_andn2_b64 vcc, exec, s[4:5]
	s_cbranch_vccnz .LBB0_146
	s_cmp_lt_u32 s82, 4
	s_cbranch_scc1 .Lprio_g1
	s_setprio 1
.Lprio_g1:
	s_cmpk_gt_i32 s84, 0x6bf
	v_readfirstlane_b32 s1, v146
	s_cbranch_scc1 .LBB0_146
	v_lshrrev_b32_e32 v0, 5, v146
	v_lshrrev_b32_e32 v2, 1, v146
	v_and_b32_e32 v0, 4, v0
	v_bfe_u32 v1, v146, 2, 2
	v_and_b32_e32 v11, 24, v2
	v_or3_b32 v0, v0, v1, v11
	v_lshlrev_b32_e32 v1, 4, v146
	v_add_u32_e32 v8, 0x2000, v1
	v_lshrrev_b32_e32 v2, 7, v8
	s_movk_i32 s0, 0xe0
	v_and_b32_e32 v4, 32, v146
	v_and_or_b32 v3, v2, s0, v0
	v_bitop3_b32 v9, v1, v4, 48 bitop3:0x6c
	v_and_b32_e32 v10, 64, v146
	v_bfe_u32 v12, v146, 2, 4
	s_movk_i32 s0, 0xf0
	v_or_b32_e32 v1, v9, v10
	v_and_or_b32 v2, v2, s0, v12
	v_lshl_or_b32 v130, v2, 12, v1
	v_lshrrev_b32_e32 v2, 3, v146
	s_movk_i32 s0, 0x60
	v_and_or_b32 v0, v2, s0, v0
	s_movk_i32 s0, 0x70
	s_ashr_i32 s33, s84, 31
	v_lshl_or_b32 v132, v0, 12, v1
	v_and_or_b32 v0, v2, s0, v12
	s_lshr_b32 s0, s33, 29
	s_add_i32 s0, s84, s0
	s_lshr_b32 s8, s1, 6
	s_ashr_i32 s6, s0, 3
	s_and_b32 s0, s0, -8
	s_lshr_b32 s10, s1, 8
	s_lshl_b32 s3, s8, 10
	s_sub_i32 s0, s84, s0
	s_cmp_lt_i32 s0, 0
	s_movk_i32 s40, 0xd9
	s_cselect_b32 s7, s40, 0xd8
	s_mul_i32 s0, s7, s0
	s_add_i32 s0, s0, s6
	s_mul_hi_i32 s6, s0, 0x4bda12f7
	s_lshr_b32 s7, s6, 31
	s_ashr_i32 s6, s6, 6
	s_add_i32 s6, s6, s7
	s_lshl_b32 s7, s6, 3
	s_mulk_i32 s6, 0xd8
	s_sub_i32 s6, s0, s6
	s_sext_i32_i16 s0, s6
	s_bfe_u32 s0, s0, 0x3001c
	s_add_i32 s9, s6, s0
	s_sext_i32_i16 s0, s9
	s_and_b32 s9, s9, 0xfff8
	s_sub_i32 s6, s6, s9
	s_sext_i32_i16 s6, s6
	s_lshr_b32 s0, s0, 3
	s_add_i32 s30, s7, s6
	s_ashr_i32 s31, s30, 31
	s_bfe_i64 s[12:13], s[0:1], 0x100000
	s_lshl_b64 s[6:7], s[30:31], 20
	s_lshl_b64 s[12:13], s[12:13], 20
	v_readlane_b32 s14, v231, 18
	v_readlane_b32 s15, v231, 19
	s_add_u32 s36, s14, s12
	s_addc_u32 s37, s15, s13
	s_add_i32 s31, s3, 0
	s_add_i32 m0, s31, 0x10000
	v_lshl_or_b32 v128, v3, 12, v1
	global_load_lds_dwordx4 v132, s[36:37]
	s_add_i32 m0, s31, 0x12000
	s_add_u32 s12, s36, 0x80000
	global_load_lds_dwordx4 v128, s[36:37]
	s_addc_u32 s13, s37, 0
	s_add_i32 m0, s31, 0x14000
	v_lshl_or_b32 v134, v0, 12, v1
	global_load_lds_dwordx4 v132, s[12:13]
	s_add_i32 m0, s31, 0x16000
	s_add_u32 s34, s96, s6
	s_addc_u32 s35, s97, s7
	s_add_i32 s41, s31, 0x2000
	global_load_lds_dwordx4 v128, s[12:13]
	s_mov_b32 m0, s31
	s_add_u32 s6, s34, 0x80000
	global_load_lds_dwordx4 v134, s[34:35]
	s_mov_b32 m0, s41
	s_addc_u32 s7, s35, 0
	s_add_i32 s42, s31, 0x4000
	global_load_lds_dwordx4 v130, s[34:35]
	s_mov_b32 m0, s42
	s_add_i32 s43, s31, 0x6000
	global_load_lds_dwordx4 v134, s[6:7]
	s_mov_b32 m0, s43
	v_mov_b32_e32 v133, 0
	global_load_lds_dwordx4 v130, s[6:7]
	v_mov_b32_e32 v129, v133
	v_mov_b32_e32 v135, v133
	v_mov_b32_e32 v131, v133
	s_cmp_eq_u32 s10, 1
	s_mov_b32 s44, 0
	v_lshl_add_u64 v[6:7], s[36:37], 0, v[132:133]
	v_lshl_add_u64 v[4:5], s[36:37], 0, v[128:129]
	v_lshl_add_u64 v[0:1], s[34:35], 0, v[134:135]
	s_cselect_b64 s[6:7], -1, 0
	s_cmp_lg_u32 s10, 1
	v_lshl_add_u64 v[2:3], s[34:35], 0, v[130:131]
	s_cbranch_scc1 .LBB0_133
	s_barrier

; #define PG8_STAGE(bufoff, gbase, voff) do { _Pragma("unroll") for (int _i = 0; _i < 2; ++_i) \
;         __builtin_amdgcn_global_load_lds((const unsigned*)((const char*)(gbase) + (voff)[_i]), (PG8_LAS unsigned*)(lds + (bufoff) + ldsw + _i * 8192), 16, 0, 0); } while (0)
; #define PG8_LDA(dst, b, h) do { _Pragma("unroll") for (int m = 0; m < 4; ++m) _Pragma("unroll") for (int k = 0; k < 2; ++k) dst[m][k] = *(const PG8_LAS bf16x8*)(lds + PG8_SA(b, h) + aoff + m * 2048 + k * 1024); } while (0)
; #define PG8_LDB(dst, b, h) do { _Pragma("unroll") for (int n = 0; n < 2; ++n) _Pragma("unroll") for (int k = 0; k < 2; ++k) dst[n][k] = *(const PG8_LAS bf16x8*)(lds + PG8_SB(b, h) + boff + n * 2048 + k * 1024); } while (0)
; #define PG8_MMA(ai, bj, At, Bt) do { __builtin_amdgcn_s_setprio(1); _Pragma("unroll") for (int m = 0; m < 4; ++m) _Pragma("unroll") for (int n = 0; n < 2; ++n) _Pragma("unroll") for (int k = 0; k < 2; ++k) \
;         acc[ai][bj][m][n] = __builtin_amdgcn_mfma_f32_16x16x32_bf16(Bt[n][k], At[m][k], acc[ai][bj][m][n], 0, 0, 0); __builtin_amdgcn_s_setprio(0); } while (0)
; #define PG8_WAIT_V(n) asm volatile("s_waitcnt vmcnt(" #n ")" ::: "memory")
; #define PG8_WAIT_L(n) asm volatile("s_waitcnt lgkmcnt(" #n ")" ::: "memory")
; #define PG8_BAR __builtin_amdgcn_s_barrier()
; #define PG8_SCHED __builtin_amdgcn_sched_barrier(0)
; template <class Epi, class Sched, bool ALIGN_EPI = false, bool SP2 = false>
; __device__ __forceinline__ void gemm_phase(PG8_LAS unsigned char* lds, const Gemm g, const Sched& S, const Epi& E) {
;     ...
;             PG8_LDB(B0, 0, 0); PG8_LDB(B1, 0, 1); PG8_SCHED; PG8_LDA(At, 0, 0); PG8_STAGE(PG8_SA(1, 1), a1 + hstep, voffA);
;             PG8_WAIT_V(8); PG8_WAIT_L(0); PG8_BAR; PG8_MMA(0, 0, At, B0); PG8_MMA(0, 1, At, B1); PG8_BAR; PG8_SCHED;
;             PG8_LDA(At, 0, 1); PG8_STAGE(PG8_SB(0, 0), b2, voffB); PG8_STAGE(PG8_SB(0, 1), b2 + hstep, voffB); PG8_STAGE(PG8_SA(0, 0), a2, voffA);
;             PG8_WAIT_V(8); PG8_WAIT_L(0); PG8_BAR; PG8_MMA(1, 0, At, B0); PG8_MMA(1, 1, At, B1); PG8_BAR; PG8_SCHED;
.LBB0_139:
	ds_read_b128 v[148:151], v153
	ds_read_b128 v[156:159], v153 offset:1024
	ds_read_b128 v[160:163], v153 offset:2048
	ds_read_b128 v[164:167], v153 offset:3072
	ds_read_b128 v[168:171], v154
	ds_read_b128 v[172:175], v154 offset:1024
	ds_read_b128 v[176:179], v154 offset:2048
	ds_read_b128 v[180:183], v154 offset:3072
	s_add_u32 s36, s34, 0xfff80080
	s_addc_u32 s37, s35, -1
	s_cmp_eq_u32 s56, 28
	s_cselect_b32 s39, s15, s37
	s_cselect_b32 s38, s52, s36
	s_cselect_b32 s37, s13, s55
	s_cselect_b32 s36, s53, s54
	v_lshl_add_u64 v[216:217], s[34:35], 0, v[136:137]
	s_add_i32 m0, s31, 0xc000
	ds_read_b128 v[184:187], v155
	ds_read_b128 v[188:191], v155 offset:1024
	ds_read_b128 v[192:195], v155 offset:2048
	ds_read_b128 v[196:199], v155 offset:3072
	ds_read_b128 v[200:203], v155 offset:4096
	ds_read_b128 v[204:207], v155 offset:5120
	ds_read_b128 v[208:211], v155 offset:6144
	ds_read_b128 v[212:215], v155 offset:7168
	global_load_lds_dwordx4 v[216:217], off
	v_lshl_add_u64 v[216:217], s[34:35], 0, v[138:139]
	s_add_i32 m0, s31, 0xe000
	s_nop 0
	global_load_lds_dwordx4 v[216:217], off
	s_waitcnt vmcnt(8)
	s_waitcnt lgkmcnt(0)
	s_barrier
	s_nop 0
	s_waitcnt lgkmcnt(0)
	v_mfma_f32_16x16x32_bf16 v[124:127], v[148:151], v[184:187], v[124:127]
	v_mfma_f32_16x16x32_bf16 v[120:123], v[160:163], v[184:187], v[120:123]
	v_mfma_f32_16x16x32_bf16 v[116:119], v[148:151], v[192:195], v[116:119]
	v_mfma_f32_16x16x32_bf16 v[108:111], v[160:163], v[192:195], v[108:111]
	v_mfma_f32_16x16x32_bf16 v[100:103], v[148:151], v[200:203], v[100:103]
	v_mfma_f32_16x16x32_bf16 v[92:95], v[160:163], v[200:203], v[92:95]
	v_mfma_f32_16x16x32_bf16 v[84:87], v[148:151], v[208:211], v[84:87]
	v_mfma_f32_16x16x32_bf16 v[76:79], v[160:163], v[208:211], v[76:79]
	v_mfma_f32_16x16x32_bf16 v[124:127], v[156:159], v[188:191], v[124:127]
	v_mfma_f32_16x16x32_bf16 v[120:123], v[164:167], v[188:191], v[120:123]
	v_mfma_f32_16x16x32_bf16 v[116:119], v[156:159], v[196:199], v[116:119]
	v_mfma_f32_16x16x32_bf16 v[108:111], v[164:167], v[196:199], v[108:111]
	v_mfma_f32_16x16x32_bf16 v[100:103], v[156:159], v[204:207], v[100:103]
	v_mfma_f32_16x16x32_bf16 v[92:95], v[164:167], v[204:207], v[92:95]
	v_mfma_f32_16x16x32_bf16 v[84:87], v[156:159], v[212:215], v[84:87]
	v_mfma_f32_16x16x32_bf16 v[76:79], v[164:167], v[212:215], v[76:79]
	s_nop 0
	s_nop 0
	v_mfma_f32_16x16x32_bf16 v[112:115], v[168:171], v[184:187], v[112:115]
	v_mfma_f32_16x16x32_bf16 v[104:107], v[176:179], v[184:187], v[104:107]
	v_mfma_f32_16x16x32_bf16 v[96:99], v[168:171], v[192:195], v[96:99]
	v_mfma_f32_16x16x32_bf16 v[88:91], v[176:179], v[192:195], v[88:91]
	v_mfma_f32_16x16x32_bf16 v[80:83], v[168:171], v[200:203], v[80:83]
	v_mfma_f32_16x16x32_bf16 v[72:75], v[176:179], v[200:203], v[72:75]
	v_mfma_f32_16x16x32_bf16 v[68:71], v[168:171], v[208:211], v[68:71]
	v_mfma_f32_16x16x32_bf16 v[64:67], v[176:179], v[208:211], v[64:67]
	v_mfma_f32_16x16x32_bf16 v[112:115], v[172:175], v[188:191], v[112:115]
	v_mfma_f32_16x16x32_bf16 v[104:107], v[180:183], v[188:191], v[104:107]
	v_mfma_f32_16x16x32_bf16 v[96:99], v[172:175], v[196:199], v[96:99]
	v_mfma_f32_16x16x32_bf16 v[88:91], v[180:183], v[196:199], v[88:91]
	v_mfma_f32_16x16x32_bf16 v[80:83], v[172:175], v[204:207], v[80:83]
	v_mfma_f32_16x16x32_bf16 v[72:75], v[180:183], v[204:207], v[72:75]
	v_mfma_f32_16x16x32_bf16 v[68:71], v[172:175], v[212:215], v[68:71]
	v_mfma_f32_16x16x32_bf16 v[64:67], v[180:183], v[212:215], v[64:67]
	s_nop 0
	s_barrier
	s_add_i32 s57, s48, s3
	v_lshl_add_u64 v[216:217], s[36:37], 0, v[132:133]
	s_mov_b32 m0, s57
	ds_read_b128 v[184:187], v155 offset:16384
	ds_read_b128 v[188:191], v155 offset:17408
	ds_read_b128 v[192:195], v155 offset:18432
	ds_read_b128 v[196:199], v155 offset:19456
	ds_read_b128 v[200:203], v155 offset:20480
	ds_read_b128 v[204:207], v155 offset:21504
	ds_read_b128 v[208:211], v155 offset:22528
	ds_read_b128 v[212:215], v155 offset:23552
	global_load_lds_dwordx4 v[216:217], off
	s_add_i32 m0, s57, 0x2000
	s_add_u32 s58, s36, 0x80000
	v_lshl_add_u64 v[218:219], s[36:37], 0, v[128:129]
	s_addc_u32 s59, s37, 0
	s_add_i32 s57, s49, s3
	global_load_lds_dwordx4 v[218:219], off
	v_lshl_add_u64 v[220:221], s[58:59], 0, v[132:133]
	s_mov_b32 m0, s57
	v_lshl_add_u64 v[222:223], s[38:39], 0, v[130:131]
	global_load_lds_dwordx4 v[220:221], off
	v_lshl_add_u64 v[220:221], s[58:59], 0, v[128:129]
	s_add_i32 m0, s57, 0x2000
	s_nop 0
	global_load_lds_dwordx4 v[220:221], off
	v_lshl_add_u64 v[220:221], s[38:39], 0, v[134:135]
	s_mov_b32 m0, s31
	s_nop 0
	global_load_lds_dwordx4 v[220:221], off
	s_mov_b32 m0, s41
	s_nop 0
	global_load_lds_dwordx4 v[222:223], off
	s_waitcnt vmcnt(8)
	s_waitcnt lgkmcnt(0)
	s_barrier
; #define PG8_STAGE(bufoff, gbase, voff) do { _Pragma("unroll") for (int _i = 0; _i < 2; ++_i) \
;         __builtin_amdgcn_global_load_lds((const unsigned*)((const char*)(gbase) + (voff)[_i]), (PG8_LAS unsigned*)(lds + (bufoff) + ldsw + _i * 8192), 16, 0, 0); } while (0)
; #define PG8_LDA(dst, b, h) do { _Pragma("unroll") for (int m = 0; m < 4; ++m) _Pragma("unroll") for (int k = 0; k < 2; ++k) dst[m][k] = *(const PG8_LAS bf16x8*)(lds + PG8_SA(b, h) + aoff + m * 2048 + k * 1024); } while (0)
; #define PG8_LDB(dst, b, h) do { _Pragma("unroll") for (int n = 0; n < 2; ++n) _Pragma("unroll") for (int k = 0; k < 2; ++k) dst[n][k] = *(const PG8_LAS bf16x8*)(lds + PG8_SB(b, h) + boff + n * 2048 + k * 1024); } while (0)
; #define PG8_MMA(ai, bj, At, Bt) do { __builtin_amdgcn_s_setprio(1); _Pragma("unroll") for (int m = 0; m < 4; ++m) _Pragma("unroll") for (int n = 0; n < 2; ++n) _Pragma("unroll") for (int k = 0; k < 2; ++k) \
;         acc[ai][bj][m][n] = __builtin_amdgcn_mfma_f32_16x16x32_bf16(Bt[n][k], At[m][k], acc[ai][bj][m][n], 0, 0, 0); __builtin_amdgcn_s_setprio(0); } while (0)
; #define PG8_WAIT_V(n) asm volatile("s_waitcnt vmcnt(" #n ")" ::: "memory")
; #define PG8_WAIT_L(n) asm volatile("s_waitcnt lgkmcnt(" #n ")" ::: "memory")
; #define PG8_BAR __builtin_amdgcn_s_barrier()
; #define PG8_SCHED __builtin_amdgcn_sched_barrier(0)
; template <class Epi, class Sched, bool ALIGN_EPI = false, bool SP2 = false>
; __device__ __forceinline__ void gemm_phase(PG8_LAS unsigned char* lds, const Gemm g, const Sched& S, const Epi& E) {
;     ...
;             PG8_WAIT_V(8); PG8_WAIT_L(0); PG8_BAR; PG8_MMA(1, 0, At, B0); PG8_MMA(1, 1, At, B1); PG8_BAR; PG8_SCHED;
;             PG8_LDB(B0, 1, 0); PG8_LDB(B1, 1, 1); PG8_SCHED; PG8_LDA(At, 1, 0); PG8_STAGE(PG8_SA(0, 1), a2 + hstep, voffA);
;             PG8_WAIT_V(8); PG8_WAIT_L(0); PG8_BAR; PG8_MMA(0, 0, At, B0); PG8_MMA(0, 1, At, B1); PG8_BAR; PG8_SCHED;
	s_nop 0
	s_waitcnt lgkmcnt(0)
	v_mfma_f32_16x16x32_bf16 v[60:63], v[148:151], v[184:187], v[60:63]
	v_mfma_f32_16x16x32_bf16 v[56:59], v[160:163], v[184:187], v[56:59]
	v_mfma_f32_16x16x32_bf16 v[52:55], v[148:151], v[192:195], v[52:55]
	v_mfma_f32_16x16x32_bf16 v[44:47], v[160:163], v[192:195], v[44:47]
	v_mfma_f32_16x16x32_bf16 v[36:39], v[148:151], v[200:203], v[36:39]
	v_mfma_f32_16x16x32_bf16 v[28:31], v[160:163], v[200:203], v[28:31]
	v_mfma_f32_16x16x32_bf16 v[20:23], v[148:151], v[208:211], v[20:23]
	v_mfma_f32_16x16x32_bf16 v[12:15], v[160:163], v[208:211], v[12:15]
	v_mfma_f32_16x16x32_bf16 v[60:63], v[156:159], v[188:191], v[60:63]
	v_mfma_f32_16x16x32_bf16 v[56:59], v[164:167], v[188:191], v[56:59]
	v_mfma_f32_16x16x32_bf16 v[52:55], v[156:159], v[196:199], v[52:55]
	v_mfma_f32_16x16x32_bf16 v[44:47], v[164:167], v[196:199], v[44:47]
	v_mfma_f32_16x16x32_bf16 v[36:39], v[156:159], v[204:207], v[36:39]
	v_mfma_f32_16x16x32_bf16 v[28:31], v[164:167], v[204:207], v[28:31]
	v_mfma_f32_16x16x32_bf16 v[20:23], v[156:159], v[212:215], v[20:23]
	v_mfma_f32_16x16x32_bf16 v[12:15], v[164:167], v[212:215], v[12:15]
	s_nop 0
	s_nop 0
	v_mfma_f32_16x16x32_bf16 v[48:51], v[168:171], v[184:187], v[48:51]
	v_mfma_f32_16x16x32_bf16 v[40:43], v[176:179], v[184:187], v[40:43]
	v_mfma_f32_16x16x32_bf16 v[32:35], v[168:171], v[192:195], v[32:35]
	v_mfma_f32_16x16x32_bf16 v[24:27], v[176:179], v[192:195], v[24:27]
	v_mfma_f32_16x16x32_bf16 v[16:19], v[168:171], v[200:203], v[16:19]
	v_mfma_f32_16x16x32_bf16 v[8:11], v[176:179], v[200:203], v[8:11]
	v_mfma_f32_16x16x32_bf16 v[4:7], v[168:171], v[208:211], v[4:7]
	v_mfma_f32_16x16x32_bf16 v[0:3], v[176:179], v[208:211], v[0:3]
	v_mfma_f32_16x16x32_bf16 v[48:51], v[172:175], v[188:191], v[48:51]
	v_mfma_f32_16x16x32_bf16 v[40:43], v[180:183], v[188:191], v[40:43]
	v_mfma_f32_16x16x32_bf16 v[32:35], v[172:175], v[196:199], v[32:35]
	v_mfma_f32_16x16x32_bf16 v[24:27], v[180:183], v[196:199], v[24:27]
	v_mfma_f32_16x16x32_bf16 v[16:19], v[172:175], v[204:207], v[16:19]
	v_mfma_f32_16x16x32_bf16 v[8:11], v[180:183], v[204:207], v[8:11]
	v_mfma_f32_16x16x32_bf16 v[4:7], v[172:175], v[212:215], v[4:7]
	v_mfma_f32_16x16x32_bf16 v[0:3], v[180:183], v[212:215], v[0:3]
	s_nop 0
	s_barrier
	s_add_i32 s57, 0, 0x18000
	s_add_i32 s58, 0, 0x1c000
	v_add_u32_e32 v164, s57, v147
	v_add_u32_e32 v180, s58, v147
	ds_read_b128 v[148:151], v164
	ds_read_b128 v[156:159], v164 offset:1024
	ds_read_b128 v[160:163], v164 offset:2048
	ds_read_b128 v[164:167], v164 offset:3072
	ds_read_b128 v[168:171], v180
	ds_read_b128 v[172:175], v180 offset:1024
	ds_read_b128 v[176:179], v180 offset:2048
	ds_read_b128 v[180:183], v180 offset:3072
	s_add_u32 s38, s38, 0x80000
	s_addc_u32 s39, s39, 0
	s_mov_b32 m0, s42
	v_lshl_add_u64 v[224:225], s[38:39], 0, v[134:135]
	ds_read_b128 v[184:187], v155 offset:32768
	ds_read_b128 v[188:191], v155 offset:33792
	ds_read_b128 v[192:195], v155 offset:34816
	ds_read_b128 v[196:199], v155 offset:35840
	ds_read_b128 v[200:203], v155 offset:36864
	ds_read_b128 v[204:207], v155 offset:37888
	ds_read_b128 v[208:211], v155 offset:38912
	ds_read_b128 v[212:215], v155 offset:39936
	global_load_lds_dwordx4 v[224:225], off
	v_lshl_add_u64 v[224:225], s[38:39], 0, v[130:131]
	s_mov_b32 m0, s43
	s_nop 0
	global_load_lds_dwordx4 v[224:225], off
	s_waitcnt vmcnt(8)
	s_waitcnt lgkmcnt(0)
	s_barrier
	s_nop 0
	s_waitcnt lgkmcnt(0)
	v_mfma_f32_16x16x32_bf16 v[124:127], v[148:151], v[184:187], v[124:127]
	v_mfma_f32_16x16x32_bf16 v[120:123], v[160:163], v[184:187], v[120:123]
	v_mfma_f32_16x16x32_bf16 v[116:119], v[148:151], v[192:195], v[116:119]
	v_mfma_f32_16x16x32_bf16 v[108:111], v[160:163], v[192:195], v[108:111]
	v_mfma_f32_16x16x32_bf16 v[100:103], v[148:151], v[200:203], v[100:103]
	v_mfma_f32_16x16x32_bf16 v[92:95], v[160:163], v[200:203], v[92:95]
	v_mfma_f32_16x16x32_bf16 v[84:87], v[148:151], v[208:211], v[84:87]
	v_mfma_f32_16x16x32_bf16 v[76:79], v[160:163], v[208:211], v[76:79]
	v_mfma_f32_16x16x32_bf16 v[124:127], v[156:159], v[188:191], v[124:127]
	v_mfma_f32_16x16x32_bf16 v[120:123], v[164:167], v[188:191], v[120:123]
	v_mfma_f32_16x16x32_bf16 v[116:119], v[156:159], v[196:199], v[116:119]
	v_mfma_f32_16x16x32_bf16 v[108:111], v[164:167], v[196:199], v[108:111]
	v_mfma_f32_16x16x32_bf16 v[100:103], v[156:159], v[204:207], v[100:103]
	v_mfma_f32_16x16x32_bf16 v[92:95], v[164:167], v[204:207], v[92:95]
	v_mfma_f32_16x16x32_bf16 v[84:87], v[156:159], v[212:215], v[84:87]
	v_mfma_f32_16x16x32_bf16 v[76:79], v[164:167], v[212:215], v[76:79]
	s_nop 0
	s_nop 0
	v_mfma_f32_16x16x32_bf16 v[112:115], v[168:171], v[184:187], v[112:115]
	v_mfma_f32_16x16x32_bf16 v[104:107], v[176:179], v[184:187], v[104:107]
	v_mfma_f32_16x16x32_bf16 v[96:99], v[168:171], v[192:195], v[96:99]
	v_mfma_f32_16x16x32_bf16 v[88:91], v[176:179], v[192:195], v[88:91]
	v_mfma_f32_16x16x32_bf16 v[80:83], v[168:171], v[200:203], v[80:83]
	v_mfma_f32_16x16x32_bf16 v[72:75], v[176:179], v[200:203], v[72:75]
	v_mfma_f32_16x16x32_bf16 v[68:71], v[168:171], v[208:211], v[68:71]
	v_mfma_f32_16x16x32_bf16 v[64:67], v[176:179], v[208:211], v[64:67]
	v_mfma_f32_16x16x32_bf16 v[112:115], v[172:175], v[188:191], v[112:115]
	v_mfma_f32_16x16x32_bf16 v[104:107], v[180:183], v[188:191], v[104:107]
	v_mfma_f32_16x16x32_bf16 v[96:99], v[172:175], v[196:199], v[96:99]
	v_mfma_f32_16x16x32_bf16 v[88:91], v[180:183], v[196:199], v[88:91]
	v_mfma_f32_16x16x32_bf16 v[80:83], v[172:175], v[204:207], v[80:83]
	v_mfma_f32_16x16x32_bf16 v[72:75], v[180:183], v[204:207], v[72:75]
	v_mfma_f32_16x16x32_bf16 v[68:71], v[172:175], v[212:215], v[68:71]
	v_mfma_f32_16x16x32_bf16 v[64:67], v[180:183], v[212:215], v[64:67]
	s_nop 0
	s_barrier
; #define PG8_STAGE(bufoff, gbase, voff) do { _Pragma("unroll") for (int _i = 0; _i < 2; ++_i) \
;         __builtin_amdgcn_global_load_lds((const unsigned*)((const char*)(gbase) + (voff)[_i]), (PG8_LAS unsigned*)(lds + (bufoff) + ldsw + _i * 8192), 16, 0, 0); } while (0)
; #define PG8_LDA(dst, b, h) do { _Pragma("unroll") for (int m = 0; m < 4; ++m) _Pragma("unroll") for (int k = 0; k < 2; ++k) dst[m][k] = *(const PG8_LAS bf16x8*)(lds + PG8_SA(b, h) + aoff + m * 2048 + k * 1024); } while (0)
; #define PG8_MMA(ai, bj, At, Bt) do { __builtin_amdgcn_s_setprio(1); _Pragma("unroll") for (int m = 0; m < 4; ++m) _Pragma("unroll") for (int n = 0; n < 2; ++n) _Pragma("unroll") for (int k = 0; k < 2; ++k) \
;         acc[ai][bj][m][n] = __builtin_amdgcn_mfma_f32_16x16x32_bf16(Bt[n][k], At[m][k], acc[ai][bj][m][n], 0, 0, 0); __builtin_amdgcn_s_setprio(0); } while (0)
; #define PG8_WAIT_V(n) asm volatile("s_waitcnt vmcnt(" #n ")" ::: "memory")
; #define PG8_WAIT_L(n) asm volatile("s_waitcnt lgkmcnt(" #n ")" ::: "memory")
; #define PG8_BAR __builtin_amdgcn_s_barrier()
; #define PG8_SCHED __builtin_amdgcn_sched_barrier(0)
; template <class Epi, class Sched, bool ALIGN_EPI = false, bool SP2 = false>
; __device__ __forceinline__ void gemm_phase(PG8_LAS unsigned char* lds, const Gemm g, const Sched& S, const Epi& E) {
;     ...
;             PG8_LDA(At, 1, 1); PG8_STAGE(PG8_SB(1, 0), b3, voffB); PG8_STAGE(PG8_SB(1, 1), b3 + hstep, voffB); PG8_STAGE(PG8_SA(1, 0), a3, voffA);
;             PG8_WAIT_V(8); PG8_WAIT_L(0); PG8_BAR; PG8_MMA(1, 0, At, B0); PG8_MMA(1, 1, At, B1); PG8_BAR; PG8_SCHED;
	s_add_i32 s38, s57, s3
	v_lshl_add_u64 v[216:217], v[216:217], 0, s[8:9]
	s_mov_b32 m0, s38
	ds_read_b128 v[184:187], v155 offset:49152
	ds_read_b128 v[188:191], v155 offset:50176
	ds_read_b128 v[192:195], v155 offset:51200
	ds_read_b128 v[196:199], v155 offset:52224
	ds_read_b128 v[200:203], v155 offset:53248
	ds_read_b128 v[204:207], v155 offset:54272
	ds_read_b128 v[208:211], v155 offset:55296
	ds_read_b128 v[212:215], v155 offset:56320
	global_load_lds_dwordx4 v[216:217], off
	s_add_i32 m0, s38, 0x2000
	s_add_u32 s36, s36, 0x80080
	v_lshl_add_u64 v[216:217], v[218:219], 0, s[8:9]
	s_addc_u32 s37, s37, 0
	s_add_i32 s38, s58, s3
	global_load_lds_dwordx4 v[216:217], off
	v_lshl_add_u64 v[216:217], s[36:37], 0, v[132:133]
	s_mov_b32 m0, s38
	s_nop 0
	global_load_lds_dwordx4 v[216:217], off
	v_lshl_add_u64 v[216:217], s[36:37], 0, v[128:129]
	s_add_i32 m0, s38, 0x2000
	s_nop 0
	global_load_lds_dwordx4 v[216:217], off
	v_lshl_add_u64 v[216:217], v[220:221], 0, s[8:9]
	s_mov_b32 m0, s45
	s_nop 0
	global_load_lds_dwordx4 v[216:217], off
	v_lshl_add_u64 v[216:217], v[222:223], 0, s[8:9]
	s_mov_b32 m0, s46
	s_nop 0
	global_load_lds_dwordx4 v[216:217], off
	s_waitcnt vmcnt(8)
	s_waitcnt lgkmcnt(0)
	s_barrier
	s_nop 0
	s_waitcnt lgkmcnt(0)
	v_mfma_f32_16x16x32_bf16 v[60:63], v[148:151], v[184:187], v[60:63]
	v_mfma_f32_16x16x32_bf16 v[56:59], v[160:163], v[184:187], v[56:59]
	v_mfma_f32_16x16x32_bf16 v[52:55], v[148:151], v[192:195], v[52:55]
	v_mfma_f32_16x16x32_bf16 v[44:47], v[160:163], v[192:195], v[44:47]
	v_mfma_f32_16x16x32_bf16 v[36:39], v[148:151], v[200:203], v[36:39]
	v_mfma_f32_16x16x32_bf16 v[28:31], v[160:163], v[200:203], v[28:31]
	v_mfma_f32_16x16x32_bf16 v[20:23], v[148:151], v[208:211], v[20:23]
	v_mfma_f32_16x16x32_bf16 v[12:15], v[160:163], v[208:211], v[12:15]
	v_mfma_f32_16x16x32_bf16 v[60:63], v[156:159], v[188:191], v[60:63]
	v_mfma_f32_16x16x32_bf16 v[56:59], v[164:167], v[188:191], v[56:59]
	v_mfma_f32_16x16x32_bf16 v[52:55], v[156:159], v[196:199], v[52:55]
	v_mfma_f32_16x16x32_bf16 v[44:47], v[164:167], v[196:199], v[44:47]
	v_mfma_f32_16x16x32_bf16 v[36:39], v[156:159], v[204:207], v[36:39]
	v_mfma_f32_16x16x32_bf16 v[28:31], v[164:167], v[204:207], v[28:31]
	v_mfma_f32_16x16x32_bf16 v[20:23], v[156:159], v[212:215], v[20:23]
	v_mfma_f32_16x16x32_bf16 v[12:15], v[164:167], v[212:215], v[12:15]
	s_nop 0
	s_nop 0
	v_mfma_f32_16x16x32_bf16 v[48:51], v[168:171], v[184:187], v[48:51]
	v_mfma_f32_16x16x32_bf16 v[40:43], v[176:179], v[184:187], v[40:43]
	v_mfma_f32_16x16x32_bf16 v[32:35], v[168:171], v[192:195], v[32:35]
	v_mfma_f32_16x16x32_bf16 v[24:27], v[176:179], v[192:195], v[24:27]
	v_mfma_f32_16x16x32_bf16 v[16:19], v[168:171], v[200:203], v[16:19]
	v_mfma_f32_16x16x32_bf16 v[8:11], v[176:179], v[200:203], v[8:11]
	v_mfma_f32_16x16x32_bf16 v[4:7], v[168:171], v[208:211], v[4:7]
	v_mfma_f32_16x16x32_bf16 v[0:3], v[176:179], v[208:211], v[0:3]
	v_mfma_f32_16x16x32_bf16 v[48:51], v[172:175], v[188:191], v[48:51]
	v_mfma_f32_16x16x32_bf16 v[40:43], v[180:183], v[188:191], v[40:43]
	v_mfma_f32_16x16x32_bf16 v[32:35], v[172:175], v[196:199], v[32:35]
	v_mfma_f32_16x16x32_bf16 v[24:27], v[180:183], v[196:199], v[24:27]
	v_mfma_f32_16x16x32_bf16 v[16:19], v[172:175], v[204:207], v[16:19]
	v_mfma_f32_16x16x32_bf16 v[8:11], v[180:183], v[204:207], v[8:11]
	v_mfma_f32_16x16x32_bf16 v[4:7], v[172:175], v[212:215], v[4:7]
	v_mfma_f32_16x16x32_bf16 v[0:3], v[180:183], v[212:215], v[0:3]
	s_nop 0
	s_barrier
	s_add_i32 s56, s56, 2
	s_add_u32 s34, s34, 0x100
	s_addc_u32 s35, s35, 0
	s_add_u32 s54, s54, 0x100
	s_addc_u32 s55, s55, 0
	s_cmp_gt_u32 s56, 29
	s_cbranch_scc0 .LBB0_139
	s_and_b64 vcc, exec, s[10:11]
	s_cbranch_vccz .LBB0_142
	s_barrier

; __device__ __forceinline__ void xcd_barrier(const XcdBarrier& b) {
;     asm volatile("s_waitcnt vmcnt(0)" ::: "memory");
;     __syncthreads();
;     if (threadIdx.x == 0) {
;         unsigned* bar = b.bar;
;         __builtin_amdgcn_s_waitcnt(0);
;         unsigned nloc = b.st[0], nx = b.st[1];
;         if (nloc == 0u) { xcd_barrier_complete(bar, b.x, nloc, nx); b.st[0] = nloc; b.st[1] = nx; }
.LBB0_146:
	s_setprio 0
	s_cmp_gt_i32 s81, 2
	s_cselect_b64 s[6:7], -1, 0
	s_and_b64 s[0:1], s[4:5], s[6:7]
	s_andn2_b64 vcc, exec, s[0:1]
	v_cmp_eq_u32_e64 s[0:1], 0, v146
	s_cbranch_vccnz .LBB0_196
	s_waitcnt vmcnt(0)
	s_waitcnt vmcnt(0)
	s_barrier
	s_and_saveexec_b64 s[4:5], s[0:1]
	s_cbranch_execz .LBB0_195
	s_add_i32 s0, 0, 0x20040
	v_mov_b32_e32 v0, s0
	s_waitcnt vmcnt(0) expcnt(0) lgkmcnt(0)
	ds_read_b32 v2, v0
	s_add_i32 s0, 0, 0x20044
	v_mov_b32_e32 v0, s0
	ds_read_b32 v0, v0
	s_waitcnt lgkmcnt(1)
	v_cmp_ne_u32_e32 vcc, 0, v2
	s_cbranch_vccnz .LBB0_163
	v_readlane_b32 s0, v231, 0
	v_readlane_b32 s1, v231, 1
	s_load_dwordx2 s[10:11], s[0:1], 0x4
	s_add_u32 s0, s22, 0x1000
	s_addc_u32 s1, s23, 0
	s_add_u32 s8, s22, 0x1100
	s_addc_u32 s9, s23, 0
	s_waitcnt lgkmcnt(0)
	s_mul_i32 s3, s10, s18
	s_add_u32 s10, s22, 0x1200
	s_mul_i32 s3, s3, s11
	s_addc_u32 s11, s23, 0
	s_add_u32 s12, s22, 0x1300
	s_addc_u32 s13, s23, 0
	s_mov_b32 s30, 1
	v_mov_b32_e32 v16, 0
	s_branch .LBB0_151

; template <class Epi, class Sched, bool ALIGN_EPI = false, bool SP2 = false>
; __device__ __forceinline__ void gemm_phase(PG8_LAS unsigned char* lds, const Gemm g, const Sched& S, const Epi& E) {
;     const int tid = threadIdx.x, wid = __builtin_amdgcn_readfirstlane(tid >> 6), lane = tid & 63, wr = wid >> 2, wc = wid & 3, fr = lane & 15, fq = lane >> 4;
;     const int K = g.K, nt = K / BK;
;     unsigned voffA[2], voffB[2];
; #pragma unroll
;     for (int i = 0; i < 2; ++i) { int R, C; stage_rc(tid * 16 + i * 8192, R, C); const int Rb = Epi::PERM ? ((R & ~31) + perm32(R & 31)) : R;
;         voffA[i] = (unsigned)(R * K + C) * 2u; voffB[i] = (unsigned)(Rb * K + C) * 2u; }
;     const size_t kstep = (size_t)(BK * 2);
;     const size_t hstep = (size_t)HALF * K * 2;
;     const size_t tstep = 2 * hstep;
;     const unsigned ldsw = (unsigned)wid * 1024u;
;     const int aoff = lds_byte(wr * 64 + fr, fq * 8), boff = lds_byte(wc * 32 + fr, fq * 8);
;     ...
;     Unit cur, nxt; int ui = 0;
;     if (!S.next(0, cur)) return;
.LBB0_590:
	s_cmp_lt_i32 s80, 5
	s_cselect_b64 s[4:5], -1, 0
	s_and_b64 s[4:5], s[4:5], s[0:1]
	s_andn2_b64 vcc, exec, s[4:5]
	s_cbranch_vccnz .LBB0_615
	s_cmp_lt_u32 s82, 4
	s_cbranch_scc1 .Lprio_g4
	s_setprio 1
.Lprio_g4:
	s_cmpk_gt_i32 s84, 0x1ff
	v_readfirstlane_b32 s10, v146
	s_cbranch_scc1 .LBB0_615
	s_ashr_i32 s3, s84, 31
	s_lshr_b32 s0, s3, 29
	s_add_i32 s7, s84, s0
	s_and_b32 s0, s7, -8
	s_sub_i32 s8, s84, s0
	s_cmp_gt_i32 s8, -1
	s_cbranch_scc0 .LBB0_594
	s_lshl_b32 s6, s8, 6
	s_cbranch_execz .LBB0_595
	s_branch .LBB0_596

; #define PG8_STAGE(bufoff, gbase, voff) do { _Pragma("unroll") for (int _i = 0; _i < 2; ++_i) \
;         __builtin_amdgcn_global_load_lds((const unsigned*)((const char*)(gbase) + (voff)[_i]), (PG8_LAS unsigned*)(lds + (bufoff) + ldsw + _i * 8192), 16, 0, 0); } while (0)
; #define PG8_LDA(dst, b, h) do { _Pragma("unroll") for (int m = 0; m < 4; ++m) _Pragma("unroll") for (int k = 0; k < 2; ++k) dst[m][k] = *(const PG8_LAS bf16x8*)(lds + PG8_SA(b, h) + aoff + m * 2048 + k * 1024); } while (0)
; #define PG8_LDB(dst, b, h) do { _Pragma("unroll") for (int n = 0; n < 2; ++n) _Pragma("unroll") for (int k = 0; k < 2; ++k) dst[n][k] = *(const PG8_LAS bf16x8*)(lds + PG8_SB(b, h) + boff + n * 2048 + k * 1024); } while (0)
; #define PG8_MMA(ai, bj, At, Bt) do { __builtin_amdgcn_s_setprio(1); _Pragma("unroll") for (int m = 0; m < 4; ++m) _Pragma("unroll") for (int n = 0; n < 2; ++n) _Pragma("unroll") for (int k = 0; k < 2; ++k) \
;         acc[ai][bj][m][n] = __builtin_amdgcn_mfma_f32_16x16x32_bf16(Bt[n][k], At[m][k], acc[ai][bj][m][n], 0, 0, 0); __builtin_amdgcn_s_setprio(0); } while (0)
; #define PG8_WAIT_V(n) asm volatile("s_waitcnt vmcnt(" #n ")" ::: "memory")
; #define PG8_WAIT_L(n) asm volatile("s_waitcnt lgkmcnt(" #n ")" ::: "memory")
; #define PG8_BAR __builtin_amdgcn_s_barrier()
; #define PG8_SCHED __builtin_amdgcn_sched_barrier(0)
; template <class Epi, class Sched, bool ALIGN_EPI = false, bool SP2 = false>
; __device__ __forceinline__ void gemm_phase(PG8_LAS unsigned char* lds, const Gemm g, const Sched& S, const Epi& E) {
;     ...
;             PG8_LDB(B0, 0, 0); PG8_LDB(B1, 0, 1); PG8_SCHED; PG8_LDA(At, 0, 0); PG8_STAGE(PG8_SA(1, 1), a1 + hstep, voffA);
;             PG8_WAIT_V(8); PG8_WAIT_L(0); PG8_BAR; PG8_MMA(0, 0, At, B0); PG8_MMA(0, 1, At, B1); PG8_BAR; PG8_SCHED;
;             PG8_LDA(At, 0, 1); PG8_STAGE(PG8_SB(0, 0), b2, voffB); PG8_STAGE(PG8_SB(0, 1), b2 + hstep, voffB); PG8_STAGE(PG8_SA(0, 0), a2, voffA);
;             PG8_WAIT_V(8); PG8_WAIT_L(0); PG8_BAR; PG8_MMA(1, 0, At, B0); PG8_MMA(1, 1, At, B1); PG8_BAR; PG8_SCHED;
.LBB0_608:
	ds_read_b128 v[154:157], v151
	ds_read_b128 v[158:161], v151 offset:1024
	ds_read_b128 v[162:165], v151 offset:2048
	ds_read_b128 v[166:169], v151 offset:3072
	ds_read_b128 v[170:173], v152
	ds_read_b128 v[174:177], v152 offset:1024
	ds_read_b128 v[178:181], v152 offset:2048
	ds_read_b128 v[182:185], v152 offset:3072
	s_add_u32 s46, s44, 0xfff80080
	s_addc_u32 s47, s45, -1
	s_cmp_eq_u32 s63, 28
	s_cselect_b32 s49, s37, s47
	s_cselect_b32 s48, s59, s46
	s_cselect_b32 s47, s35, s62
	s_cselect_b32 s46, s60, s61
	v_lshl_add_u64 v[148:149], s[44:45], 0, v[136:137]
	s_add_i32 m0, s33, 0xc000
	ds_read_b128 v[186:189], v153
	ds_read_b128 v[190:193], v153 offset:1024
	ds_read_b128 v[194:197], v153 offset:2048
	ds_read_b128 v[198:201], v153 offset:3072
	ds_read_b128 v[202:205], v153 offset:4096
	ds_read_b128 v[206:209], v153 offset:5120
	ds_read_b128 v[210:213], v153 offset:6144
	ds_read_b128 v[214:217], v153 offset:7168
	global_load_lds_dwordx4 v[148:149], off
	v_lshl_add_u64 v[148:149], s[44:45], 0, v[138:139]
	s_add_i32 m0, s33, 0xe000
	s_nop 0
	global_load_lds_dwordx4 v[148:149], off
	s_waitcnt vmcnt(8)
	s_waitcnt lgkmcnt(0)
	s_barrier
	s_nop 0
	s_waitcnt lgkmcnt(0)
	v_mfma_f32_16x16x32_bf16 v[124:127], v[154:157], v[186:189], v[124:127]
	v_mfma_f32_16x16x32_bf16 v[120:123], v[162:165], v[186:189], v[120:123]
	v_mfma_f32_16x16x32_bf16 v[116:119], v[154:157], v[194:197], v[116:119]
	v_mfma_f32_16x16x32_bf16 v[104:107], v[162:165], v[194:197], v[104:107]
	v_mfma_f32_16x16x32_bf16 v[100:103], v[154:157], v[202:205], v[100:103]
	v_mfma_f32_16x16x32_bf16 v[88:91], v[162:165], v[202:205], v[88:91]
	v_mfma_f32_16x16x32_bf16 v[84:87], v[154:157], v[210:213], v[84:87]
	v_mfma_f32_16x16x32_bf16 v[72:75], v[162:165], v[210:213], v[72:75]
	v_mfma_f32_16x16x32_bf16 v[124:127], v[158:161], v[190:193], v[124:127]
	v_mfma_f32_16x16x32_bf16 v[120:123], v[166:169], v[190:193], v[120:123]
	v_mfma_f32_16x16x32_bf16 v[116:119], v[158:161], v[198:201], v[116:119]
	v_mfma_f32_16x16x32_bf16 v[104:107], v[166:169], v[198:201], v[104:107]
	v_mfma_f32_16x16x32_bf16 v[100:103], v[158:161], v[206:209], v[100:103]
	v_mfma_f32_16x16x32_bf16 v[88:91], v[166:169], v[206:209], v[88:91]
	v_mfma_f32_16x16x32_bf16 v[84:87], v[158:161], v[214:217], v[84:87]
	v_mfma_f32_16x16x32_bf16 v[72:75], v[166:169], v[214:217], v[72:75]
	s_nop 0
	s_nop 0
	v_mfma_f32_16x16x32_bf16 v[112:115], v[170:173], v[186:189], v[112:115]
	v_mfma_f32_16x16x32_bf16 v[108:111], v[178:181], v[186:189], v[108:111]
	v_mfma_f32_16x16x32_bf16 v[96:99], v[170:173], v[194:197], v[96:99]
	v_mfma_f32_16x16x32_bf16 v[92:95], v[178:181], v[194:197], v[92:95]
	v_mfma_f32_16x16x32_bf16 v[80:83], v[170:173], v[202:205], v[80:83]
	v_mfma_f32_16x16x32_bf16 v[76:79], v[178:181], v[202:205], v[76:79]
	v_mfma_f32_16x16x32_bf16 v[68:71], v[170:173], v[210:213], v[68:71]
	v_mfma_f32_16x16x32_bf16 v[64:67], v[178:181], v[210:213], v[64:67]
	v_mfma_f32_16x16x32_bf16 v[112:115], v[174:177], v[190:193], v[112:115]
	v_mfma_f32_16x16x32_bf16 v[108:111], v[182:185], v[190:193], v[108:111]
	v_mfma_f32_16x16x32_bf16 v[96:99], v[174:177], v[198:201], v[96:99]
	v_mfma_f32_16x16x32_bf16 v[92:95], v[182:185], v[198:201], v[92:95]
	v_mfma_f32_16x16x32_bf16 v[80:83], v[174:177], v[206:209], v[80:83]
	v_mfma_f32_16x16x32_bf16 v[76:79], v[182:185], v[206:209], v[76:79]
	v_mfma_f32_16x16x32_bf16 v[68:71], v[174:177], v[214:217], v[68:71]
	v_mfma_f32_16x16x32_bf16 v[64:67], v[182:185], v[214:217], v[64:67]
	s_nop 0
	s_barrier
	s_add_i32 s64, s56, s13
	v_lshl_add_u64 v[148:149], s[46:47], 0, v[130:131]
	s_mov_b32 m0, s64
	ds_read_b128 v[186:189], v153 offset:16384
	ds_read_b128 v[190:193], v153 offset:17408
	ds_read_b128 v[194:197], v153 offset:18432
	ds_read_b128 v[198:201], v153 offset:19456
	ds_read_b128 v[202:205], v153 offset:20480
	ds_read_b128 v[206:209], v153 offset:21504
	ds_read_b128 v[210:213], v153 offset:22528
	ds_read_b128 v[214:217], v153 offset:23552
	global_load_lds_dwordx4 v[148:149], off
	s_add_i32 m0, s64, 0x2000
	s_add_u32 s64, s46, 0x80000
	v_lshl_add_u64 v[218:219], s[46:47], 0, v[134:135]
	s_addc_u32 s65, s47, 0
	s_add_i32 s66, s57, s13
	global_load_lds_dwordx4 v[218:219], off
	v_lshl_add_u64 v[220:221], s[64:65], 0, v[130:131]
	s_mov_b32 m0, s66
	v_lshl_add_u64 v[222:223], s[48:49], 0, v[132:133]
	global_load_lds_dwordx4 v[220:221], off
	v_lshl_add_u64 v[220:221], s[64:65], 0, v[134:135]
	s_add_i32 m0, s66, 0x2000
	s_nop 0
	global_load_lds_dwordx4 v[220:221], off
	v_lshl_add_u64 v[220:221], s[48:49], 0, v[128:129]
	s_mov_b32 m0, s33
	s_nop 0
	global_load_lds_dwordx4 v[220:221], off
	s_mov_b32 m0, s43
	s_nop 0
	global_load_lds_dwordx4 v[222:223], off
	s_waitcnt vmcnt(8)
	s_waitcnt lgkmcnt(0)
	s_barrier
; #define PG8_STAGE(bufoff, gbase, voff) do { _Pragma("unroll") for (int _i = 0; _i < 2; ++_i) \
;         __builtin_amdgcn_global_load_lds((const unsigned*)((const char*)(gbase) + (voff)[_i]), (PG8_LAS unsigned*)(lds + (bufoff) + ldsw + _i * 8192), 16, 0, 0); } while (0)
; #define PG8_LDA(dst, b, h) do { _Pragma("unroll") for (int m = 0; m < 4; ++m) _Pragma("unroll") for (int k = 0; k < 2; ++k) dst[m][k] = *(const PG8_LAS bf16x8*)(lds + PG8_SA(b, h) + aoff + m * 2048 + k * 1024); } while (0)
; #define PG8_LDB(dst, b, h) do { _Pragma("unroll") for (int n = 0; n < 2; ++n) _Pragma("unroll") for (int k = 0; k < 2; ++k) dst[n][k] = *(const PG8_LAS bf16x8*)(lds + PG8_SB(b, h) + boff + n * 2048 + k * 1024); } while (0)
; #define PG8_MMA(ai, bj, At, Bt) do { __builtin_amdgcn_s_setprio(1); _Pragma("unroll") for (int m = 0; m < 4; ++m) _Pragma("unroll") for (int n = 0; n < 2; ++n) _Pragma("unroll") for (int k = 0; k < 2; ++k) \
;         acc[ai][bj][m][n] = __builtin_amdgcn_mfma_f32_16x16x32_bf16(Bt[n][k], At[m][k], acc[ai][bj][m][n], 0, 0, 0); __builtin_amdgcn_s_setprio(0); } while (0)
; #define PG8_WAIT_V(n) asm volatile("s_waitcnt vmcnt(" #n ")" ::: "memory")
; #define PG8_WAIT_L(n) asm volatile("s_waitcnt lgkmcnt(" #n ")" ::: "memory")
; #define PG8_BAR __builtin_amdgcn_s_barrier()
; #define PG8_SCHED __builtin_amdgcn_sched_barrier(0)
; template <class Epi, class Sched, bool ALIGN_EPI = false, bool SP2 = false>
; __device__ __forceinline__ void gemm_phase(PG8_LAS unsigned char* lds, const Gemm g, const Sched& S, const Epi& E) {
;     ...
;             PG8_WAIT_V(8); PG8_WAIT_L(0); PG8_BAR; PG8_MMA(1, 0, At, B0); PG8_MMA(1, 1, At, B1); PG8_BAR; PG8_SCHED;
;             PG8_LDB(B0, 1, 0); PG8_LDB(B1, 1, 1); PG8_SCHED; PG8_LDA(At, 1, 0); PG8_STAGE(PG8_SA(0, 1), a2 + hstep, voffA);
;             PG8_WAIT_V(8); PG8_WAIT_L(0); PG8_BAR; PG8_MMA(0, 0, At, B0); PG8_MMA(0, 1, At, B1); PG8_BAR; PG8_SCHED;
	s_nop 0
	s_waitcnt lgkmcnt(0)
	v_mfma_f32_16x16x32_bf16 v[60:63], v[154:157], v[186:189], v[60:63]
	v_mfma_f32_16x16x32_bf16 v[56:59], v[162:165], v[186:189], v[56:59]
	v_mfma_f32_16x16x32_bf16 v[52:55], v[154:157], v[194:197], v[52:55]
	v_mfma_f32_16x16x32_bf16 v[40:43], v[162:165], v[194:197], v[40:43]
	v_mfma_f32_16x16x32_bf16 v[36:39], v[154:157], v[202:205], v[36:39]
	v_mfma_f32_16x16x32_bf16 v[24:27], v[162:165], v[202:205], v[24:27]
	v_mfma_f32_16x16x32_bf16 v[20:23], v[154:157], v[210:213], v[20:23]
	v_mfma_f32_16x16x32_bf16 v[8:11], v[162:165], v[210:213], v[8:11]
	v_mfma_f32_16x16x32_bf16 v[60:63], v[158:161], v[190:193], v[60:63]
	v_mfma_f32_16x16x32_bf16 v[56:59], v[166:169], v[190:193], v[56:59]
	v_mfma_f32_16x16x32_bf16 v[52:55], v[158:161], v[198:201], v[52:55]
	v_mfma_f32_16x16x32_bf16 v[40:43], v[166:169], v[198:201], v[40:43]
	v_mfma_f32_16x16x32_bf16 v[36:39], v[158:161], v[206:209], v[36:39]
	v_mfma_f32_16x16x32_bf16 v[24:27], v[166:169], v[206:209], v[24:27]
	v_mfma_f32_16x16x32_bf16 v[20:23], v[158:161], v[214:217], v[20:23]
	v_mfma_f32_16x16x32_bf16 v[8:11], v[166:169], v[214:217], v[8:11]
	s_nop 0
	s_nop 0
	v_mfma_f32_16x16x32_bf16 v[48:51], v[170:173], v[186:189], v[48:51]
	v_mfma_f32_16x16x32_bf16 v[44:47], v[178:181], v[186:189], v[44:47]
	v_mfma_f32_16x16x32_bf16 v[32:35], v[170:173], v[194:197], v[32:35]
	v_mfma_f32_16x16x32_bf16 v[28:31], v[178:181], v[194:197], v[28:31]
	v_mfma_f32_16x16x32_bf16 v[16:19], v[170:173], v[202:205], v[16:19]
	v_mfma_f32_16x16x32_bf16 v[12:15], v[178:181], v[202:205], v[12:15]
	v_mfma_f32_16x16x32_bf16 v[4:7], v[170:173], v[210:213], v[4:7]
	v_mfma_f32_16x16x32_bf16 v[0:3], v[178:181], v[210:213], v[0:3]
	v_mfma_f32_16x16x32_bf16 v[48:51], v[174:177], v[190:193], v[48:51]
	v_mfma_f32_16x16x32_bf16 v[44:47], v[182:185], v[190:193], v[44:47]
	v_mfma_f32_16x16x32_bf16 v[32:35], v[174:177], v[198:201], v[32:35]
	v_mfma_f32_16x16x32_bf16 v[28:31], v[182:185], v[198:201], v[28:31]
	v_mfma_f32_16x16x32_bf16 v[16:19], v[174:177], v[206:209], v[16:19]
	v_mfma_f32_16x16x32_bf16 v[12:15], v[182:185], v[206:209], v[12:15]
	v_mfma_f32_16x16x32_bf16 v[4:7], v[174:177], v[214:217], v[4:7]
	v_mfma_f32_16x16x32_bf16 v[0:3], v[182:185], v[214:217], v[0:3]
	s_nop 0
	s_barrier
	s_add_i32 s64, 0, 0x18000
	s_add_i32 s65, 0, 0x1c000
	v_add_u32_e32 v166, s64, v147
	v_add_u32_e32 v182, s65, v147
	ds_read_b128 v[154:157], v166
	ds_read_b128 v[158:161], v166 offset:1024
	ds_read_b128 v[162:165], v166 offset:2048
	ds_read_b128 v[166:169], v166 offset:3072
	ds_read_b128 v[170:173], v182
	ds_read_b128 v[174:177], v182 offset:1024
	ds_read_b128 v[178:181], v182 offset:2048
	ds_read_b128 v[182:185], v182 offset:3072
	s_add_u32 s48, s48, 0x80000
	s_addc_u32 s49, s49, 0
	s_mov_b32 m0, s50
	v_lshl_add_u64 v[224:225], s[48:49], 0, v[128:129]
	ds_read_b128 v[186:189], v153 offset:32768
	ds_read_b128 v[190:193], v153 offset:33792
	ds_read_b128 v[194:197], v153 offset:34816
	ds_read_b128 v[198:201], v153 offset:35840
	ds_read_b128 v[202:205], v153 offset:36864
	ds_read_b128 v[206:209], v153 offset:37888
	ds_read_b128 v[210:213], v153 offset:38912
	ds_read_b128 v[214:217], v153 offset:39936
	global_load_lds_dwordx4 v[224:225], off
	v_lshl_add_u64 v[224:225], s[48:49], 0, v[132:133]
	s_mov_b32 m0, s51
	s_nop 0
	global_load_lds_dwordx4 v[224:225], off
	s_waitcnt vmcnt(8)
	s_waitcnt lgkmcnt(0)
	s_barrier
	s_nop 0
	s_waitcnt lgkmcnt(0)
	v_mfma_f32_16x16x32_bf16 v[124:127], v[154:157], v[186:189], v[124:127]
	v_mfma_f32_16x16x32_bf16 v[120:123], v[162:165], v[186:189], v[120:123]
	v_mfma_f32_16x16x32_bf16 v[116:119], v[154:157], v[194:197], v[116:119]
	v_mfma_f32_16x16x32_bf16 v[104:107], v[162:165], v[194:197], v[104:107]
	v_mfma_f32_16x16x32_bf16 v[100:103], v[154:157], v[202:205], v[100:103]
	v_mfma_f32_16x16x32_bf16 v[88:91], v[162:165], v[202:205], v[88:91]
	v_mfma_f32_16x16x32_bf16 v[84:87], v[154:157], v[210:213], v[84:87]
	v_mfma_f32_16x16x32_bf16 v[72:75], v[162:165], v[210:213], v[72:75]
	v_mfma_f32_16x16x32_bf16 v[124:127], v[158:161], v[190:193], v[124:127]
	v_mfma_f32_16x16x32_bf16 v[120:123], v[166:169], v[190:193], v[120:123]
	v_mfma_f32_16x16x32_bf16 v[116:119], v[158:161], v[198:201], v[116:119]
	v_mfma_f32_16x16x32_bf16 v[104:107], v[166:169], v[198:201], v[104:107]
	v_mfma_f32_16x16x32_bf16 v[100:103], v[158:161], v[206:209], v[100:103]
	v_mfma_f32_16x16x32_bf16 v[88:91], v[166:169], v[206:209], v[88:91]
	v_mfma_f32_16x16x32_bf16 v[84:87], v[158:161], v[214:217], v[84:87]
	v_mfma_f32_16x16x32_bf16 v[72:75], v[166:169], v[214:217], v[72:75]
	s_nop 0
	s_nop 0
	v_mfma_f32_16x16x32_bf16 v[112:115], v[170:173], v[186:189], v[112:115]
	v_mfma_f32_16x16x32_bf16 v[108:111], v[178:181], v[186:189], v[108:111]
	v_mfma_f32_16x16x32_bf16 v[96:99], v[170:173], v[194:197], v[96:99]
	v_mfma_f32_16x16x32_bf16 v[92:95], v[178:181], v[194:197], v[92:95]
	v_mfma_f32_16x16x32_bf16 v[80:83], v[170:173], v[202:205], v[80:83]
	v_mfma_f32_16x16x32_bf16 v[76:79], v[178:181], v[202:205], v[76:79]
	v_mfma_f32_16x16x32_bf16 v[68:71], v[170:173], v[210:213], v[68:71]
	v_mfma_f32_16x16x32_bf16 v[64:67], v[178:181], v[210:213], v[64:67]
	v_mfma_f32_16x16x32_bf16 v[112:115], v[174:177], v[190:193], v[112:115]
	v_mfma_f32_16x16x32_bf16 v[108:111], v[182:185], v[190:193], v[108:111]
	v_mfma_f32_16x16x32_bf16 v[96:99], v[174:177], v[198:201], v[96:99]
	v_mfma_f32_16x16x32_bf16 v[92:95], v[182:185], v[198:201], v[92:95]
	v_mfma_f32_16x16x32_bf16 v[80:83], v[174:177], v[206:209], v[80:83]
	v_mfma_f32_16x16x32_bf16 v[76:79], v[182:185], v[206:209], v[76:79]
	v_mfma_f32_16x16x32_bf16 v[68:71], v[174:177], v[214:217], v[68:71]
	v_mfma_f32_16x16x32_bf16 v[64:67], v[182:185], v[214:217], v[64:67]
	s_nop 0
	s_barrier
; #define PG8_STAGE(bufoff, gbase, voff) do { _Pragma("unroll") for (int _i = 0; _i < 2; ++_i) \
;         __builtin_amdgcn_global_load_lds((const unsigned*)((const char*)(gbase) + (voff)[_i]), (PG8_LAS unsigned*)(lds + (bufoff) + ldsw + _i * 8192), 16, 0, 0); } while (0)
; #define PG8_LDA(dst, b, h) do { _Pragma("unroll") for (int m = 0; m < 4; ++m) _Pragma("unroll") for (int k = 0; k < 2; ++k) dst[m][k] = *(const PG8_LAS bf16x8*)(lds + PG8_SA(b, h) + aoff + m * 2048 + k * 1024); } while (0)
; #define PG8_MMA(ai, bj, At, Bt) do { __builtin_amdgcn_s_setprio(1); _Pragma("unroll") for (int m = 0; m < 4; ++m) _Pragma("unroll") for (int n = 0; n < 2; ++n) _Pragma("unroll") for (int k = 0; k < 2; ++k) \
;         acc[ai][bj][m][n] = __builtin_amdgcn_mfma_f32_16x16x32_bf16(Bt[n][k], At[m][k], acc[ai][bj][m][n], 0, 0, 0); __builtin_amdgcn_s_setprio(0); } while (0)
; #define PG8_WAIT_V(n) asm volatile("s_waitcnt vmcnt(" #n ")" ::: "memory")
; #define PG8_WAIT_L(n) asm volatile("s_waitcnt lgkmcnt(" #n ")" ::: "memory")
; #define PG8_BAR __builtin_amdgcn_s_barrier()
; #define PG8_SCHED __builtin_amdgcn_sched_barrier(0)
; template <class Epi, class Sched, bool ALIGN_EPI = false, bool SP2 = false>
; __device__ __forceinline__ void gemm_phase(PG8_LAS unsigned char* lds, const Gemm g, const Sched& S, const Epi& E) {
;     ...
;             PG8_LDA(At, 1, 1); PG8_STAGE(PG8_SB(1, 0), b3, voffB); PG8_STAGE(PG8_SB(1, 1), b3 + hstep, voffB); PG8_STAGE(PG8_SA(1, 0), a3, voffA);
;             PG8_WAIT_V(8); PG8_WAIT_L(0); PG8_BAR; PG8_MMA(1, 0, At, B0); PG8_MMA(1, 1, At, B1); PG8_BAR; PG8_SCHED;
	s_add_i32 s48, s64, s13
	v_lshl_add_u64 v[148:149], v[148:149], 0, s[8:9]
	s_mov_b32 m0, s48
	ds_read_b128 v[186:189], v153 offset:49152
	ds_read_b128 v[190:193], v153 offset:50176
	ds_read_b128 v[194:197], v153 offset:51200
	ds_read_b128 v[198:201], v153 offset:52224
	ds_read_b128 v[202:205], v153 offset:53248
	ds_read_b128 v[206:209], v153 offset:54272
	ds_read_b128 v[210:213], v153 offset:55296
	ds_read_b128 v[214:217], v153 offset:56320
	global_load_lds_dwordx4 v[148:149], off
	s_add_i32 m0, s48, 0x2000
	s_add_u32 s46, s46, 0x80080
	v_lshl_add_u64 v[148:149], v[218:219], 0, s[8:9]
	s_addc_u32 s47, s47, 0
	s_add_i32 s48, s65, s13
	global_load_lds_dwordx4 v[148:149], off
	v_lshl_add_u64 v[148:149], s[46:47], 0, v[130:131]
	s_mov_b32 m0, s48
	s_nop 0
	global_load_lds_dwordx4 v[148:149], off
	v_lshl_add_u64 v[148:149], s[46:47], 0, v[134:135]
	s_add_i32 m0, s48, 0x2000
	s_nop 0
	global_load_lds_dwordx4 v[148:149], off
	v_lshl_add_u64 v[148:149], v[220:221], 0, s[8:9]
	s_mov_b32 m0, s53
	s_nop 0
	global_load_lds_dwordx4 v[148:149], off
	v_lshl_add_u64 v[148:149], v[222:223], 0, s[8:9]
	s_mov_b32 m0, s54
	s_nop 0
	global_load_lds_dwordx4 v[148:149], off
	s_waitcnt vmcnt(8)
	s_waitcnt lgkmcnt(0)
	s_barrier
	s_nop 0
	s_waitcnt lgkmcnt(0)
	v_mfma_f32_16x16x32_bf16 v[60:63], v[154:157], v[186:189], v[60:63]
	v_mfma_f32_16x16x32_bf16 v[56:59], v[162:165], v[186:189], v[56:59]
	v_mfma_f32_16x16x32_bf16 v[52:55], v[154:157], v[194:197], v[52:55]
	v_mfma_f32_16x16x32_bf16 v[40:43], v[162:165], v[194:197], v[40:43]
	v_mfma_f32_16x16x32_bf16 v[36:39], v[154:157], v[202:205], v[36:39]
	v_mfma_f32_16x16x32_bf16 v[24:27], v[162:165], v[202:205], v[24:27]
	v_mfma_f32_16x16x32_bf16 v[20:23], v[154:157], v[210:213], v[20:23]
	v_mfma_f32_16x16x32_bf16 v[8:11], v[162:165], v[210:213], v[8:11]
	v_mfma_f32_16x16x32_bf16 v[60:63], v[158:161], v[190:193], v[60:63]
	v_mfma_f32_16x16x32_bf16 v[56:59], v[166:169], v[190:193], v[56:59]
	v_mfma_f32_16x16x32_bf16 v[52:55], v[158:161], v[198:201], v[52:55]
	v_mfma_f32_16x16x32_bf16 v[40:43], v[166:169], v[198:201], v[40:43]
	v_mfma_f32_16x16x32_bf16 v[36:39], v[158:161], v[206:209], v[36:39]
	v_mfma_f32_16x16x32_bf16 v[24:27], v[166:169], v[206:209], v[24:27]
	v_mfma_f32_16x16x32_bf16 v[20:23], v[158:161], v[214:217], v[20:23]
	v_mfma_f32_16x16x32_bf16 v[8:11], v[166:169], v[214:217], v[8:11]
	s_nop 0
	s_nop 0
	v_mfma_f32_16x16x32_bf16 v[48:51], v[170:173], v[186:189], v[48:51]
	v_mfma_f32_16x16x32_bf16 v[44:47], v[178:181], v[186:189], v[44:47]
	v_mfma_f32_16x16x32_bf16 v[32:35], v[170:173], v[194:197], v[32:35]
	v_mfma_f32_16x16x32_bf16 v[28:31], v[178:181], v[194:197], v[28:31]
	v_mfma_f32_16x16x32_bf16 v[16:19], v[170:173], v[202:205], v[16:19]
	v_mfma_f32_16x16x32_bf16 v[12:15], v[178:181], v[202:205], v[12:15]
	v_mfma_f32_16x16x32_bf16 v[4:7], v[170:173], v[210:213], v[4:7]
	v_mfma_f32_16x16x32_bf16 v[0:3], v[178:181], v[210:213], v[0:3]
	v_mfma_f32_16x16x32_bf16 v[48:51], v[174:177], v[190:193], v[48:51]
	v_mfma_f32_16x16x32_bf16 v[44:47], v[182:185], v[190:193], v[44:47]
	v_mfma_f32_16x16x32_bf16 v[32:35], v[174:177], v[198:201], v[32:35]
	v_mfma_f32_16x16x32_bf16 v[28:31], v[182:185], v[198:201], v[28:31]
	v_mfma_f32_16x16x32_bf16 v[16:19], v[174:177], v[206:209], v[16:19]
	v_mfma_f32_16x16x32_bf16 v[12:15], v[182:185], v[206:209], v[12:15]
	v_mfma_f32_16x16x32_bf16 v[4:7], v[174:177], v[214:217], v[4:7]
	v_mfma_f32_16x16x32_bf16 v[0:3], v[182:185], v[214:217], v[0:3]
	s_nop 0
	s_barrier
	s_add_i32 s63, s63, 2
	s_add_u32 s44, s44, 0x100
	s_addc_u32 s45, s45, 0
	s_add_u32 s61, s61, 0x100
	s_addc_u32 s62, s62, 0
	s_cmp_gt_u32 s63, 29
	s_cbranch_scc0 .LBB0_608
	s_and_b64 vcc, exec, s[10:11]
	s_cbranch_vccz .LBB0_611
	s_barrier

; __device__ __forceinline__ void xcd_barrier(const XcdBarrier& b) {
;     asm volatile("s_waitcnt vmcnt(0)" ::: "memory");
;     __syncthreads();
;     if (threadIdx.x == 0) {
;         unsigned* bar = b.bar;
;         __builtin_amdgcn_s_waitcnt(0);
;         unsigned nloc = b.st[0], nx = b.st[1];
;         if (nloc == 0u) { xcd_barrier_complete(bar, b.x, nloc, nx); b.st[0] = nloc; b.st[1] = nx; }
.LBB0_615:
	s_setprio 0
	s_cmp_gt_i32 s81, 5
	s_cselect_b64 s[0:1], -1, 0
	s_and_b64 s[4:5], s[4:5], s[0:1]
	s_andn2_b64 vcc, exec, s[4:5]
	s_cbranch_vccnz .LBB0_665
	s_waitcnt vmcnt(0)
	v_cmp_eq_u32_e32 vcc, 0, v146
	s_waitcnt vmcnt(0) lgkmcnt(0)
	s_barrier
	s_and_saveexec_b64 s[4:5], vcc
	s_cbranch_execz .LBB0_664
	s_add_i32 s3, 0, 0x20040
	v_mov_b32_e32 v0, s3
	s_waitcnt vmcnt(0) expcnt(0) lgkmcnt(0)
	ds_read_b32 v2, v0
	s_add_i32 s3, 0, 0x20044
	v_mov_b32_e32 v0, s3
	ds_read_b32 v0, v0
	s_waitcnt lgkmcnt(1)
	v_cmp_ne_u32_e32 vcc, 0, v2
	s_cbranch_vccnz .LBB0_632
	v_readlane_b32 s2, v231, 0
	v_readlane_b32 s3, v231, 1
	s_load_dwordx2 s[10:11], s[2:3], 0x4
	s_add_u32 s6, s22, 0x1000
	s_addc_u32 s7, s23, 0
	s_add_u32 s8, s22, 0x1100
	s_addc_u32 s9, s23, 0
	s_waitcnt lgkmcnt(0)
	s_mul_i32 s3, s10, s18
	s_add_u32 s10, s22, 0x1200
	s_mul_i32 s3, s3, s11
	s_addc_u32 s11, s23, 0
	s_add_u32 s12, s22, 0x1300
	s_addc_u32 s13, s23, 0
	s_mov_b32 s30, 1
	v_mov_b32_e32 v16, 0
	s_branch .LBB0_620

; #define PG8_STAGE(bufoff, gbase, voff) do { _Pragma("unroll") for (int _i = 0; _i < 2; ++_i) \
;         __builtin_amdgcn_global_load_lds((const unsigned*)((const char*)(gbase) + (voff)[_i]), (PG8_LAS unsigned*)(lds + (bufoff) + ldsw + _i * 8192), 16, 0, 0); } while (0)
; #define PG8_WAIT_V(n) asm volatile("s_waitcnt vmcnt(" #n ")" ::: "memory")
; #define PG8_BAR __builtin_amdgcn_s_barrier()
; template <class Epi, class Sched, bool ALIGN_EPI = false, bool SP2 = false>
; __device__ __forceinline__ void gemm_phase(PG8_LAS unsigned char* lds, const Gemm g, const Sched& S, const Epi& E) {
;     const int tid = threadIdx.x, wid = __builtin_amdgcn_readfirstlane(tid >> 6), lane = tid & 63, wr = wid >> 2, wc = wid & 3, fr = lane & 15, fq = lane >> 4;
;     const int K = g.K, nt = K / BK;
;     unsigned voffA[2], voffB[2];
; #pragma unroll
;     for (int i = 0; i < 2; ++i) { int R, C; stage_rc(tid * 16 + i * 8192, R, C); const int Rb = Epi::PERM ? ((R & ~31) + perm32(R & 31)) : R;
;         voffA[i] = (unsigned)(R * K + C) * 2u; voffB[i] = (unsigned)(Rb * K + C) * 2u; }
;     const size_t kstep = (size_t)(BK * 2);
;     const size_t hstep = (size_t)HALF * K * 2;
;     const size_t tstep = 2 * hstep;
;     const unsigned ldsw = (unsigned)wid * 1024u;
;     const int aoff = lds_byte(wr * 64 + fr, fq * 8), boff = lds_byte(wc * 32 + fr, fq * 8);
;     ...
;     Unit cur, nxt; int ui = 0;
;     if (!S.next(0, cur)) return;
;     f32x4 acc[2][2][4][2];
; #pragma unroll
;     for (int a = 0; a < 2; ++a)
; #pragma unroll
;         for (int b = 0; b < 2; ++b)
; #pragma unroll
;             for (int m = 0; m < 4; ++m)
; #pragma unroll
;                 for (int n = 0; n < 2; ++n) acc[a][b][m][n] = (f32x4){0.f, 0.f, 0.f, 0.f};
;     bf16x8 At[4][2], B0[2][2], B1[2][2];
;     const char* cA = (const char*)g.A + (size_t)cur.pm * tstep; const char* cB = (const char*)g.Bt + (size_t)cur.pn * tstep;
;     S.a_ready(cur);
;     if constexpr (SP2) {
;         PG8_STAGE(PG8_SB(0, 0), cB, voffB); PG8_STAGE(PG8_SB(0, 1), cB + hstep, voffB); PG8_STAGE(PG8_SA(0, 0), cA, voffA); PG8_STAGE(PG8_SA(0, 1), cA + hstep, voffA);
;         if (wr == 1) PG8_BAR;
;         PG8_WAIT_V(2); PG8_BAR;
.LBB0_723:
	s_cmp_lt_i32 s80, 7
	s_cselect_b64 s[4:5], -1, 0
	s_and_b64 s[4:5], s[4:5], s[0:1]
	s_andn2_b64 vcc, exec, s[4:5]
	s_cbranch_vccnz .LBB0_740
	s_cmp_lt_u32 s82, 4
	s_cbranch_scc1 .Lprio_g6
	s_setprio 1
.Lprio_g6:
	s_cmpk_gt_i32 s84, 0x7ff
	v_readfirstlane_b32 s1, v146
	s_cbranch_scc1 .LBB0_740
	v_lshrrev_b32_e32 v0, 5, v146
	v_lshrrev_b32_e32 v2, 1, v146
	v_and_b32_e32 v0, 4, v0
	v_bfe_u32 v1, v146, 2, 2
	v_and_b32_e32 v11, 24, v2
	v_or3_b32 v0, v0, v1, v11
	v_lshlrev_b32_e32 v1, 4, v146
	s_waitcnt lgkmcnt(0)
	v_add_u32_e32 v8, 0x2000, v1
	v_lshrrev_b32_e32 v2, 7, v8
	s_movk_i32 s0, 0xe0
	v_and_b32_e32 v4, 32, v146
	v_and_or_b32 v3, v2, s0, v0
	v_bitop3_b32 v9, v1, v4, 48 bitop3:0x6c
	v_and_b32_e32 v10, 64, v146
	v_bfe_u32 v12, v146, 2, 4
	s_movk_i32 s0, 0xf0
	v_or_b32_e32 v1, v9, v10
	v_and_or_b32 v2, v2, s0, v12
	s_waitcnt vmcnt(0)
	v_lshl_or_b32 v130, v2, 12, v1
	v_lshrrev_b32_e32 v2, 3, v146
	s_movk_i32 s0, 0x60
	v_and_or_b32 v0, v2, s0, v0
	s_movk_i32 s0, 0x70
	s_ashr_i32 s33, s84, 31
	v_lshl_or_b32 v132, v0, 12, v1
	v_and_or_b32 v0, v2, s0, v12
	s_lshr_b32 s0, s33, 29
	s_add_i32 s0, s84, s0
	s_lshr_b32 s8, s1, 6
	s_ashr_i32 s6, s0, 3
	s_and_b32 s0, s0, -8
	s_lshr_b32 s10, s1, 8
	s_lshl_b32 s3, s8, 10
	s_sub_i32 s0, s84, s0
	s_cmp_lt_i32 s0, 0
	s_movk_i32 s48, 0x101
	s_cselect_b32 s7, s48, 0x100
	s_mul_i32 s0, s7, s0
	s_add_i32 s0, s0, s6
	s_ashr_i32 s6, s0, 31
	s_lshr_b32 s6, s6, 24
	s_add_i32 s6, s0, s6
	s_ashr_i32 s7, s6, 8
	s_and_b32 s6, s6, 0xffffff00
	s_sub_i32 s6, s0, s6
	s_sext_i32_i16 s0, s6
	s_bfe_u32 s0, s0, 0x3001c
	s_add_i32 s9, s6, s0
	s_sext_i32_i16 s0, s9
	s_and_b32 s9, s9, 0xfff8
	s_sub_i32 s6, s6, s9
	s_lshl_b32 s7, s7, 3
	s_sext_i32_i16 s6, s6
	s_lshr_b32 s0, s0, 3
	s_add_i32 s40, s7, s6
	s_ashr_i32 s41, s40, 31
	s_bfe_i64 s[12:13], s[0:1], 0x100000
	s_lshl_b64 s[6:7], s[40:41], 20
	s_lshl_b64 s[12:13], s[12:13], 20
	v_readlane_b32 s14, v231, 22
	v_readlane_b32 s15, v231, 23
	s_add_u32 s44, s14, s12
	s_addc_u32 s45, s15, s13
	s_add_i32 s41, s3, 0
	s_add_i32 m0, s41, 0x10000
	v_lshl_or_b32 v128, v3, 12, v1
	global_load_lds_dwordx4 v132, s[44:45]
	s_add_i32 m0, s41, 0x12000
	s_add_u32 s12, s44, 0x80000
	global_load_lds_dwordx4 v128, s[44:45]
	s_addc_u32 s13, s45, 0
	s_add_i32 m0, s41, 0x14000
	v_lshl_or_b32 v134, v0, 12, v1
	global_load_lds_dwordx4 v132, s[12:13]
	s_add_i32 m0, s41, 0x16000
	s_add_u32 s42, s96, s6
	s_addc_u32 s43, s97, s7
	s_add_i32 s49, s41, 0x2000
	global_load_lds_dwordx4 v128, s[12:13]
	s_mov_b32 m0, s41
	s_add_u32 s6, s42, 0x80000
	global_load_lds_dwordx4 v134, s[42:43]
	s_mov_b32 m0, s49
	s_addc_u32 s7, s43, 0
	s_add_i32 s50, s41, 0x4000
	global_load_lds_dwordx4 v130, s[42:43]
	s_mov_b32 m0, s50
	s_add_i32 s51, s41, 0x6000
	global_load_lds_dwordx4 v134, s[6:7]
	s_mov_b32 m0, s51
	v_mov_b32_e32 v133, 0
	global_load_lds_dwordx4 v130, s[6:7]
	v_mov_b32_e32 v129, v133
	v_mov_b32_e32 v135, v133
	v_mov_b32_e32 v131, v133
	s_cmp_eq_u32 s10, 1
	s_mov_b32 s52, 0
	v_lshl_add_u64 v[6:7], s[44:45], 0, v[132:133]
	v_lshl_add_u64 v[4:5], s[44:45], 0, v[128:129]
	v_lshl_add_u64 v[0:1], s[42:43], 0, v[134:135]
	s_cselect_b64 s[6:7], -1, 0
	s_cmp_lg_u32 s10, 1
	v_lshl_add_u64 v[2:3], s[42:43], 0, v[130:131]
	s_cbranch_scc1 .LBB0_727
	s_barrier

; #define PG8_STAGE(bufoff, gbase, voff) do { _Pragma("unroll") for (int _i = 0; _i < 2; ++_i) \
;         __builtin_amdgcn_global_load_lds((const unsigned*)((const char*)(gbase) + (voff)[_i]), (PG8_LAS unsigned*)(lds + (bufoff) + ldsw + _i * 8192), 16, 0, 0); } while (0)
; #define PG8_LDA(dst, b, h) do { _Pragma("unroll") for (int m = 0; m < 4; ++m) _Pragma("unroll") for (int k = 0; k < 2; ++k) dst[m][k] = *(const PG8_LAS bf16x8*)(lds + PG8_SA(b, h) + aoff + m * 2048 + k * 1024); } while (0)
; #define PG8_LDB(dst, b, h) do { _Pragma("unroll") for (int n = 0; n < 2; ++n) _Pragma("unroll") for (int k = 0; k < 2; ++k) dst[n][k] = *(const PG8_LAS bf16x8*)(lds + PG8_SB(b, h) + boff + n * 2048 + k * 1024); } while (0)
; #define PG8_MMA(ai, bj, At, Bt) do { __builtin_amdgcn_s_setprio(1); _Pragma("unroll") for (int m = 0; m < 4; ++m) _Pragma("unroll") for (int n = 0; n < 2; ++n) _Pragma("unroll") for (int k = 0; k < 2; ++k) \
;         acc[ai][bj][m][n] = __builtin_amdgcn_mfma_f32_16x16x32_bf16(Bt[n][k], At[m][k], acc[ai][bj][m][n], 0, 0, 0); __builtin_amdgcn_s_setprio(0); } while (0)
; #define PG8_WAIT_V(n) asm volatile("s_waitcnt vmcnt(" #n ")" ::: "memory")
; #define PG8_WAIT_L(n) asm volatile("s_waitcnt lgkmcnt(" #n ")" ::: "memory")
; #define PG8_BAR __builtin_amdgcn_s_barrier()
; #define PG8_SCHED __builtin_amdgcn_sched_barrier(0)
; template <class Epi, class Sched, bool ALIGN_EPI = false, bool SP2 = false>
; __device__ __forceinline__ void gemm_phase(PG8_LAS unsigned char* lds, const Gemm g, const Sched& S, const Epi& E) {
;     ...
;             PG8_LDB(B0, 0, 0); PG8_LDB(B1, 0, 1); PG8_SCHED; PG8_LDA(At, 0, 0); PG8_STAGE(PG8_SA(1, 1), a1 + hstep, voffA);
;             PG8_WAIT_V(8); PG8_WAIT_L(0); PG8_BAR; PG8_MMA(0, 0, At, B0); PG8_MMA(0, 1, At, B1); PG8_BAR; PG8_SCHED;
;             PG8_LDA(At, 0, 1); PG8_STAGE(PG8_SB(0, 0), b2, voffB); PG8_STAGE(PG8_SB(0, 1), b2 + hstep, voffB); PG8_STAGE(PG8_SA(0, 0), a2, voffA);
;             PG8_WAIT_V(8); PG8_WAIT_L(0); PG8_BAR; PG8_MMA(1, 0, At, B0); PG8_MMA(1, 1, At, B1); PG8_BAR; PG8_SCHED;
.LBB0_733:
	ds_read_b128 v[154:157], v151
	ds_read_b128 v[158:161], v151 offset:1024
	ds_read_b128 v[162:165], v151 offset:2048
	ds_read_b128 v[166:169], v151 offset:3072
	ds_read_b128 v[170:173], v152
	ds_read_b128 v[174:177], v152 offset:1024
	ds_read_b128 v[178:181], v152 offset:2048
	ds_read_b128 v[182:185], v152 offset:3072
	s_add_u32 s44, s42, 0xfff80080
	s_addc_u32 s45, s43, -1
	s_cmp_eq_u32 s67, 28
	s_cselect_b32 s47, s35, s45
	s_cselect_b32 s46, s63, s44
	s_cselect_b32 s45, s31, s66
	s_cselect_b32 s44, s64, s65
	v_lshl_add_u64 v[148:149], s[42:43], 0, v[136:137]
	s_add_i32 m0, s41, 0xc000
	ds_read_b128 v[186:189], v153
	ds_read_b128 v[190:193], v153 offset:1024
	ds_read_b128 v[194:197], v153 offset:2048
	ds_read_b128 v[198:201], v153 offset:3072
	ds_read_b128 v[202:205], v153 offset:4096
	ds_read_b128 v[206:209], v153 offset:5120
	ds_read_b128 v[210:213], v153 offset:6144
	ds_read_b128 v[214:217], v153 offset:7168
	global_load_lds_dwordx4 v[148:149], off
	v_lshl_add_u64 v[148:149], s[42:43], 0, v[138:139]
	s_add_i32 m0, s41, 0xe000
	s_nop 0
	global_load_lds_dwordx4 v[148:149], off
	s_waitcnt vmcnt(8)
	s_waitcnt lgkmcnt(0)
	s_barrier
	s_nop 0
	s_waitcnt lgkmcnt(0)
	v_mfma_f32_16x16x32_bf16 v[124:127], v[154:157], v[186:189], v[124:127]
	v_mfma_f32_16x16x32_bf16 v[120:123], v[162:165], v[186:189], v[120:123]
	v_mfma_f32_16x16x32_bf16 v[108:111], v[154:157], v[194:197], v[108:111]
	v_mfma_f32_16x16x32_bf16 v[104:107], v[162:165], v[194:197], v[104:107]
	v_mfma_f32_16x16x32_bf16 v[92:95], v[154:157], v[202:205], v[92:95]
	v_mfma_f32_16x16x32_bf16 v[88:91], v[162:165], v[202:205], v[88:91]
	v_mfma_f32_16x16x32_bf16 v[76:79], v[154:157], v[210:213], v[76:79]
	v_mfma_f32_16x16x32_bf16 v[72:75], v[162:165], v[210:213], v[72:75]
	v_mfma_f32_16x16x32_bf16 v[124:127], v[158:161], v[190:193], v[124:127]
	v_mfma_f32_16x16x32_bf16 v[120:123], v[166:169], v[190:193], v[120:123]
	v_mfma_f32_16x16x32_bf16 v[108:111], v[158:161], v[198:201], v[108:111]
	v_mfma_f32_16x16x32_bf16 v[104:107], v[166:169], v[198:201], v[104:107]
	v_mfma_f32_16x16x32_bf16 v[92:95], v[158:161], v[206:209], v[92:95]
	v_mfma_f32_16x16x32_bf16 v[88:91], v[166:169], v[206:209], v[88:91]
	v_mfma_f32_16x16x32_bf16 v[76:79], v[158:161], v[214:217], v[76:79]
	v_mfma_f32_16x16x32_bf16 v[72:75], v[166:169], v[214:217], v[72:75]
	s_nop 0
	s_nop 0
	v_mfma_f32_16x16x32_bf16 v[116:119], v[170:173], v[186:189], v[116:119]
	v_mfma_f32_16x16x32_bf16 v[112:115], v[178:181], v[186:189], v[112:115]
	v_mfma_f32_16x16x32_bf16 v[100:103], v[170:173], v[194:197], v[100:103]
	v_mfma_f32_16x16x32_bf16 v[96:99], v[178:181], v[194:197], v[96:99]
	v_mfma_f32_16x16x32_bf16 v[84:87], v[170:173], v[202:205], v[84:87]
	v_mfma_f32_16x16x32_bf16 v[80:83], v[178:181], v[202:205], v[80:83]
	v_mfma_f32_16x16x32_bf16 v[68:71], v[170:173], v[210:213], v[68:71]
	v_mfma_f32_16x16x32_bf16 v[64:67], v[178:181], v[210:213], v[64:67]
	v_mfma_f32_16x16x32_bf16 v[116:119], v[174:177], v[190:193], v[116:119]
	v_mfma_f32_16x16x32_bf16 v[112:115], v[182:185], v[190:193], v[112:115]
	v_mfma_f32_16x16x32_bf16 v[100:103], v[174:177], v[198:201], v[100:103]
	v_mfma_f32_16x16x32_bf16 v[96:99], v[182:185], v[198:201], v[96:99]
	v_mfma_f32_16x16x32_bf16 v[84:87], v[174:177], v[206:209], v[84:87]
	v_mfma_f32_16x16x32_bf16 v[80:83], v[182:185], v[206:209], v[80:83]
	v_mfma_f32_16x16x32_bf16 v[68:71], v[174:177], v[214:217], v[68:71]
	v_mfma_f32_16x16x32_bf16 v[64:67], v[182:185], v[214:217], v[64:67]
	s_nop 0
	s_barrier
	s_add_i32 s68, s56, s3
	v_lshl_add_u64 v[148:149], s[44:45], 0, v[132:133]
	s_mov_b32 m0, s68
	ds_read_b128 v[186:189], v153 offset:16384
	ds_read_b128 v[190:193], v153 offset:17408
	ds_read_b128 v[194:197], v153 offset:18432
	ds_read_b128 v[198:201], v153 offset:19456
	ds_read_b128 v[202:205], v153 offset:20480
	ds_read_b128 v[206:209], v153 offset:21504
	ds_read_b128 v[210:213], v153 offset:22528
	ds_read_b128 v[214:217], v153 offset:23552
	global_load_lds_dwordx4 v[148:149], off
	s_add_i32 m0, s68, 0x2000
	s_add_u32 s68, s44, 0x80000
	v_lshl_add_u64 v[218:219], s[44:45], 0, v[128:129]
	s_addc_u32 s69, s45, 0
	s_add_i32 s70, s57, s3
	global_load_lds_dwordx4 v[218:219], off
	v_lshl_add_u64 v[220:221], s[68:69], 0, v[132:133]
	s_mov_b32 m0, s70
	v_lshl_add_u64 v[222:223], s[46:47], 0, v[130:131]
	global_load_lds_dwordx4 v[220:221], off
	v_lshl_add_u64 v[220:221], s[68:69], 0, v[128:129]
	s_add_i32 m0, s70, 0x2000
	s_nop 0
	global_load_lds_dwordx4 v[220:221], off
	v_lshl_add_u64 v[220:221], s[46:47], 0, v[134:135]
	s_mov_b32 m0, s41
	s_nop 0
	global_load_lds_dwordx4 v[220:221], off
	s_mov_b32 m0, s49
	s_nop 0
	global_load_lds_dwordx4 v[222:223], off
	s_waitcnt vmcnt(8)
	s_waitcnt lgkmcnt(0)
	s_barrier
; #define PG8_STAGE(bufoff, gbase, voff) do { _Pragma("unroll") for (int _i = 0; _i < 2; ++_i) \
;         __builtin_amdgcn_global_load_lds((const unsigned*)((const char*)(gbase) + (voff)[_i]), (PG8_LAS unsigned*)(lds + (bufoff) + ldsw + _i * 8192), 16, 0, 0); } while (0)
; #define PG8_LDA(dst, b, h) do { _Pragma("unroll") for (int m = 0; m < 4; ++m) _Pragma("unroll") for (int k = 0; k < 2; ++k) dst[m][k] = *(const PG8_LAS bf16x8*)(lds + PG8_SA(b, h) + aoff + m * 2048 + k * 1024); } while (0)
; #define PG8_LDB(dst, b, h) do { _Pragma("unroll") for (int n = 0; n < 2; ++n) _Pragma("unroll") for (int k = 0; k < 2; ++k) dst[n][k] = *(const PG8_LAS bf16x8*)(lds + PG8_SB(b, h) + boff + n * 2048 + k * 1024); } while (0)
; #define PG8_MMA(ai, bj, At, Bt) do { __builtin_amdgcn_s_setprio(1); _Pragma("unroll") for (int m = 0; m < 4; ++m) _Pragma("unroll") for (int n = 0; n < 2; ++n) _Pragma("unroll") for (int k = 0; k < 2; ++k) \
;         acc[ai][bj][m][n] = __builtin_amdgcn_mfma_f32_16x16x32_bf16(Bt[n][k], At[m][k], acc[ai][bj][m][n], 0, 0, 0); __builtin_amdgcn_s_setprio(0); } while (0)
; #define PG8_WAIT_V(n) asm volatile("s_waitcnt vmcnt(" #n ")" ::: "memory")
; #define PG8_WAIT_L(n) asm volatile("s_waitcnt lgkmcnt(" #n ")" ::: "memory")
; #define PG8_BAR __builtin_amdgcn_s_barrier()
; #define PG8_SCHED __builtin_amdgcn_sched_barrier(0)
; template <class Epi, class Sched, bool ALIGN_EPI = false, bool SP2 = false>
; __device__ __forceinline__ void gemm_phase(PG8_LAS unsigned char* lds, const Gemm g, const Sched& S, const Epi& E) {
;     ...
;             PG8_WAIT_V(8); PG8_WAIT_L(0); PG8_BAR; PG8_MMA(1, 0, At, B0); PG8_MMA(1, 1, At, B1); PG8_BAR; PG8_SCHED;
;             PG8_LDB(B0, 1, 0); PG8_LDB(B1, 1, 1); PG8_SCHED; PG8_LDA(At, 1, 0); PG8_STAGE(PG8_SA(0, 1), a2 + hstep, voffA);
;             PG8_WAIT_V(8); PG8_WAIT_L(0); PG8_BAR; PG8_MMA(0, 0, At, B0); PG8_MMA(0, 1, At, B1); PG8_BAR; PG8_SCHED;
	s_nop 0
	s_waitcnt lgkmcnt(0)
	v_mfma_f32_16x16x32_bf16 v[60:63], v[154:157], v[186:189], v[60:63]
	v_mfma_f32_16x16x32_bf16 v[56:59], v[162:165], v[186:189], v[56:59]
	v_mfma_f32_16x16x32_bf16 v[44:47], v[154:157], v[194:197], v[44:47]
	v_mfma_f32_16x16x32_bf16 v[40:43], v[162:165], v[194:197], v[40:43]
	v_mfma_f32_16x16x32_bf16 v[28:31], v[154:157], v[202:205], v[28:31]
	v_mfma_f32_16x16x32_bf16 v[24:27], v[162:165], v[202:205], v[24:27]
	v_mfma_f32_16x16x32_bf16 v[12:15], v[154:157], v[210:213], v[12:15]
	v_mfma_f32_16x16x32_bf16 v[8:11], v[162:165], v[210:213], v[8:11]
	v_mfma_f32_16x16x32_bf16 v[60:63], v[158:161], v[190:193], v[60:63]
	v_mfma_f32_16x16x32_bf16 v[56:59], v[166:169], v[190:193], v[56:59]
	v_mfma_f32_16x16x32_bf16 v[44:47], v[158:161], v[198:201], v[44:47]
	v_mfma_f32_16x16x32_bf16 v[40:43], v[166:169], v[198:201], v[40:43]
	v_mfma_f32_16x16x32_bf16 v[28:31], v[158:161], v[206:209], v[28:31]
	v_mfma_f32_16x16x32_bf16 v[24:27], v[166:169], v[206:209], v[24:27]
	v_mfma_f32_16x16x32_bf16 v[12:15], v[158:161], v[214:217], v[12:15]
	v_mfma_f32_16x16x32_bf16 v[8:11], v[166:169], v[214:217], v[8:11]
	s_nop 0
	s_nop 0
	v_mfma_f32_16x16x32_bf16 v[52:55], v[170:173], v[186:189], v[52:55]
	v_mfma_f32_16x16x32_bf16 v[48:51], v[178:181], v[186:189], v[48:51]
	v_mfma_f32_16x16x32_bf16 v[36:39], v[170:173], v[194:197], v[36:39]
	v_mfma_f32_16x16x32_bf16 v[32:35], v[178:181], v[194:197], v[32:35]
	v_mfma_f32_16x16x32_bf16 v[20:23], v[170:173], v[202:205], v[20:23]
	v_mfma_f32_16x16x32_bf16 v[16:19], v[178:181], v[202:205], v[16:19]
	v_mfma_f32_16x16x32_bf16 v[4:7], v[170:173], v[210:213], v[4:7]
	v_mfma_f32_16x16x32_bf16 v[0:3], v[178:181], v[210:213], v[0:3]
	v_mfma_f32_16x16x32_bf16 v[52:55], v[174:177], v[190:193], v[52:55]
	v_mfma_f32_16x16x32_bf16 v[48:51], v[182:185], v[190:193], v[48:51]
	v_mfma_f32_16x16x32_bf16 v[36:39], v[174:177], v[198:201], v[36:39]
	v_mfma_f32_16x16x32_bf16 v[32:35], v[182:185], v[198:201], v[32:35]
	v_mfma_f32_16x16x32_bf16 v[20:23], v[174:177], v[206:209], v[20:23]
	v_mfma_f32_16x16x32_bf16 v[16:19], v[182:185], v[206:209], v[16:19]
	v_mfma_f32_16x16x32_bf16 v[4:7], v[174:177], v[214:217], v[4:7]
	v_mfma_f32_16x16x32_bf16 v[0:3], v[182:185], v[214:217], v[0:3]
	s_nop 0
	s_barrier
	s_add_i32 s68, 0, 0x18000
	s_add_i32 s69, 0, 0x1c000
	v_add_u32_e32 v166, s68, v147
	v_add_u32_e32 v182, s69, v147
	ds_read_b128 v[154:157], v166
	ds_read_b128 v[158:161], v166 offset:1024
	ds_read_b128 v[162:165], v166 offset:2048
	ds_read_b128 v[166:169], v166 offset:3072
	ds_read_b128 v[170:173], v182
	ds_read_b128 v[174:177], v182 offset:1024
	ds_read_b128 v[178:181], v182 offset:2048
	ds_read_b128 v[182:185], v182 offset:3072
	s_add_u32 s46, s46, 0x80000
	s_addc_u32 s47, s47, 0
	s_mov_b32 m0, s50
	v_lshl_add_u64 v[224:225], s[46:47], 0, v[134:135]
	ds_read_b128 v[186:189], v153 offset:32768
	ds_read_b128 v[190:193], v153 offset:33792
	ds_read_b128 v[194:197], v153 offset:34816
	ds_read_b128 v[198:201], v153 offset:35840
	ds_read_b128 v[202:205], v153 offset:36864
	ds_read_b128 v[206:209], v153 offset:37888
	ds_read_b128 v[210:213], v153 offset:38912
	ds_read_b128 v[214:217], v153 offset:39936
	global_load_lds_dwordx4 v[224:225], off
	v_lshl_add_u64 v[224:225], s[46:47], 0, v[130:131]
	s_mov_b32 m0, s51
	s_nop 0
	global_load_lds_dwordx4 v[224:225], off
	s_waitcnt vmcnt(8)
	s_waitcnt lgkmcnt(0)
	s_barrier
	s_nop 0
	s_waitcnt lgkmcnt(0)
	v_mfma_f32_16x16x32_bf16 v[124:127], v[154:157], v[186:189], v[124:127]
	v_mfma_f32_16x16x32_bf16 v[120:123], v[162:165], v[186:189], v[120:123]
	v_mfma_f32_16x16x32_bf16 v[108:111], v[154:157], v[194:197], v[108:111]
	v_mfma_f32_16x16x32_bf16 v[104:107], v[162:165], v[194:197], v[104:107]
	v_mfma_f32_16x16x32_bf16 v[92:95], v[154:157], v[202:205], v[92:95]
	v_mfma_f32_16x16x32_bf16 v[88:91], v[162:165], v[202:205], v[88:91]
	v_mfma_f32_16x16x32_bf16 v[76:79], v[154:157], v[210:213], v[76:79]
	v_mfma_f32_16x16x32_bf16 v[72:75], v[162:165], v[210:213], v[72:75]
	v_mfma_f32_16x16x32_bf16 v[124:127], v[158:161], v[190:193], v[124:127]
	v_mfma_f32_16x16x32_bf16 v[120:123], v[166:169], v[190:193], v[120:123]
	v_mfma_f32_16x16x32_bf16 v[108:111], v[158:161], v[198:201], v[108:111]
	v_mfma_f32_16x16x32_bf16 v[104:107], v[166:169], v[198:201], v[104:107]
	v_mfma_f32_16x16x32_bf16 v[92:95], v[158:161], v[206:209], v[92:95]
	v_mfma_f32_16x16x32_bf16 v[88:91], v[166:169], v[206:209], v[88:91]
	v_mfma_f32_16x16x32_bf16 v[76:79], v[158:161], v[214:217], v[76:79]
	v_mfma_f32_16x16x32_bf16 v[72:75], v[166:169], v[214:217], v[72:75]
	s_nop 0
	s_nop 0
	v_mfma_f32_16x16x32_bf16 v[116:119], v[170:173], v[186:189], v[116:119]
	v_mfma_f32_16x16x32_bf16 v[112:115], v[178:181], v[186:189], v[112:115]
	v_mfma_f32_16x16x32_bf16 v[100:103], v[170:173], v[194:197], v[100:103]
	v_mfma_f32_16x16x32_bf16 v[96:99], v[178:181], v[194:197], v[96:99]
	v_mfma_f32_16x16x32_bf16 v[84:87], v[170:173], v[202:205], v[84:87]
	v_mfma_f32_16x16x32_bf16 v[80:83], v[178:181], v[202:205], v[80:83]
	v_mfma_f32_16x16x32_bf16 v[68:71], v[170:173], v[210:213], v[68:71]
	v_mfma_f32_16x16x32_bf16 v[64:67], v[178:181], v[210:213], v[64:67]
	v_mfma_f32_16x16x32_bf16 v[116:119], v[174:177], v[190:193], v[116:119]
	v_mfma_f32_16x16x32_bf16 v[112:115], v[182:185], v[190:193], v[112:115]
	v_mfma_f32_16x16x32_bf16 v[100:103], v[174:177], v[198:201], v[100:103]
	v_mfma_f32_16x16x32_bf16 v[96:99], v[182:185], v[198:201], v[96:99]
	v_mfma_f32_16x16x32_bf16 v[84:87], v[174:177], v[206:209], v[84:87]
	v_mfma_f32_16x16x32_bf16 v[80:83], v[182:185], v[206:209], v[80:83]
	v_mfma_f32_16x16x32_bf16 v[68:71], v[174:177], v[214:217], v[68:71]
	v_mfma_f32_16x16x32_bf16 v[64:67], v[182:185], v[214:217], v[64:67]
	s_nop 0
	s_barrier
; #define PG8_STAGE(bufoff, gbase, voff) do { _Pragma("unroll") for (int _i = 0; _i < 2; ++_i) \
;         __builtin_amdgcn_global_load_lds((const unsigned*)((const char*)(gbase) + (voff)[_i]), (PG8_LAS unsigned*)(lds + (bufoff) + ldsw + _i * 8192), 16, 0, 0); } while (0)
; #define PG8_LDA(dst, b, h) do { _Pragma("unroll") for (int m = 0; m < 4; ++m) _Pragma("unroll") for (int k = 0; k < 2; ++k) dst[m][k] = *(const PG8_LAS bf16x8*)(lds + PG8_SA(b, h) + aoff + m * 2048 + k * 1024); } while (0)
; #define PG8_MMA(ai, bj, At, Bt) do { __builtin_amdgcn_s_setprio(1); _Pragma("unroll") for (int m = 0; m < 4; ++m) _Pragma("unroll") for (int n = 0; n < 2; ++n) _Pragma("unroll") for (int k = 0; k < 2; ++k) \
;         acc[ai][bj][m][n] = __builtin_amdgcn_mfma_f32_16x16x32_bf16(Bt[n][k], At[m][k], acc[ai][bj][m][n], 0, 0, 0); __builtin_amdgcn_s_setprio(0); } while (0)
; #define PG8_WAIT_V(n) asm volatile("s_waitcnt vmcnt(" #n ")" ::: "memory")
; #define PG8_WAIT_L(n) asm volatile("s_waitcnt lgkmcnt(" #n ")" ::: "memory")
; #define PG8_BAR __builtin_amdgcn_s_barrier()
; #define PG8_SCHED __builtin_amdgcn_sched_barrier(0)
; template <class Epi, class Sched, bool ALIGN_EPI = false, bool SP2 = false>
; __device__ __forceinline__ void gemm_phase(PG8_LAS unsigned char* lds, const Gemm g, const Sched& S, const Epi& E) {
;     ...
;             PG8_LDA(At, 1, 1); PG8_STAGE(PG8_SB(1, 0), b3, voffB); PG8_STAGE(PG8_SB(1, 1), b3 + hstep, voffB); PG8_STAGE(PG8_SA(1, 0), a3, voffA);
;             PG8_WAIT_V(8); PG8_WAIT_L(0); PG8_BAR; PG8_MMA(1, 0, At, B0); PG8_MMA(1, 1, At, B1); PG8_BAR; PG8_SCHED;
	s_add_i32 s46, s68, s3
	v_lshl_add_u64 v[148:149], v[148:149], 0, s[8:9]
	s_mov_b32 m0, s46
	ds_read_b128 v[186:189], v153 offset:49152
	ds_read_b128 v[190:193], v153 offset:50176
	ds_read_b128 v[194:197], v153 offset:51200
	ds_read_b128 v[198:201], v153 offset:52224
	ds_read_b128 v[202:205], v153 offset:53248
	ds_read_b128 v[206:209], v153 offset:54272
	ds_read_b128 v[210:213], v153 offset:55296
	ds_read_b128 v[214:217], v153 offset:56320
	global_load_lds_dwordx4 v[148:149], off
	s_add_i32 m0, s46, 0x2000
	s_add_u32 s44, s44, 0x80080
	v_lshl_add_u64 v[148:149], v[218:219], 0, s[8:9]
	s_addc_u32 s45, s45, 0
	s_add_i32 s46, s69, s3
	global_load_lds_dwordx4 v[148:149], off
	v_lshl_add_u64 v[148:149], s[44:45], 0, v[132:133]
	s_mov_b32 m0, s46
	s_nop 0
	global_load_lds_dwordx4 v[148:149], off
	v_lshl_add_u64 v[148:149], s[44:45], 0, v[128:129]
	s_add_i32 m0, s46, 0x2000
	s_nop 0
	global_load_lds_dwordx4 v[148:149], off
	v_lshl_add_u64 v[148:149], v[220:221], 0, s[8:9]
	s_mov_b32 m0, s53
	s_nop 0
	global_load_lds_dwordx4 v[148:149], off
	v_lshl_add_u64 v[148:149], v[222:223], 0, s[8:9]
	s_mov_b32 m0, s54
	s_nop 0
	global_load_lds_dwordx4 v[148:149], off
	s_waitcnt vmcnt(8)
	s_waitcnt lgkmcnt(0)
	s_barrier
	s_nop 0
	s_waitcnt lgkmcnt(0)
	v_mfma_f32_16x16x32_bf16 v[60:63], v[154:157], v[186:189], v[60:63]
	v_mfma_f32_16x16x32_bf16 v[56:59], v[162:165], v[186:189], v[56:59]
	v_mfma_f32_16x16x32_bf16 v[44:47], v[154:157], v[194:197], v[44:47]
	v_mfma_f32_16x16x32_bf16 v[40:43], v[162:165], v[194:197], v[40:43]
	v_mfma_f32_16x16x32_bf16 v[28:31], v[154:157], v[202:205], v[28:31]
	v_mfma_f32_16x16x32_bf16 v[24:27], v[162:165], v[202:205], v[24:27]
	v_mfma_f32_16x16x32_bf16 v[12:15], v[154:157], v[210:213], v[12:15]
	v_mfma_f32_16x16x32_bf16 v[8:11], v[162:165], v[210:213], v[8:11]
	v_mfma_f32_16x16x32_bf16 v[60:63], v[158:161], v[190:193], v[60:63]
	v_mfma_f32_16x16x32_bf16 v[56:59], v[166:169], v[190:193], v[56:59]
	v_mfma_f32_16x16x32_bf16 v[44:47], v[158:161], v[198:201], v[44:47]
	v_mfma_f32_16x16x32_bf16 v[40:43], v[166:169], v[198:201], v[40:43]
	v_mfma_f32_16x16x32_bf16 v[28:31], v[158:161], v[206:209], v[28:31]
	v_mfma_f32_16x16x32_bf16 v[24:27], v[166:169], v[206:209], v[24:27]
	v_mfma_f32_16x16x32_bf16 v[12:15], v[158:161], v[214:217], v[12:15]
	v_mfma_f32_16x16x32_bf16 v[8:11], v[166:169], v[214:217], v[8:11]
	s_nop 0
	s_nop 0
	v_mfma_f32_16x16x32_bf16 v[52:55], v[170:173], v[186:189], v[52:55]
	v_mfma_f32_16x16x32_bf16 v[48:51], v[178:181], v[186:189], v[48:51]
	v_mfma_f32_16x16x32_bf16 v[36:39], v[170:173], v[194:197], v[36:39]
	v_mfma_f32_16x16x32_bf16 v[32:35], v[178:181], v[194:197], v[32:35]
	v_mfma_f32_16x16x32_bf16 v[20:23], v[170:173], v[202:205], v[20:23]
	v_mfma_f32_16x16x32_bf16 v[16:19], v[178:181], v[202:205], v[16:19]
	v_mfma_f32_16x16x32_bf16 v[4:7], v[170:173], v[210:213], v[4:7]
	v_mfma_f32_16x16x32_bf16 v[0:3], v[178:181], v[210:213], v[0:3]
	v_mfma_f32_16x16x32_bf16 v[52:55], v[174:177], v[190:193], v[52:55]
	v_mfma_f32_16x16x32_bf16 v[48:51], v[182:185], v[190:193], v[48:51]
	v_mfma_f32_16x16x32_bf16 v[36:39], v[174:177], v[198:201], v[36:39]
	v_mfma_f32_16x16x32_bf16 v[32:35], v[182:185], v[198:201], v[32:35]
	v_mfma_f32_16x16x32_bf16 v[20:23], v[174:177], v[206:209], v[20:23]
	v_mfma_f32_16x16x32_bf16 v[16:19], v[182:185], v[206:209], v[16:19]
	v_mfma_f32_16x16x32_bf16 v[4:7], v[174:177], v[214:217], v[4:7]
	v_mfma_f32_16x16x32_bf16 v[0:3], v[182:185], v[214:217], v[0:3]
	s_nop 0
	s_barrier
	s_add_i32 s67, s67, 2
	s_add_u32 s42, s42, 0x100
	s_addc_u32 s43, s43, 0
	s_add_u32 s65, s65, 0x100
	s_addc_u32 s66, s66, 0
	s_cmp_gt_u32 s67, 29
	s_cbranch_scc0 .LBB0_733
	s_and_b64 vcc, exec, s[10:11]
	s_cbranch_vccz .LBB0_736
	s_barrier

; __device__ __forceinline__ void xcd_barrier(const XcdBarrier& b) {
;     asm volatile("s_waitcnt vmcnt(0)" ::: "memory");
;     __syncthreads();
;     if (threadIdx.x == 0) {
;         unsigned* bar = b.bar;
;         __builtin_amdgcn_s_waitcnt(0);
;         unsigned nloc = b.st[0], nx = b.st[1];
;         if (nloc == 0u) { xcd_barrier_complete(bar, b.x, nloc, nx); b.st[0] = nloc; b.st[1] = nx; }
.LBB0_740:
	s_setprio 0
	s_cmp_gt_i32 s81, 7
	s_cselect_b64 s[0:1], -1, 0
	s_and_b64 s[4:5], s[4:5], s[0:1]
	s_andn2_b64 vcc, exec, s[4:5]
	s_cbranch_vccnz .LBB0_790
	s_waitcnt vmcnt(0)
	v_cmp_eq_u32_e32 vcc, 0, v146
	s_waitcnt vmcnt(0) lgkmcnt(0)
	s_barrier
	s_and_saveexec_b64 s[4:5], vcc
	s_cbranch_execz .LBB0_789
	s_add_i32 s3, 0, 0x20040
	v_mov_b32_e32 v0, s3
	s_waitcnt vmcnt(0) expcnt(0) lgkmcnt(0)
	ds_read_b32 v2, v0
	s_add_i32 s3, 0, 0x20044
	v_mov_b32_e32 v0, s3
	ds_read_b32 v0, v0
	s_waitcnt lgkmcnt(1)
	v_cmp_ne_u32_e32 vcc, 0, v2
	s_cbranch_vccnz .LBB0_757
	v_readlane_b32 s2, v231, 0
	v_readlane_b32 s3, v231, 1
	s_load_dwordx2 s[10:11], s[2:3], 0x4
	s_add_u32 s6, s22, 0x1000
	s_addc_u32 s7, s23, 0
	s_add_u32 s8, s22, 0x1100
	s_addc_u32 s9, s23, 0
	s_waitcnt lgkmcnt(0)
	s_mul_i32 s3, s10, s18
	s_add_u32 s10, s22, 0x1200
	s_mul_i32 s3, s3, s11
	s_addc_u32 s11, s23, 0
	s_add_u32 s12, s22, 0x1300
	s_addc_u32 s13, s23, 0
	s_mov_b32 s30, 1
	v_mov_b32_e32 v16, 0
	s_branch .LBB0_745

; template <class Epi, class Sched, bool ALIGN_EPI = false, bool SP2 = false>
; __device__ __forceinline__ void gemm_phase(PG8_LAS unsigned char* lds, const Gemm g, const Sched& S, const Epi& E) {
;     const int tid = threadIdx.x, wid = __builtin_amdgcn_readfirstlane(tid >> 6), lane = tid & 63, wr = wid >> 2, wc = wid & 3, fr = lane & 15, fq = lane >> 4;
;     const int K = g.K, nt = K / BK;
;     unsigned voffA[2], voffB[2];
; #pragma unroll
;     for (int i = 0; i < 2; ++i) { int R, C; stage_rc(tid * 16 + i * 8192, R, C); const int Rb = Epi::PERM ? ((R & ~31) + perm32(R & 31)) : R;
;         voffA[i] = (unsigned)(R * K + C) * 2u; voffB[i] = (unsigned)(Rb * K + C) * 2u; }
;     const size_t kstep = (size_t)(BK * 2);
;     const size_t hstep = (size_t)HALF * K * 2;
;     const size_t tstep = 2 * hstep;
;     const unsigned ldsw = (unsigned)wid * 1024u;
;     const int aoff = lds_byte(wr * 64 + fr, fq * 8), boff = lds_byte(wc * 32 + fr, fq * 8);
;     ...
;     Unit cur, nxt; int ui = 0;
;     if (!S.next(0, cur)) return;
.LBB0_790:
	s_cmp_lt_i32 s80, 8
	s_cselect_b64 s[4:5], -1, 0
	s_and_b64 s[4:5], s[4:5], s[0:1]
	s_andn2_b64 vcc, exec, s[4:5]
	s_cbranch_vccnz .LBB0_815
	s_cmp_lt_u32 s82, 4
	s_cbranch_scc1 .Lprio_g7
	s_setprio 1
.Lprio_g7:
	s_cmpk_gt_i32 s84, 0x1ff
	v_readfirstlane_b32 s12, v146
	s_cbranch_scc1 .LBB0_815
	s_ashr_i32 s3, s84, 31
	s_lshr_b32 s0, s3, 29
	s_add_i32 s7, s84, s0
	s_and_b32 s0, s7, -8
	s_sub_i32 s8, s84, s0
	s_cmp_gt_i32 s8, -1
	s_cbranch_scc0 .LBB0_794
	s_lshl_b32 s6, s8, 6
	s_cbranch_execz .LBB0_795
	s_branch .LBB0_796

; #define PG8_STAGE(bufoff, gbase, voff) do { _Pragma("unroll") for (int _i = 0; _i < 2; ++_i) \
;         __builtin_amdgcn_global_load_lds((const unsigned*)((const char*)(gbase) + (voff)[_i]), (PG8_LAS unsigned*)(lds + (bufoff) + ldsw + _i * 8192), 16, 0, 0); } while (0)
; #define PG8_LDA(dst, b, h) do { _Pragma("unroll") for (int m = 0; m < 4; ++m) _Pragma("unroll") for (int k = 0; k < 2; ++k) dst[m][k] = *(const PG8_LAS bf16x8*)(lds + PG8_SA(b, h) + aoff + m * 2048 + k * 1024); } while (0)
; #define PG8_LDB(dst, b, h) do { _Pragma("unroll") for (int n = 0; n < 2; ++n) _Pragma("unroll") for (int k = 0; k < 2; ++k) dst[n][k] = *(const PG8_LAS bf16x8*)(lds + PG8_SB(b, h) + boff + n * 2048 + k * 1024); } while (0)
; #define PG8_MMA(ai, bj, At, Bt) do { __builtin_amdgcn_s_setprio(1); _Pragma("unroll") for (int m = 0; m < 4; ++m) _Pragma("unroll") for (int n = 0; n < 2; ++n) _Pragma("unroll") for (int k = 0; k < 2; ++k) \
;         acc[ai][bj][m][n] = __builtin_amdgcn_mfma_f32_16x16x32_bf16(Bt[n][k], At[m][k], acc[ai][bj][m][n], 0, 0, 0); __builtin_amdgcn_s_setprio(0); } while (0)
; #define PG8_WAIT_V(n) asm volatile("s_waitcnt vmcnt(" #n ")" ::: "memory")
; #define PG8_WAIT_L(n) asm volatile("s_waitcnt lgkmcnt(" #n ")" ::: "memory")
; #define PG8_BAR __builtin_amdgcn_s_barrier()
; #define PG8_SCHED __builtin_amdgcn_sched_barrier(0)
; template <class Epi, class Sched, bool ALIGN_EPI = false, bool SP2 = false>
; __device__ __forceinline__ void gemm_phase(PG8_LAS unsigned char* lds, const Gemm g, const Sched& S, const Epi& E) {
;     ...
;             PG8_LDB(B0, 0, 0); PG8_LDB(B1, 0, 1); PG8_SCHED; PG8_LDA(At, 0, 0); PG8_STAGE(PG8_SA(1, 1), a1 + hstep, voffA);
;             PG8_WAIT_V(8); PG8_WAIT_L(0); PG8_BAR; PG8_MMA(0, 0, At, B0); PG8_MMA(0, 1, At, B1); PG8_BAR; PG8_SCHED;
;             PG8_LDA(At, 0, 1); PG8_STAGE(PG8_SB(0, 0), b2, voffB); PG8_STAGE(PG8_SB(0, 1), b2 + hstep, voffB); PG8_STAGE(PG8_SA(0, 0), a2, voffA);
;             PG8_WAIT_V(8); PG8_WAIT_L(0); PG8_BAR; PG8_MMA(1, 0, At, B0); PG8_MMA(1, 1, At, B1); PG8_BAR; PG8_SCHED;
.LBB0_808:
	ds_read_b128 v[128:131], v181
	ds_read_b128 v[132:135], v181 offset:1024
	ds_read_b128 v[136:139], v181 offset:2048
	ds_read_b128 v[140:143], v181 offset:3072
	ds_read_b128 v[164:167], v182
	ds_read_b128 v[168:171], v182 offset:1024
	ds_read_b128 v[172:175], v182 offset:2048
	ds_read_b128 v[176:179], v182 offset:3072
	s_add_u32 s40, s38, 0xffe00080
	s_addc_u32 s41, s39, -1
	s_cmpk_eq_i32 s57, 0x7c
	s_cselect_b32 s43, s29, s41
	s_cselect_b32 s42, s53, s40
	s_cselect_b32 s41, s17, s56
	s_cselect_b32 s40, s54, s55
	v_lshl_add_u64 v[216:217], s[38:39], 0, v[156:157]
	s_add_i32 m0, s33, 0xc000
	ds_read_b128 v[184:187], v183
	ds_read_b128 v[188:191], v183 offset:1024
	ds_read_b128 v[192:195], v183 offset:2048
	ds_read_b128 v[196:199], v183 offset:3072
	ds_read_b128 v[200:203], v183 offset:4096
	ds_read_b128 v[204:207], v183 offset:5120
	ds_read_b128 v[208:211], v183 offset:6144
	ds_read_b128 v[212:215], v183 offset:7168
	global_load_lds_dwordx4 v[216:217], off
	v_lshl_add_u64 v[216:217], s[38:39], 0, v[158:159]
	s_add_i32 m0, s33, 0xe000
	s_nop 0
	global_load_lds_dwordx4 v[216:217], off
	s_waitcnt vmcnt(8)
	s_waitcnt lgkmcnt(0)
	s_barrier
	s_nop 0
	s_waitcnt lgkmcnt(0)
	v_mfma_f32_16x16x32_bf16 v[124:127], v[128:131], v[184:187], v[124:127]
	v_mfma_f32_16x16x32_bf16 v[120:123], v[136:139], v[184:187], v[120:123]
	v_mfma_f32_16x16x32_bf16 v[116:119], v[128:131], v[192:195], v[116:119]
	v_mfma_f32_16x16x32_bf16 v[112:115], v[136:139], v[192:195], v[112:115]
	v_mfma_f32_16x16x32_bf16 v[108:111], v[128:131], v[200:203], v[108:111]
	v_mfma_f32_16x16x32_bf16 v[104:107], v[136:139], v[200:203], v[104:107]
	v_mfma_f32_16x16x32_bf16 v[100:103], v[128:131], v[208:211], v[100:103]
	v_mfma_f32_16x16x32_bf16 v[96:99], v[136:139], v[208:211], v[96:99]
	v_mfma_f32_16x16x32_bf16 v[124:127], v[132:135], v[188:191], v[124:127]
	v_mfma_f32_16x16x32_bf16 v[120:123], v[140:143], v[188:191], v[120:123]
	v_mfma_f32_16x16x32_bf16 v[116:119], v[132:135], v[196:199], v[116:119]
	v_mfma_f32_16x16x32_bf16 v[112:115], v[140:143], v[196:199], v[112:115]
	v_mfma_f32_16x16x32_bf16 v[108:111], v[132:135], v[204:207], v[108:111]
	v_mfma_f32_16x16x32_bf16 v[104:107], v[140:143], v[204:207], v[104:107]
	v_mfma_f32_16x16x32_bf16 v[100:103], v[132:135], v[212:215], v[100:103]
	v_mfma_f32_16x16x32_bf16 v[96:99], v[140:143], v[212:215], v[96:99]
	s_nop 0
	s_nop 0
	v_mfma_f32_16x16x32_bf16 v[64:67], v[164:167], v[184:187], v[64:67]
	v_mfma_f32_16x16x32_bf16 v[56:59], v[172:175], v[184:187], v[56:59]
	v_mfma_f32_16x16x32_bf16 v[52:55], v[164:167], v[192:195], v[52:55]
	v_mfma_f32_16x16x32_bf16 v[48:51], v[172:175], v[192:195], v[48:51]
	v_mfma_f32_16x16x32_bf16 v[44:47], v[164:167], v[200:203], v[44:47]
	v_mfma_f32_16x16x32_bf16 v[40:43], v[172:175], v[200:203], v[40:43]
	v_mfma_f32_16x16x32_bf16 v[36:39], v[164:167], v[208:211], v[36:39]
	v_mfma_f32_16x16x32_bf16 v[32:35], v[172:175], v[208:211], v[32:35]
	v_mfma_f32_16x16x32_bf16 v[64:67], v[168:171], v[188:191], v[64:67]
	v_mfma_f32_16x16x32_bf16 v[56:59], v[176:179], v[188:191], v[56:59]
	v_mfma_f32_16x16x32_bf16 v[52:55], v[168:171], v[196:199], v[52:55]
	v_mfma_f32_16x16x32_bf16 v[48:51], v[176:179], v[196:199], v[48:51]
	v_mfma_f32_16x16x32_bf16 v[44:47], v[168:171], v[204:207], v[44:47]
	v_mfma_f32_16x16x32_bf16 v[40:43], v[176:179], v[204:207], v[40:43]
	v_mfma_f32_16x16x32_bf16 v[36:39], v[168:171], v[212:215], v[36:39]
	v_mfma_f32_16x16x32_bf16 v[32:35], v[176:179], v[212:215], v[32:35]
	s_nop 0
	s_barrier
	s_add_i32 s58, s50, s15
	v_lshl_add_u64 v[216:217], s[40:41], 0, v[150:151]
	s_mov_b32 m0, s58
	ds_read_b128 v[184:187], v183 offset:16384
	ds_read_b128 v[188:191], v183 offset:17408
	ds_read_b128 v[192:195], v183 offset:18432
	ds_read_b128 v[196:199], v183 offset:19456
	ds_read_b128 v[200:203], v183 offset:20480
	ds_read_b128 v[204:207], v183 offset:21504
	ds_read_b128 v[208:211], v183 offset:22528
	ds_read_b128 v[212:215], v183 offset:23552
	global_load_lds_dwordx4 v[216:217], off
	s_add_i32 m0, s58, 0x2000
	s_add_u32 s58, s40, 0x200000
	v_lshl_add_u64 v[218:219], s[40:41], 0, v[154:155]
	s_addc_u32 s59, s41, 0
	s_add_i32 s60, s51, s15
	global_load_lds_dwordx4 v[218:219], off
	v_lshl_add_u64 v[220:221], s[58:59], 0, v[150:151]
	s_mov_b32 m0, s60
	v_lshl_add_u64 v[222:223], s[42:43], 0, v[152:153]
	global_load_lds_dwordx4 v[220:221], off
	v_lshl_add_u64 v[220:221], s[58:59], 0, v[154:155]
	s_add_i32 m0, s60, 0x2000
	s_nop 0
	global_load_lds_dwordx4 v[220:221], off
	v_lshl_add_u64 v[220:221], s[42:43], 0, v[148:149]
	s_mov_b32 m0, s33
	s_nop 0
	global_load_lds_dwordx4 v[220:221], off
	s_mov_b32 m0, s37
	s_nop 0
	global_load_lds_dwordx4 v[222:223], off
	s_waitcnt vmcnt(8)
	s_waitcnt lgkmcnt(0)
	s_barrier
; #define PG8_STAGE(bufoff, gbase, voff) do { _Pragma("unroll") for (int _i = 0; _i < 2; ++_i) \
;         __builtin_amdgcn_global_load_lds((const unsigned*)((const char*)(gbase) + (voff)[_i]), (PG8_LAS unsigned*)(lds + (bufoff) + ldsw + _i * 8192), 16, 0, 0); } while (0)
; #define PG8_LDA(dst, b, h) do { _Pragma("unroll") for (int m = 0; m < 4; ++m) _Pragma("unroll") for (int k = 0; k < 2; ++k) dst[m][k] = *(const PG8_LAS bf16x8*)(lds + PG8_SA(b, h) + aoff + m * 2048 + k * 1024); } while (0)
; #define PG8_LDB(dst, b, h) do { _Pragma("unroll") for (int n = 0; n < 2; ++n) _Pragma("unroll") for (int k = 0; k < 2; ++k) dst[n][k] = *(const PG8_LAS bf16x8*)(lds + PG8_SB(b, h) + boff + n * 2048 + k * 1024); } while (0)
; #define PG8_MMA(ai, bj, At, Bt) do { __builtin_amdgcn_s_setprio(1); _Pragma("unroll") for (int m = 0; m < 4; ++m) _Pragma("unroll") for (int n = 0; n < 2; ++n) _Pragma("unroll") for (int k = 0; k < 2; ++k) \
;         acc[ai][bj][m][n] = __builtin_amdgcn_mfma_f32_16x16x32_bf16(Bt[n][k], At[m][k], acc[ai][bj][m][n], 0, 0, 0); __builtin_amdgcn_s_setprio(0); } while (0)
; #define PG8_WAIT_V(n) asm volatile("s_waitcnt vmcnt(" #n ")" ::: "memory")
; #define PG8_WAIT_L(n) asm volatile("s_waitcnt lgkmcnt(" #n ")" ::: "memory")
; #define PG8_BAR __builtin_amdgcn_s_barrier()
; #define PG8_SCHED __builtin_amdgcn_sched_barrier(0)
; template <class Epi, class Sched, bool ALIGN_EPI = false, bool SP2 = false>
; __device__ __forceinline__ void gemm_phase(PG8_LAS unsigned char* lds, const Gemm g, const Sched& S, const Epi& E) {
;     ...
;             PG8_WAIT_V(8); PG8_WAIT_L(0); PG8_BAR; PG8_MMA(1, 0, At, B0); PG8_MMA(1, 1, At, B1); PG8_BAR; PG8_SCHED;
;             PG8_LDB(B0, 1, 0); PG8_LDB(B1, 1, 1); PG8_SCHED; PG8_LDA(At, 1, 0); PG8_STAGE(PG8_SA(0, 1), a2 + hstep, voffA);
;             PG8_WAIT_V(8); PG8_WAIT_L(0); PG8_BAR; PG8_MMA(0, 0, At, B0); PG8_MMA(0, 1, At, B1); PG8_BAR; PG8_SCHED;
	s_nop 0
	s_waitcnt lgkmcnt(0)
	v_mfma_f32_16x16x32_bf16 v[92:95], v[128:131], v[184:187], v[92:95]
	v_mfma_f32_16x16x32_bf16 v[88:91], v[136:139], v[184:187], v[88:91]
	v_mfma_f32_16x16x32_bf16 v[84:87], v[128:131], v[192:195], v[84:87]
	v_mfma_f32_16x16x32_bf16 v[80:83], v[136:139], v[192:195], v[80:83]
	v_mfma_f32_16x16x32_bf16 v[76:79], v[128:131], v[200:203], v[76:79]
	v_mfma_f32_16x16x32_bf16 v[72:75], v[136:139], v[200:203], v[72:75]
	v_mfma_f32_16x16x32_bf16 v[68:71], v[128:131], v[208:211], v[68:71]
	v_mfma_f32_16x16x32_bf16 v[60:63], v[136:139], v[208:211], v[60:63]
	v_mfma_f32_16x16x32_bf16 v[92:95], v[132:135], v[188:191], v[92:95]
	v_mfma_f32_16x16x32_bf16 v[88:91], v[140:143], v[188:191], v[88:91]
	v_mfma_f32_16x16x32_bf16 v[84:87], v[132:135], v[196:199], v[84:87]
	v_mfma_f32_16x16x32_bf16 v[80:83], v[140:143], v[196:199], v[80:83]
	v_mfma_f32_16x16x32_bf16 v[76:79], v[132:135], v[204:207], v[76:79]
	v_mfma_f32_16x16x32_bf16 v[72:75], v[140:143], v[204:207], v[72:75]
	v_mfma_f32_16x16x32_bf16 v[68:71], v[132:135], v[212:215], v[68:71]
	v_mfma_f32_16x16x32_bf16 v[60:63], v[140:143], v[212:215], v[60:63]
	s_nop 0
	s_nop 0
	v_mfma_f32_16x16x32_bf16 v[28:31], v[164:167], v[184:187], v[28:31]
	v_mfma_f32_16x16x32_bf16 v[24:27], v[172:175], v[184:187], v[24:27]
	v_mfma_f32_16x16x32_bf16 v[20:23], v[164:167], v[192:195], v[20:23]
	v_mfma_f32_16x16x32_bf16 v[16:19], v[172:175], v[192:195], v[16:19]
	v_mfma_f32_16x16x32_bf16 v[12:15], v[164:167], v[200:203], v[12:15]
	v_mfma_f32_16x16x32_bf16 v[8:11], v[172:175], v[200:203], v[8:11]
	v_mfma_f32_16x16x32_bf16 v[4:7], v[164:167], v[208:211], v[4:7]
	v_mfma_f32_16x16x32_bf16 v[0:3], v[172:175], v[208:211], v[0:3]
	v_mfma_f32_16x16x32_bf16 v[28:31], v[168:171], v[188:191], v[28:31]
	v_mfma_f32_16x16x32_bf16 v[24:27], v[176:179], v[188:191], v[24:27]
	v_mfma_f32_16x16x32_bf16 v[20:23], v[168:171], v[196:199], v[20:23]
	v_mfma_f32_16x16x32_bf16 v[16:19], v[176:179], v[196:199], v[16:19]
	v_mfma_f32_16x16x32_bf16 v[12:15], v[168:171], v[204:207], v[12:15]
	v_mfma_f32_16x16x32_bf16 v[8:11], v[176:179], v[204:207], v[8:11]
	v_mfma_f32_16x16x32_bf16 v[4:7], v[168:171], v[212:215], v[4:7]
	v_mfma_f32_16x16x32_bf16 v[0:3], v[176:179], v[212:215], v[0:3]
	s_nop 0
	s_barrier
	s_add_i32 s58, 0, 0x18000
	s_add_i32 s59, 0, 0x1c000
	v_add_u32_e32 v140, s58, v147
	v_add_u32_e32 v176, s59, v147
	ds_read_b128 v[128:131], v140
	ds_read_b128 v[132:135], v140 offset:1024
	ds_read_b128 v[136:139], v140 offset:2048
	ds_read_b128 v[140:143], v140 offset:3072
	ds_read_b128 v[164:167], v176
	ds_read_b128 v[168:171], v176 offset:1024
	ds_read_b128 v[172:175], v176 offset:2048
	ds_read_b128 v[176:179], v176 offset:3072
	s_add_u32 s42, s42, 0x200000
	s_addc_u32 s43, s43, 0
	s_mov_b32 m0, s44
	v_lshl_add_u64 v[224:225], s[42:43], 0, v[148:149]
	ds_read_b128 v[184:187], v183 offset:32768
	ds_read_b128 v[188:191], v183 offset:33792
	ds_read_b128 v[192:195], v183 offset:34816
	ds_read_b128 v[196:199], v183 offset:35840
	ds_read_b128 v[200:203], v183 offset:36864
	ds_read_b128 v[204:207], v183 offset:37888
	ds_read_b128 v[208:211], v183 offset:38912
	ds_read_b128 v[212:215], v183 offset:39936
	global_load_lds_dwordx4 v[224:225], off
	v_lshl_add_u64 v[224:225], s[42:43], 0, v[152:153]
	s_mov_b32 m0, s45
	s_nop 0
	global_load_lds_dwordx4 v[224:225], off
	s_waitcnt vmcnt(8)
	s_waitcnt lgkmcnt(0)
	s_barrier
	s_nop 0
	s_waitcnt lgkmcnt(0)
	v_mfma_f32_16x16x32_bf16 v[124:127], v[128:131], v[184:187], v[124:127]
	v_mfma_f32_16x16x32_bf16 v[120:123], v[136:139], v[184:187], v[120:123]
	v_mfma_f32_16x16x32_bf16 v[116:119], v[128:131], v[192:195], v[116:119]
	v_mfma_f32_16x16x32_bf16 v[112:115], v[136:139], v[192:195], v[112:115]
	v_mfma_f32_16x16x32_bf16 v[108:111], v[128:131], v[200:203], v[108:111]
	v_mfma_f32_16x16x32_bf16 v[104:107], v[136:139], v[200:203], v[104:107]
	v_mfma_f32_16x16x32_bf16 v[100:103], v[128:131], v[208:211], v[100:103]
	v_mfma_f32_16x16x32_bf16 v[96:99], v[136:139], v[208:211], v[96:99]
	v_mfma_f32_16x16x32_bf16 v[124:127], v[132:135], v[188:191], v[124:127]
	v_mfma_f32_16x16x32_bf16 v[120:123], v[140:143], v[188:191], v[120:123]
	v_mfma_f32_16x16x32_bf16 v[116:119], v[132:135], v[196:199], v[116:119]
	v_mfma_f32_16x16x32_bf16 v[112:115], v[140:143], v[196:199], v[112:115]
	v_mfma_f32_16x16x32_bf16 v[108:111], v[132:135], v[204:207], v[108:111]
	v_mfma_f32_16x16x32_bf16 v[104:107], v[140:143], v[204:207], v[104:107]
	v_mfma_f32_16x16x32_bf16 v[100:103], v[132:135], v[212:215], v[100:103]
	v_mfma_f32_16x16x32_bf16 v[96:99], v[140:143], v[212:215], v[96:99]
	s_nop 0
	s_nop 0
	v_mfma_f32_16x16x32_bf16 v[64:67], v[164:167], v[184:187], v[64:67]
	v_mfma_f32_16x16x32_bf16 v[56:59], v[172:175], v[184:187], v[56:59]
	v_mfma_f32_16x16x32_bf16 v[52:55], v[164:167], v[192:195], v[52:55]
	v_mfma_f32_16x16x32_bf16 v[48:51], v[172:175], v[192:195], v[48:51]
	v_mfma_f32_16x16x32_bf16 v[44:47], v[164:167], v[200:203], v[44:47]
	v_mfma_f32_16x16x32_bf16 v[40:43], v[172:175], v[200:203], v[40:43]
	v_mfma_f32_16x16x32_bf16 v[36:39], v[164:167], v[208:211], v[36:39]
	v_mfma_f32_16x16x32_bf16 v[32:35], v[172:175], v[208:211], v[32:35]
	v_mfma_f32_16x16x32_bf16 v[64:67], v[168:171], v[188:191], v[64:67]
	v_mfma_f32_16x16x32_bf16 v[56:59], v[176:179], v[188:191], v[56:59]
	v_mfma_f32_16x16x32_bf16 v[52:55], v[168:171], v[196:199], v[52:55]
	v_mfma_f32_16x16x32_bf16 v[48:51], v[176:179], v[196:199], v[48:51]
	v_mfma_f32_16x16x32_bf16 v[44:47], v[168:171], v[204:207], v[44:47]
	v_mfma_f32_16x16x32_bf16 v[40:43], v[176:179], v[204:207], v[40:43]
	v_mfma_f32_16x16x32_bf16 v[36:39], v[168:171], v[212:215], v[36:39]
	v_mfma_f32_16x16x32_bf16 v[32:35], v[176:179], v[212:215], v[32:35]
	s_nop 0
	s_barrier
; #define PG8_STAGE(bufoff, gbase, voff) do { _Pragma("unroll") for (int _i = 0; _i < 2; ++_i) \
;         __builtin_amdgcn_global_load_lds((const unsigned*)((const char*)(gbase) + (voff)[_i]), (PG8_LAS unsigned*)(lds + (bufoff) + ldsw + _i * 8192), 16, 0, 0); } while (0)
; #define PG8_LDA(dst, b, h) do { _Pragma("unroll") for (int m = 0; m < 4; ++m) _Pragma("unroll") for (int k = 0; k < 2; ++k) dst[m][k] = *(const PG8_LAS bf16x8*)(lds + PG8_SA(b, h) + aoff + m * 2048 + k * 1024); } while (0)
; #define PG8_LDB(dst, b, h) do { _Pragma("unroll") for (int n = 0; n < 2; ++n) _Pragma("unroll") for (int k = 0; k < 2; ++k) dst[n][k] = *(const PG8_LAS bf16x8*)(lds + PG8_SB(b, h) + boff + n * 2048 + k * 1024); } while (0)
; template <class Epi, class Sched, bool ALIGN_EPI = false, bool SP2 = false>
; __device__ __forceinline__ void gemm_phase(PG8_LAS unsigned char* lds, const Gemm g, const Sched& S, const Epi& E) {
;     ...
;         for (int t = 0; t < nt; t += 2) {
;             const bool last = (t == nt - 2);
;             const char* a1 = cA + (size_t)(t + 1) * kstep;
;             const char* a2 = last ? nA : cA + (size_t)(t + 2) * kstep; const char* b2 = last ? nB : cB + (size_t)(t + 2) * kstep;
;             const char* a3 = a2 + kstep; const char* b3 = b2 + kstep;
;             if (last && has_next) S.a_ready(nxt);
;             if constexpr (SP2) {
;             PG8_LDB(B0, 0, 0); PG8_LDB(B1, 0, 1); PG8_SCHED; PG8_LDA(At, 0, 0); PG8_STAGE(PG8_SA(1, 1), a1 + hstep, voffA);
;             PG8_WAIT_V(8); PG8_WAIT_L(0); PG8_BAR; PG8_MMA(0, 0, At, B0); PG8_MMA(0, 1, At, B1); PG8_BAR; PG8_SCHED;
;             PG8_LDA(At, 0, 1); PG8_STAGE(PG8_SB(0, 0), b2, voffB); PG8_STAGE(PG8_SB(0, 1), b2 + hstep, voffB); PG8_STAGE(PG8_SA(0, 0), a2, voffA);
;             PG8_WAIT_V(8); PG8_WAIT_L(0); PG8_BAR; PG8_MMA(1, 0, At, B0); PG8_MMA(1, 1, At, B1); PG8_BAR; PG8_SCHED;
;             PG8_LDB(B0, 1, 0); PG8_LDB(B1, 1, 1); PG8_SCHED; PG8_LDA(At, 1, 0); PG8_STAGE(PG8_SA(0, 1), a2 + hstep, voffA);
;             PG8_WAIT_V(8); PG8_WAIT_L(0); PG8_BAR; PG8_MMA(0, 0, At, B0); PG8_MMA(0, 1, At, B1); PG8_BAR; PG8_SCHED;
;             PG8_LDA(At, 1, 1); PG8_STAGE(PG8_SB(1, 0), b3, voffB); PG8_STAGE(PG8_SB(1, 1), b3 + hstep, voffB); PG8_STAGE(PG8_SA(1, 0), a3, voffA);
;             PG8_WAIT_V(8); PG8_WAIT_L(0); PG8_BAR; PG8_MMA(1, 0, At, B0); PG8_MMA(1, 1, At, B1); PG8_BAR; PG8_SCHED;
	s_add_i32 s42, s58, s15
	v_lshl_add_u64 v[216:217], v[216:217], 0, s[10:11]
	s_mov_b32 m0, s42
	ds_read_b128 v[184:187], v183 offset:49152
	ds_read_b128 v[188:191], v183 offset:50176
	ds_read_b128 v[192:195], v183 offset:51200
	ds_read_b128 v[196:199], v183 offset:52224
	ds_read_b128 v[200:203], v183 offset:53248
	ds_read_b128 v[204:207], v183 offset:54272
	ds_read_b128 v[208:211], v183 offset:55296
	ds_read_b128 v[212:215], v183 offset:56320
	global_load_lds_dwordx4 v[216:217], off
	s_add_i32 m0, s42, 0x2000
	s_add_u32 s40, s40, 0x200080
	v_lshl_add_u64 v[216:217], v[218:219], 0, s[10:11]
	s_addc_u32 s41, s41, 0
	s_add_i32 s42, s59, s15
	global_load_lds_dwordx4 v[216:217], off
	v_lshl_add_u64 v[216:217], s[40:41], 0, v[150:151]
	s_mov_b32 m0, s42
	s_nop 0
	global_load_lds_dwordx4 v[216:217], off
	v_lshl_add_u64 v[216:217], s[40:41], 0, v[154:155]
	s_add_i32 m0, s42, 0x2000
	s_nop 0
	global_load_lds_dwordx4 v[216:217], off
	v_lshl_add_u64 v[216:217], v[220:221], 0, s[10:11]
	s_mov_b32 m0, s47
	s_nop 0
	global_load_lds_dwordx4 v[216:217], off
	v_lshl_add_u64 v[216:217], v[222:223], 0, s[10:11]
	s_mov_b32 m0, s48
	s_nop 0
	global_load_lds_dwordx4 v[216:217], off
	s_waitcnt vmcnt(8)
	s_waitcnt lgkmcnt(0)
	s_barrier
	s_nop 0
	s_waitcnt lgkmcnt(0)
	v_mfma_f32_16x16x32_bf16 v[92:95], v[128:131], v[184:187], v[92:95]
	v_mfma_f32_16x16x32_bf16 v[88:91], v[136:139], v[184:187], v[88:91]
	v_mfma_f32_16x16x32_bf16 v[84:87], v[128:131], v[192:195], v[84:87]
	v_mfma_f32_16x16x32_bf16 v[80:83], v[136:139], v[192:195], v[80:83]
	v_mfma_f32_16x16x32_bf16 v[76:79], v[128:131], v[200:203], v[76:79]
	v_mfma_f32_16x16x32_bf16 v[72:75], v[136:139], v[200:203], v[72:75]
	v_mfma_f32_16x16x32_bf16 v[68:71], v[128:131], v[208:211], v[68:71]
	v_mfma_f32_16x16x32_bf16 v[60:63], v[136:139], v[208:211], v[60:63]
	v_mfma_f32_16x16x32_bf16 v[92:95], v[132:135], v[188:191], v[92:95]
	v_mfma_f32_16x16x32_bf16 v[88:91], v[140:143], v[188:191], v[88:91]
	v_mfma_f32_16x16x32_bf16 v[84:87], v[132:135], v[196:199], v[84:87]
	v_mfma_f32_16x16x32_bf16 v[80:83], v[140:143], v[196:199], v[80:83]
	v_mfma_f32_16x16x32_bf16 v[76:79], v[132:135], v[204:207], v[76:79]
	v_mfma_f32_16x16x32_bf16 v[72:75], v[140:143], v[204:207], v[72:75]
	v_mfma_f32_16x16x32_bf16 v[68:71], v[132:135], v[212:215], v[68:71]
	v_mfma_f32_16x16x32_bf16 v[60:63], v[140:143], v[212:215], v[60:63]
	s_nop 0
	s_nop 0
	v_mfma_f32_16x16x32_bf16 v[28:31], v[164:167], v[184:187], v[28:31]
	v_mfma_f32_16x16x32_bf16 v[24:27], v[172:175], v[184:187], v[24:27]
	v_mfma_f32_16x16x32_bf16 v[20:23], v[164:167], v[192:195], v[20:23]
	v_mfma_f32_16x16x32_bf16 v[16:19], v[172:175], v[192:195], v[16:19]
	v_mfma_f32_16x16x32_bf16 v[12:15], v[164:167], v[200:203], v[12:15]
	v_mfma_f32_16x16x32_bf16 v[8:11], v[172:175], v[200:203], v[8:11]
	v_mfma_f32_16x16x32_bf16 v[4:7], v[164:167], v[208:211], v[4:7]
	v_mfma_f32_16x16x32_bf16 v[0:3], v[172:175], v[208:211], v[0:3]
	v_mfma_f32_16x16x32_bf16 v[28:31], v[168:171], v[188:191], v[28:31]
	v_mfma_f32_16x16x32_bf16 v[24:27], v[176:179], v[188:191], v[24:27]
	v_mfma_f32_16x16x32_bf16 v[20:23], v[168:171], v[196:199], v[20:23]
	v_mfma_f32_16x16x32_bf16 v[16:19], v[176:179], v[196:199], v[16:19]
	v_mfma_f32_16x16x32_bf16 v[12:15], v[168:171], v[204:207], v[12:15]
	v_mfma_f32_16x16x32_bf16 v[8:11], v[176:179], v[204:207], v[8:11]
	v_mfma_f32_16x16x32_bf16 v[4:7], v[168:171], v[212:215], v[4:7]
	v_mfma_f32_16x16x32_bf16 v[0:3], v[176:179], v[212:215], v[0:3]
	s_nop 0
	s_barrier
	s_add_i32 s57, s57, 2
	s_add_u32 s38, s38, 0x100
	s_addc_u32 s39, s39, 0
	s_add_u32 s55, s55, 0x100
	s_addc_u32 s56, s56, 0
	s_cmpk_gt_u32 s57, 0x7d
	s_cbranch_scc0 .LBB0_808
	s_and_b64 vcc, exec, s[12:13]
	s_cbranch_vccz .LBB0_811
	s_barrier

; __device__ __forceinline__ unsigned xb_ld(unsigned* p)              { return __hip_atomic_load(p, __ATOMIC_RELAXED, __HIP_MEMORY_SCOPE_AGENT); }
; __device__ __forceinline__ void xcd_barrier_complete(unsigned* bar, unsigned x, unsigned& nloc, unsigned& nx) {
;     const unsigned G = gridDim.x * gridDim.y * gridDim.z;
;     unsigned sum, cnt, mine, sp = 0u;
;     for (;;) {
;         sum = 0u; cnt = 0u; mine = 0u;
; #pragma unroll
;         for (unsigned j = 0; j < 16; ++j) { const unsigned c = xb_ld(&bar[XB_XCNT(j)]); sum += c; cnt += (c > 0u) ? 1u : 0u; mine = (j == x) ? c : mine; }
; __device__ __forceinline__ void xcd_barrier(const XcdBarrier& b) {
;     asm volatile("s_waitcnt vmcnt(0)" ::: "memory");
;     __syncthreads();
;     if (threadIdx.x == 0) {
;         unsigned* bar = b.bar;
;         __builtin_amdgcn_s_waitcnt(0);
;         unsigned nloc = b.st[0], nx = b.st[1];
;         if (nloc == 0u) { xcd_barrier_complete(bar, b.x, nloc, nx); b.st[0] = nloc; b.st[1] = nx; }
.LBB0_815:
	s_setprio 0
	s_cmp_gt_i32 s81, 8
	s_cselect_b64 s[0:1], -1, 0
	s_and_b64 s[4:5], s[4:5], s[0:1]
	s_andn2_b64 vcc, exec, s[4:5]
	s_cbranch_vccnz .LBB0_865
	s_waitcnt vmcnt(0)
	v_cmp_eq_u32_e32 vcc, 0, v146
	s_waitcnt vmcnt(0) lgkmcnt(0)
	s_barrier
	s_and_saveexec_b64 s[4:5], vcc
	s_cbranch_execz .LBB0_864
	s_add_i32 s3, 0, 0x20040
	v_mov_b32_e32 v0, s3
	s_waitcnt vmcnt(0) expcnt(0) lgkmcnt(0)
	ds_read_b32 v2, v0
	s_add_i32 s3, 0, 0x20044
	v_mov_b32_e32 v0, s3
	ds_read_b32 v0, v0
	s_waitcnt lgkmcnt(1)
	v_cmp_ne_u32_e32 vcc, 0, v2
	s_cbranch_vccnz .LBB0_832
	v_readlane_b32 s2, v231, 0
	v_readlane_b32 s3, v231, 1
	s_load_dwordx2 s[10:11], s[2:3], 0x4
	s_add_u32 s6, s22, 0x1000
	s_addc_u32 s7, s23, 0
	s_add_u32 s8, s22, 0x1100
	s_addc_u32 s9, s23, 0
	s_waitcnt lgkmcnt(0)
	s_mul_i32 s3, s10, s18
	s_add_u32 s10, s22, 0x1200
	s_mul_i32 s3, s3, s11
	s_addc_u32 s11, s23, 0
	s_add_u32 s12, s22, 0x1300
	s_addc_u32 s13, s23, 0
	s_mov_b32 s30, 1
	v_mov_b32_e32 v16, 0
	s_branch .LBB0_820

; #define PG8_STAGE(bufoff, gbase, voff) do { _Pragma("unroll") for (int _i = 0; _i < 2; ++_i) \
;         __builtin_amdgcn_global_load_lds((const unsigned*)((const char*)(gbase) + (voff)[_i]), (PG8_LAS unsigned*)(lds + (bufoff) + ldsw + _i * 8192), 16, 0, 0); } while (0)
; #define PG8_WAIT_V(n) asm volatile("s_waitcnt vmcnt(" #n ")" ::: "memory")
; #define PG8_BAR __builtin_amdgcn_s_barrier()
; template <class Epi, class Sched, bool ALIGN_EPI = false, bool SP2 = false>
; __device__ __forceinline__ void gemm_phase(PG8_LAS unsigned char* lds, const Gemm g, const Sched& S, const Epi& E) {
;     const int tid = threadIdx.x, wid = __builtin_amdgcn_readfirstlane(tid >> 6), lane = tid & 63, wr = wid >> 2, wc = wid & 3, fr = lane & 15, fq = lane >> 4;
;     const int K = g.K, nt = K / BK;
;     unsigned voffA[2], voffB[2];
; #pragma unroll
;     for (int i = 0; i < 2; ++i) { int R, C; stage_rc(tid * 16 + i * 8192, R, C); const int Rb = Epi::PERM ? ((R & ~31) + perm32(R & 31)) : R;
;         voffA[i] = (unsigned)(R * K + C) * 2u; voffB[i] = (unsigned)(Rb * K + C) * 2u; }
;     const size_t kstep = (size_t)(BK * 2);
;     const size_t hstep = (size_t)HALF * K * 2;
;     const size_t tstep = 2 * hstep;
;     const unsigned ldsw = (unsigned)wid * 1024u;
;     const int aoff = lds_byte(wr * 64 + fr, fq * 8), boff = lds_byte(wc * 32 + fr, fq * 8);
;     ...
;     Unit cur, nxt; int ui = 0;
;     if (!S.next(0, cur)) return;
;     f32x4 acc[2][2][4][2];
; #pragma unroll
;     for (int a = 0; a < 2; ++a)
; #pragma unroll
;         for (int b = 0; b < 2; ++b)
; #pragma unroll
;             for (int m = 0; m < 4; ++m)
; #pragma unroll
;                 for (int n = 0; n < 2; ++n) acc[a][b][m][n] = (f32x4){0.f, 0.f, 0.f, 0.f};
;     bf16x8 At[4][2], B0[2][2], B1[2][2];
;     const char* cA = (const char*)g.A + (size_t)cur.pm * tstep; const char* cB = (const char*)g.Bt + (size_t)cur.pn * tstep;
;     S.a_ready(cur);
;     if constexpr (SP2) {
;         PG8_STAGE(PG8_SB(0, 0), cB, voffB); PG8_STAGE(PG8_SB(0, 1), cB + hstep, voffB); PG8_STAGE(PG8_SA(0, 0), cA, voffA); PG8_STAGE(PG8_SA(0, 1), cA + hstep, voffA);
;         if (wr == 1) PG8_BAR;
;         PG8_WAIT_V(2); PG8_BAR;
;         PG8_STAGE(PG8_SB(1, 0), cB + kstep, voffB); PG8_STAGE(PG8_SA(1, 0), cA + kstep, voffA); PG8_STAGE(PG8_SB(1, 1), cB + hstep + kstep, voffB);
;         PG8_WAIT_V(6); PG8_BAR;
.LBB0_1002:
	s_cmp_lt_i32 s80, 10
	s_cselect_b64 s[4:5], -1, 0
	s_and_b64 s[4:5], s[4:5], s[0:1]
	s_andn2_b64 vcc, exec, s[4:5]
	s_cbranch_vccnz .LBB0_1019
	s_cmp_lt_u32 s82, 4
	s_cbranch_scc1 .Lprio_g9
	s_setprio 1
.Lprio_g9:
	s_cmpk_gt_i32 s84, 0x5ff
	v_readfirstlane_b32 s1, v146
	s_cbranch_scc1 .LBB0_1019
	v_lshrrev_b32_e32 v0, 5, v146
	v_lshrrev_b32_e32 v2, 1, v146
	v_and_b32_e32 v0, 4, v0
	v_bfe_u32 v1, v146, 2, 2
	v_and_b32_e32 v11, 24, v2
	v_or3_b32 v0, v0, v1, v11
	v_lshlrev_b32_e32 v1, 4, v146
	s_waitcnt lgkmcnt(0)
	v_add_u32_e32 v8, 0x2000, v1
	v_lshrrev_b32_e32 v2, 7, v8
	s_movk_i32 s0, 0xe0
	v_and_b32_e32 v4, 32, v146
	v_and_or_b32 v3, v2, s0, v0
	v_bitop3_b32 v9, v1, v4, 48 bitop3:0x6c
	v_and_b32_e32 v10, 64, v146
	v_bfe_u32 v12, v146, 2, 4
	s_movk_i32 s0, 0xf0
	v_or_b32_e32 v1, v9, v10
	v_and_or_b32 v2, v2, s0, v12
	s_waitcnt vmcnt(0)
	v_lshl_or_b32 v130, v2, 12, v1
	v_lshrrev_b32_e32 v2, 3, v146
	s_movk_i32 s0, 0x60
	v_and_or_b32 v0, v2, s0, v0
	s_movk_i32 s0, 0x70
	s_ashr_i32 s33, s84, 31
	v_lshl_or_b32 v132, v0, 12, v1
	v_and_or_b32 v0, v2, s0, v12
	s_lshr_b32 s0, s33, 29
	s_add_i32 s0, s84, s0
	s_lshr_b32 s8, s1, 6
	s_ashr_i32 s6, s0, 3
	s_and_b32 s0, s0, -8
	s_lshr_b32 s9, s1, 8
	s_lshl_b32 s3, s8, 10
	s_sub_i32 s0, s84, s0
	s_cmp_lt_i32 s0, 0
	s_movk_i32 s42, 0xc1
	s_cselect_b32 s7, s42, 0xc0
	s_mul_i32 s0, s0, s7
	s_add_i32 s0, s0, s6
	s_mul_hi_i32 s6, s0, 0x2aaaaaab
	s_lshr_b32 s7, s6, 31
	s_ashr_i32 s6, s6, 5
	s_add_i32 s6, s6, s7
	s_lshl_b32 s7, s6, 3
	s_mulk_i32 s6, 0xc0
	s_sub_i32 s6, s0, s6
	s_sext_i32_i16 s0, s6
	s_bfe_u32 s0, s0, 0x3001c
	s_add_i32 s10, s6, s0
	s_sext_i32_i16 s0, s10
	s_and_b32 s10, s10, 0xfff8
	s_sub_i32 s6, s6, s10
	s_sext_i32_i16 s6, s6
	s_lshr_b32 s0, s0, 3
	s_add_i32 s34, s7, s6
	s_ashr_i32 s35, s34, 31
	s_bfe_i64 s[10:11], s[0:1], 0x100000
	s_lshl_b64 s[6:7], s[34:35], 20
	s_lshl_b64 s[10:11], s[10:11], 20
	v_readlane_b32 s12, v231, 18
	v_readlane_b32 s13, v231, 19
	s_add_u32 s38, s12, s10
	s_addc_u32 s39, s13, s11
	s_add_i32 s43, s3, 0
	s_add_i32 m0, s43, 0x10000
	v_lshl_or_b32 v128, v3, 12, v1
	global_load_lds_dwordx4 v132, s[38:39]
	s_add_i32 m0, s43, 0x12000
	s_add_u32 s10, s38, 0x80000
	global_load_lds_dwordx4 v128, s[38:39]
	s_addc_u32 s11, s39, 0
	s_add_i32 m0, s43, 0x14000
	v_lshl_or_b32 v134, v0, 12, v1
	global_load_lds_dwordx4 v132, s[10:11]
	s_add_i32 m0, s43, 0x16000
	s_add_u32 s36, s96, s6
	s_addc_u32 s37, s97, s7
	s_add_i32 s44, s43, 0x2000
	global_load_lds_dwordx4 v128, s[10:11]
	s_mov_b32 m0, s43
	s_add_u32 s6, s36, 0x80000
	global_load_lds_dwordx4 v134, s[36:37]
	s_mov_b32 m0, s44
	s_addc_u32 s7, s37, 0
	s_add_i32 s45, s43, 0x4000
	global_load_lds_dwordx4 v130, s[36:37]
	s_mov_b32 m0, s45
	s_add_i32 s46, s43, 0x6000
	global_load_lds_dwordx4 v134, s[6:7]
	s_mov_b32 m0, s46
	v_mov_b32_e32 v137, 0
	global_load_lds_dwordx4 v130, s[6:7]
	v_mov_b32_e32 v133, v137
	v_mov_b32_e32 v129, v137
	v_mov_b32_e32 v135, v137
	v_mov_b32_e32 v131, v137
	s_cmp_eq_u32 s9, 1
	s_mov_b32 s47, 0
	v_lshl_add_u64 v[6:7], s[38:39], 0, v[132:133]
	v_lshl_add_u64 v[4:5], s[38:39], 0, v[128:129]
	v_lshl_add_u64 v[0:1], s[36:37], 0, v[134:135]
	s_cselect_b64 s[6:7], -1, 0
	s_cmp_lg_u32 s9, 1
	v_lshl_add_u64 v[2:3], s[36:37], 0, v[130:131]
	s_cbranch_scc1 .LBB0_1006
	s_barrier

; #define PG8_STAGE(bufoff, gbase, voff) do { _Pragma("unroll") for (int _i = 0; _i < 2; ++_i) \
;         __builtin_amdgcn_global_load_lds((const unsigned*)((const char*)(gbase) + (voff)[_i]), (PG8_LAS unsigned*)(lds + (bufoff) + ldsw + _i * 8192), 16, 0, 0); } while (0)
; #define PG8_LDA(dst, b, h) do { _Pragma("unroll") for (int m = 0; m < 4; ++m) _Pragma("unroll") for (int k = 0; k < 2; ++k) dst[m][k] = *(const PG8_LAS bf16x8*)(lds + PG8_SA(b, h) + aoff + m * 2048 + k * 1024); } while (0)
; #define PG8_LDB(dst, b, h) do { _Pragma("unroll") for (int n = 0; n < 2; ++n) _Pragma("unroll") for (int k = 0; k < 2; ++k) dst[n][k] = *(const PG8_LAS bf16x8*)(lds + PG8_SB(b, h) + boff + n * 2048 + k * 1024); } while (0)
; #define PG8_MMA(ai, bj, At, Bt) do { __builtin_amdgcn_s_setprio(1); _Pragma("unroll") for (int m = 0; m < 4; ++m) _Pragma("unroll") for (int n = 0; n < 2; ++n) _Pragma("unroll") for (int k = 0; k < 2; ++k) \
;         acc[ai][bj][m][n] = __builtin_amdgcn_mfma_f32_16x16x32_bf16(Bt[n][k], At[m][k], acc[ai][bj][m][n], 0, 0, 0); __builtin_amdgcn_s_setprio(0); } while (0)
; #define PG8_WAIT_V(n) asm volatile("s_waitcnt vmcnt(" #n ")" ::: "memory")
; #define PG8_WAIT_L(n) asm volatile("s_waitcnt lgkmcnt(" #n ")" ::: "memory")
; #define PG8_BAR __builtin_amdgcn_s_barrier()
; #define PG8_SCHED __builtin_amdgcn_sched_barrier(0)
; template <class Epi, class Sched, bool ALIGN_EPI = false, bool SP2 = false>
; __device__ __forceinline__ void gemm_phase(PG8_LAS unsigned char* lds, const Gemm g, const Sched& S, const Epi& E) {
;     ...
;         for (int t = 0; t < nt; t += 2) {
;             const bool last = (t == nt - 2);
;             const char* a1 = cA + (size_t)(t + 1) * kstep;
;             const char* a2 = last ? nA : cA + (size_t)(t + 2) * kstep; const char* b2 = last ? nB : cB + (size_t)(t + 2) * kstep;
;             const char* a3 = a2 + kstep; const char* b3 = b2 + kstep;
;             if (last && has_next) S.a_ready(nxt);
;             if constexpr (SP2) {
;             PG8_LDB(B0, 0, 0); PG8_LDB(B1, 0, 1); PG8_SCHED; PG8_LDA(At, 0, 0); PG8_STAGE(PG8_SA(1, 1), a1 + hstep, voffA);
;             PG8_WAIT_V(8); PG8_WAIT_L(0); PG8_BAR; PG8_MMA(0, 0, At, B0); PG8_MMA(0, 1, At, B1); PG8_BAR; PG8_SCHED;
;             PG8_LDA(At, 0, 1); PG8_STAGE(PG8_SB(0, 0), b2, voffB); PG8_STAGE(PG8_SB(0, 1), b2 + hstep, voffB); PG8_STAGE(PG8_SA(0, 0), a2, voffA);
.LBB0_1012:
	ds_read_b128 v[154:157], v150
	ds_read_b128 v[158:161], v150 offset:1024
	ds_read_b128 v[162:165], v150 offset:2048
	ds_read_b128 v[166:169], v150 offset:3072
	ds_read_b128 v[170:173], v151
	ds_read_b128 v[174:177], v151 offset:1024
	ds_read_b128 v[178:181], v151 offset:2048
	ds_read_b128 v[182:185], v151 offset:3072
	s_add_u32 s38, s36, 0xfff80080
	s_addc_u32 s39, s37, -1
	s_cmp_eq_u32 s58, 28
	s_cselect_b32 s41, s17, s39
	s_cselect_b32 s40, s54, s38
	s_cselect_b32 s39, s15, s57
	s_cselect_b32 s38, s55, s56
	v_lshl_add_u64 v[218:219], s[36:37], 0, v[138:139]
	s_add_i32 m0, s43, 0xc000
	ds_read_b128 v[186:189], v152
	ds_read_b128 v[190:193], v152 offset:1024
	ds_read_b128 v[194:197], v152 offset:2048
	ds_read_b128 v[198:201], v152 offset:3072
	ds_read_b128 v[202:205], v152 offset:4096
	ds_read_b128 v[206:209], v152 offset:5120
	ds_read_b128 v[210:213], v152 offset:6144
	ds_read_b128 v[214:217], v152 offset:7168
	global_load_lds_dwordx4 v[218:219], off
	v_lshl_add_u64 v[218:219], s[36:37], 0, v[140:141]
	s_add_i32 m0, s43, 0xe000
	s_nop 0
	global_load_lds_dwordx4 v[218:219], off
	s_waitcnt vmcnt(8)
	s_waitcnt lgkmcnt(0)
	s_barrier
	s_nop 0
	s_waitcnt lgkmcnt(0)
	v_mfma_f32_16x16x32_bf16 v[124:127], v[154:157], v[186:189], v[124:127]
	v_mfma_f32_16x16x32_bf16 v[120:123], v[162:165], v[186:189], v[120:123]
	v_mfma_f32_16x16x32_bf16 v[116:119], v[154:157], v[194:197], v[116:119]
	v_mfma_f32_16x16x32_bf16 v[112:115], v[162:165], v[194:197], v[112:115]
	v_mfma_f32_16x16x32_bf16 v[108:111], v[154:157], v[202:205], v[108:111]
	v_mfma_f32_16x16x32_bf16 v[104:107], v[162:165], v[202:205], v[104:107]
	v_mfma_f32_16x16x32_bf16 v[100:103], v[154:157], v[210:213], v[100:103]
	v_mfma_f32_16x16x32_bf16 v[96:99], v[162:165], v[210:213], v[96:99]
	v_mfma_f32_16x16x32_bf16 v[124:127], v[158:161], v[190:193], v[124:127]
	v_mfma_f32_16x16x32_bf16 v[120:123], v[166:169], v[190:193], v[120:123]
	v_mfma_f32_16x16x32_bf16 v[116:119], v[158:161], v[198:201], v[116:119]
	v_mfma_f32_16x16x32_bf16 v[112:115], v[166:169], v[198:201], v[112:115]
	v_mfma_f32_16x16x32_bf16 v[108:111], v[158:161], v[206:209], v[108:111]
	v_mfma_f32_16x16x32_bf16 v[104:107], v[166:169], v[206:209], v[104:107]
	v_mfma_f32_16x16x32_bf16 v[100:103], v[158:161], v[214:217], v[100:103]
	v_mfma_f32_16x16x32_bf16 v[96:99], v[166:169], v[214:217], v[96:99]
	s_nop 0
	s_nop 0
	v_mfma_f32_16x16x32_bf16 v[76:79], v[170:173], v[186:189], v[76:79]
	v_mfma_f32_16x16x32_bf16 v[68:71], v[178:181], v[186:189], v[68:71]
	v_mfma_f32_16x16x32_bf16 v[60:63], v[170:173], v[194:197], v[60:63]
	v_mfma_f32_16x16x32_bf16 v[52:55], v[178:181], v[194:197], v[52:55]
	v_mfma_f32_16x16x32_bf16 v[44:47], v[170:173], v[202:205], v[44:47]
	v_mfma_f32_16x16x32_bf16 v[40:43], v[178:181], v[202:205], v[40:43]
	v_mfma_f32_16x16x32_bf16 v[36:39], v[170:173], v[210:213], v[36:39]
	v_mfma_f32_16x16x32_bf16 v[32:35], v[178:181], v[210:213], v[32:35]
	v_mfma_f32_16x16x32_bf16 v[76:79], v[174:177], v[190:193], v[76:79]
	v_mfma_f32_16x16x32_bf16 v[68:71], v[182:185], v[190:193], v[68:71]
	v_mfma_f32_16x16x32_bf16 v[60:63], v[174:177], v[198:201], v[60:63]
	v_mfma_f32_16x16x32_bf16 v[52:55], v[182:185], v[198:201], v[52:55]
	v_mfma_f32_16x16x32_bf16 v[44:47], v[174:177], v[206:209], v[44:47]
	v_mfma_f32_16x16x32_bf16 v[40:43], v[182:185], v[206:209], v[40:43]
	v_mfma_f32_16x16x32_bf16 v[36:39], v[174:177], v[214:217], v[36:39]
	v_mfma_f32_16x16x32_bf16 v[32:35], v[182:185], v[214:217], v[32:35]
	s_nop 0
	s_barrier
	s_add_i32 s59, s52, s3
	v_lshl_add_u64 v[218:219], s[38:39], 0, v[132:133]
	s_mov_b32 m0, s59
	ds_read_b128 v[186:189], v152 offset:16384
	ds_read_b128 v[190:193], v152 offset:17408
	ds_read_b128 v[194:197], v152 offset:18432
	ds_read_b128 v[198:201], v152 offset:19456
	ds_read_b128 v[202:205], v152 offset:20480
	ds_read_b128 v[206:209], v152 offset:21504
	ds_read_b128 v[210:213], v152 offset:22528
	ds_read_b128 v[214:217], v152 offset:23552
	global_load_lds_dwordx4 v[218:219], off
	s_add_i32 m0, s59, 0x2000
	s_add_u32 s60, s38, 0x80000
	v_lshl_add_u64 v[220:221], s[38:39], 0, v[128:129]
	s_addc_u32 s61, s39, 0
	s_add_i32 s59, s53, s3
	global_load_lds_dwordx4 v[220:221], off
	v_lshl_add_u64 v[222:223], s[60:61], 0, v[132:133]
	s_mov_b32 m0, s59
	v_lshl_add_u64 v[224:225], s[40:41], 0, v[130:131]
	global_load_lds_dwordx4 v[222:223], off
	v_lshl_add_u64 v[222:223], s[60:61], 0, v[128:129]
	s_add_i32 m0, s59, 0x2000
	s_nop 0
	global_load_lds_dwordx4 v[222:223], off
	v_lshl_add_u64 v[222:223], s[40:41], 0, v[134:135]
	s_mov_b32 m0, s43
	s_nop 0
	global_load_lds_dwordx4 v[222:223], off
	s_mov_b32 m0, s44
	s_nop 0
	global_load_lds_dwordx4 v[224:225], off
	s_waitcnt vmcnt(8)
	s_waitcnt lgkmcnt(0)
	s_barrier
; #define PG8_STAGE(bufoff, gbase, voff) do { _Pragma("unroll") for (int _i = 0; _i < 2; ++_i) \
;         __builtin_amdgcn_global_load_lds((const unsigned*)((const char*)(gbase) + (voff)[_i]), (PG8_LAS unsigned*)(lds + (bufoff) + ldsw + _i * 8192), 16, 0, 0); } while (0)
; #define PG8_LDA(dst, b, h) do { _Pragma("unroll") for (int m = 0; m < 4; ++m) _Pragma("unroll") for (int k = 0; k < 2; ++k) dst[m][k] = *(const PG8_LAS bf16x8*)(lds + PG8_SA(b, h) + aoff + m * 2048 + k * 1024); } while (0)
; #define PG8_LDB(dst, b, h) do { _Pragma("unroll") for (int n = 0; n < 2; ++n) _Pragma("unroll") for (int k = 0; k < 2; ++k) dst[n][k] = *(const PG8_LAS bf16x8*)(lds + PG8_SB(b, h) + boff + n * 2048 + k * 1024); } while (0)
; #define PG8_MMA(ai, bj, At, Bt) do { __builtin_amdgcn_s_setprio(1); _Pragma("unroll") for (int m = 0; m < 4; ++m) _Pragma("unroll") for (int n = 0; n < 2; ++n) _Pragma("unroll") for (int k = 0; k < 2; ++k) \
;         acc[ai][bj][m][n] = __builtin_amdgcn_mfma_f32_16x16x32_bf16(Bt[n][k], At[m][k], acc[ai][bj][m][n], 0, 0, 0); __builtin_amdgcn_s_setprio(0); } while (0)
; #define PG8_WAIT_V(n) asm volatile("s_waitcnt vmcnt(" #n ")" ::: "memory")
; #define PG8_WAIT_L(n) asm volatile("s_waitcnt lgkmcnt(" #n ")" ::: "memory")
; #define PG8_BAR __builtin_amdgcn_s_barrier()
; #define PG8_SCHED __builtin_amdgcn_sched_barrier(0)
; template <class Epi, class Sched, bool ALIGN_EPI = false, bool SP2 = false>
; __device__ __forceinline__ void gemm_phase(PG8_LAS unsigned char* lds, const Gemm g, const Sched& S, const Epi& E) {
;     ...
;             PG8_WAIT_V(8); PG8_WAIT_L(0); PG8_BAR; PG8_MMA(1, 0, At, B0); PG8_MMA(1, 1, At, B1); PG8_BAR; PG8_SCHED;
;             PG8_LDB(B0, 1, 0); PG8_LDB(B1, 1, 1); PG8_SCHED; PG8_LDA(At, 1, 0); PG8_STAGE(PG8_SA(0, 1), a2 + hstep, voffA);
;             PG8_WAIT_V(8); PG8_WAIT_L(0); PG8_BAR; PG8_MMA(0, 0, At, B0); PG8_MMA(0, 1, At, B1); PG8_BAR; PG8_SCHED;
	s_nop 0
	s_waitcnt lgkmcnt(0)
	v_mfma_f32_16x16x32_bf16 v[92:95], v[154:157], v[186:189], v[92:95]
	v_mfma_f32_16x16x32_bf16 v[88:91], v[162:165], v[186:189], v[88:91]
	v_mfma_f32_16x16x32_bf16 v[84:87], v[154:157], v[194:197], v[84:87]
	v_mfma_f32_16x16x32_bf16 v[80:83], v[162:165], v[194:197], v[80:83]
	v_mfma_f32_16x16x32_bf16 v[72:75], v[154:157], v[202:205], v[72:75]
	v_mfma_f32_16x16x32_bf16 v[64:67], v[162:165], v[202:205], v[64:67]
	v_mfma_f32_16x16x32_bf16 v[56:59], v[154:157], v[210:213], v[56:59]
	v_mfma_f32_16x16x32_bf16 v[48:51], v[162:165], v[210:213], v[48:51]
	v_mfma_f32_16x16x32_bf16 v[92:95], v[158:161], v[190:193], v[92:95]
	v_mfma_f32_16x16x32_bf16 v[88:91], v[166:169], v[190:193], v[88:91]
	v_mfma_f32_16x16x32_bf16 v[84:87], v[158:161], v[198:201], v[84:87]
	v_mfma_f32_16x16x32_bf16 v[80:83], v[166:169], v[198:201], v[80:83]
	v_mfma_f32_16x16x32_bf16 v[72:75], v[158:161], v[206:209], v[72:75]
	v_mfma_f32_16x16x32_bf16 v[64:67], v[166:169], v[206:209], v[64:67]
	v_mfma_f32_16x16x32_bf16 v[56:59], v[158:161], v[214:217], v[56:59]
	v_mfma_f32_16x16x32_bf16 v[48:51], v[166:169], v[214:217], v[48:51]
	s_nop 0
	s_nop 0
	v_mfma_f32_16x16x32_bf16 v[28:31], v[170:173], v[186:189], v[28:31]
	v_mfma_f32_16x16x32_bf16 v[24:27], v[178:181], v[186:189], v[24:27]
	v_mfma_f32_16x16x32_bf16 v[20:23], v[170:173], v[194:197], v[20:23]
	v_mfma_f32_16x16x32_bf16 v[16:19], v[178:181], v[194:197], v[16:19]
	v_mfma_f32_16x16x32_bf16 v[12:15], v[170:173], v[202:205], v[12:15]
	v_mfma_f32_16x16x32_bf16 v[8:11], v[178:181], v[202:205], v[8:11]
	v_mfma_f32_16x16x32_bf16 v[4:7], v[170:173], v[210:213], v[4:7]
	v_mfma_f32_16x16x32_bf16 v[0:3], v[178:181], v[210:213], v[0:3]
	v_mfma_f32_16x16x32_bf16 v[28:31], v[174:177], v[190:193], v[28:31]
	v_mfma_f32_16x16x32_bf16 v[24:27], v[182:185], v[190:193], v[24:27]
	v_mfma_f32_16x16x32_bf16 v[20:23], v[174:177], v[198:201], v[20:23]
	v_mfma_f32_16x16x32_bf16 v[16:19], v[182:185], v[198:201], v[16:19]
	v_mfma_f32_16x16x32_bf16 v[12:15], v[174:177], v[206:209], v[12:15]
	v_mfma_f32_16x16x32_bf16 v[8:11], v[182:185], v[206:209], v[8:11]
	v_mfma_f32_16x16x32_bf16 v[4:7], v[174:177], v[214:217], v[4:7]
	v_mfma_f32_16x16x32_bf16 v[0:3], v[182:185], v[214:217], v[0:3]
	s_nop 0
	s_barrier
	s_add_i32 s59, 0, 0x18000
	v_add_u32_e32 v153, s59, v147
	s_add_i32 s60, 0, 0x1c000
	ds_read_b128 v[154:157], v153
	ds_read_b128 v[158:161], v153 offset:1024
	ds_read_b128 v[162:165], v153 offset:2048
	ds_read_b128 v[166:169], v153 offset:3072
	v_add_u32_e32 v153, s60, v147
	ds_read_b128 v[170:173], v153
	ds_read_b128 v[174:177], v153 offset:1024
	ds_read_b128 v[178:181], v153 offset:2048
	ds_read_b128 v[182:185], v153 offset:3072
	s_add_u32 s40, s40, 0x80000
	s_addc_u32 s41, s41, 0
	s_mov_b32 m0, s45
	v_lshl_add_u64 v[226:227], s[40:41], 0, v[134:135]
	ds_read_b128 v[186:189], v152 offset:32768
	ds_read_b128 v[190:193], v152 offset:33792
	ds_read_b128 v[194:197], v152 offset:34816
	ds_read_b128 v[198:201], v152 offset:35840
	ds_read_b128 v[202:205], v152 offset:36864
	ds_read_b128 v[206:209], v152 offset:37888
	ds_read_b128 v[210:213], v152 offset:38912
	ds_read_b128 v[214:217], v152 offset:39936
	global_load_lds_dwordx4 v[226:227], off
	v_lshl_add_u64 v[226:227], s[40:41], 0, v[130:131]
	s_mov_b32 m0, s46
	s_nop 0
	global_load_lds_dwordx4 v[226:227], off
	s_waitcnt vmcnt(8)
	s_waitcnt lgkmcnt(0)
	s_barrier
	s_nop 0
	s_waitcnt lgkmcnt(0)
	v_mfma_f32_16x16x32_bf16 v[124:127], v[154:157], v[186:189], v[124:127]
	v_mfma_f32_16x16x32_bf16 v[120:123], v[162:165], v[186:189], v[120:123]
	v_mfma_f32_16x16x32_bf16 v[116:119], v[154:157], v[194:197], v[116:119]
	v_mfma_f32_16x16x32_bf16 v[112:115], v[162:165], v[194:197], v[112:115]
	v_mfma_f32_16x16x32_bf16 v[108:111], v[154:157], v[202:205], v[108:111]
	v_mfma_f32_16x16x32_bf16 v[104:107], v[162:165], v[202:205], v[104:107]
	v_mfma_f32_16x16x32_bf16 v[100:103], v[154:157], v[210:213], v[100:103]
	v_mfma_f32_16x16x32_bf16 v[96:99], v[162:165], v[210:213], v[96:99]
	v_mfma_f32_16x16x32_bf16 v[124:127], v[158:161], v[190:193], v[124:127]
	v_mfma_f32_16x16x32_bf16 v[120:123], v[166:169], v[190:193], v[120:123]
	v_mfma_f32_16x16x32_bf16 v[116:119], v[158:161], v[198:201], v[116:119]
	v_mfma_f32_16x16x32_bf16 v[112:115], v[166:169], v[198:201], v[112:115]
	v_mfma_f32_16x16x32_bf16 v[108:111], v[158:161], v[206:209], v[108:111]
	v_mfma_f32_16x16x32_bf16 v[104:107], v[166:169], v[206:209], v[104:107]
	v_mfma_f32_16x16x32_bf16 v[100:103], v[158:161], v[214:217], v[100:103]
	v_mfma_f32_16x16x32_bf16 v[96:99], v[166:169], v[214:217], v[96:99]
	s_nop 0
	s_nop 0
	v_mfma_f32_16x16x32_bf16 v[76:79], v[170:173], v[186:189], v[76:79]
	v_mfma_f32_16x16x32_bf16 v[68:71], v[178:181], v[186:189], v[68:71]
	v_mfma_f32_16x16x32_bf16 v[60:63], v[170:173], v[194:197], v[60:63]
	v_mfma_f32_16x16x32_bf16 v[52:55], v[178:181], v[194:197], v[52:55]
	v_mfma_f32_16x16x32_bf16 v[44:47], v[170:173], v[202:205], v[44:47]
	v_mfma_f32_16x16x32_bf16 v[40:43], v[178:181], v[202:205], v[40:43]
	v_mfma_f32_16x16x32_bf16 v[36:39], v[170:173], v[210:213], v[36:39]
	v_mfma_f32_16x16x32_bf16 v[32:35], v[178:181], v[210:213], v[32:35]
	v_mfma_f32_16x16x32_bf16 v[76:79], v[174:177], v[190:193], v[76:79]
	v_mfma_f32_16x16x32_bf16 v[68:71], v[182:185], v[190:193], v[68:71]
	v_mfma_f32_16x16x32_bf16 v[60:63], v[174:177], v[198:201], v[60:63]
	v_mfma_f32_16x16x32_bf16 v[52:55], v[182:185], v[198:201], v[52:55]
	v_mfma_f32_16x16x32_bf16 v[44:47], v[174:177], v[206:209], v[44:47]
	v_mfma_f32_16x16x32_bf16 v[40:43], v[182:185], v[206:209], v[40:43]
	v_mfma_f32_16x16x32_bf16 v[36:39], v[174:177], v[214:217], v[36:39]
	v_mfma_f32_16x16x32_bf16 v[32:35], v[182:185], v[214:217], v[32:35]
	s_nop 0
	s_barrier
; #define PG8_STAGE(bufoff, gbase, voff) do { _Pragma("unroll") for (int _i = 0; _i < 2; ++_i) \
;         __builtin_amdgcn_global_load_lds((const unsigned*)((const char*)(gbase) + (voff)[_i]), (PG8_LAS unsigned*)(lds + (bufoff) + ldsw + _i * 8192), 16, 0, 0); } while (0)
; #define PG8_LDA(dst, b, h) do { _Pragma("unroll") for (int m = 0; m < 4; ++m) _Pragma("unroll") for (int k = 0; k < 2; ++k) dst[m][k] = *(const PG8_LAS bf16x8*)(lds + PG8_SA(b, h) + aoff + m * 2048 + k * 1024); } while (0)
; #define PG8_MMA(ai, bj, At, Bt) do { __builtin_amdgcn_s_setprio(1); _Pragma("unroll") for (int m = 0; m < 4; ++m) _Pragma("unroll") for (int n = 0; n < 2; ++n) _Pragma("unroll") for (int k = 0; k < 2; ++k) \
;         acc[ai][bj][m][n] = __builtin_amdgcn_mfma_f32_16x16x32_bf16(Bt[n][k], At[m][k], acc[ai][bj][m][n], 0, 0, 0); __builtin_amdgcn_s_setprio(0); } while (0)
; #define PG8_WAIT_V(n) asm volatile("s_waitcnt vmcnt(" #n ")" ::: "memory")
; #define PG8_WAIT_L(n) asm volatile("s_waitcnt lgkmcnt(" #n ")" ::: "memory")
; #define PG8_BAR __builtin_amdgcn_s_barrier()
; #define PG8_SCHED __builtin_amdgcn_sched_barrier(0)
; template <class Epi, class Sched, bool ALIGN_EPI = false, bool SP2 = false>
; __device__ __forceinline__ void gemm_phase(PG8_LAS unsigned char* lds, const Gemm g, const Sched& S, const Epi& E) {
;     ...
;         for (int t = 0; t < nt; t += 2) {
;             const bool last = (t == nt - 2);
;     ...
;             PG8_LDA(At, 1, 1); PG8_STAGE(PG8_SB(1, 0), b3, voffB); PG8_STAGE(PG8_SB(1, 1), b3 + hstep, voffB); PG8_STAGE(PG8_SA(1, 0), a3, voffA);
;             PG8_WAIT_V(8); PG8_WAIT_L(0); PG8_BAR; PG8_MMA(1, 0, At, B0); PG8_MMA(1, 1, At, B1); PG8_BAR; PG8_SCHED;
	s_add_i32 s40, s59, s3
	v_lshl_add_u64 v[218:219], v[218:219], 0, s[8:9]
	s_mov_b32 m0, s40
	ds_read_b128 v[186:189], v152 offset:49152
	ds_read_b128 v[190:193], v152 offset:50176
	ds_read_b128 v[194:197], v152 offset:51200
	ds_read_b128 v[198:201], v152 offset:52224
	ds_read_b128 v[202:205], v152 offset:53248
	ds_read_b128 v[206:209], v152 offset:54272
	ds_read_b128 v[210:213], v152 offset:55296
	ds_read_b128 v[214:217], v152 offset:56320
	global_load_lds_dwordx4 v[218:219], off
	s_add_i32 m0, s40, 0x2000
	s_add_u32 s38, s38, 0x80080
	v_lshl_add_u64 v[218:219], v[220:221], 0, s[8:9]
	s_addc_u32 s39, s39, 0
	s_add_i32 s40, s60, s3
	global_load_lds_dwordx4 v[218:219], off
	v_lshl_add_u64 v[218:219], s[38:39], 0, v[132:133]
	s_mov_b32 m0, s40
	s_nop 0
	global_load_lds_dwordx4 v[218:219], off
	v_lshl_add_u64 v[218:219], s[38:39], 0, v[128:129]
	s_add_i32 m0, s40, 0x2000
	s_nop 0
	global_load_lds_dwordx4 v[218:219], off
	v_lshl_add_u64 v[218:219], v[222:223], 0, s[8:9]
	s_mov_b32 m0, s49
	s_nop 0
	global_load_lds_dwordx4 v[218:219], off
	v_lshl_add_u64 v[218:219], v[224:225], 0, s[8:9]
	s_mov_b32 m0, s50
	s_nop 0
	global_load_lds_dwordx4 v[218:219], off
	s_waitcnt vmcnt(8)
	s_waitcnt lgkmcnt(0)
	s_barrier
	s_nop 0
	s_waitcnt lgkmcnt(0)
	v_mfma_f32_16x16x32_bf16 v[92:95], v[154:157], v[186:189], v[92:95]
	v_mfma_f32_16x16x32_bf16 v[88:91], v[162:165], v[186:189], v[88:91]
	v_mfma_f32_16x16x32_bf16 v[84:87], v[154:157], v[194:197], v[84:87]
	v_mfma_f32_16x16x32_bf16 v[80:83], v[162:165], v[194:197], v[80:83]
	v_mfma_f32_16x16x32_bf16 v[72:75], v[154:157], v[202:205], v[72:75]
	v_mfma_f32_16x16x32_bf16 v[64:67], v[162:165], v[202:205], v[64:67]
	v_mfma_f32_16x16x32_bf16 v[56:59], v[154:157], v[210:213], v[56:59]
	v_mfma_f32_16x16x32_bf16 v[48:51], v[162:165], v[210:213], v[48:51]
	v_mfma_f32_16x16x32_bf16 v[92:95], v[158:161], v[190:193], v[92:95]
	v_mfma_f32_16x16x32_bf16 v[88:91], v[166:169], v[190:193], v[88:91]
	v_mfma_f32_16x16x32_bf16 v[84:87], v[158:161], v[198:201], v[84:87]
	v_mfma_f32_16x16x32_bf16 v[80:83], v[166:169], v[198:201], v[80:83]
	v_mfma_f32_16x16x32_bf16 v[72:75], v[158:161], v[206:209], v[72:75]
	v_mfma_f32_16x16x32_bf16 v[64:67], v[166:169], v[206:209], v[64:67]
	v_mfma_f32_16x16x32_bf16 v[56:59], v[158:161], v[214:217], v[56:59]
	v_mfma_f32_16x16x32_bf16 v[48:51], v[166:169], v[214:217], v[48:51]
	s_nop 0
	s_nop 0
	v_mfma_f32_16x16x32_bf16 v[28:31], v[170:173], v[186:189], v[28:31]
	v_mfma_f32_16x16x32_bf16 v[24:27], v[178:181], v[186:189], v[24:27]
	v_mfma_f32_16x16x32_bf16 v[20:23], v[170:173], v[194:197], v[20:23]
	v_mfma_f32_16x16x32_bf16 v[16:19], v[178:181], v[194:197], v[16:19]
	v_mfma_f32_16x16x32_bf16 v[12:15], v[170:173], v[202:205], v[12:15]
	v_mfma_f32_16x16x32_bf16 v[8:11], v[178:181], v[202:205], v[8:11]
	v_mfma_f32_16x16x32_bf16 v[4:7], v[170:173], v[210:213], v[4:7]
	v_mfma_f32_16x16x32_bf16 v[0:3], v[178:181], v[210:213], v[0:3]
	v_mfma_f32_16x16x32_bf16 v[28:31], v[174:177], v[190:193], v[28:31]
	v_mfma_f32_16x16x32_bf16 v[24:27], v[182:185], v[190:193], v[24:27]
	v_mfma_f32_16x16x32_bf16 v[20:23], v[174:177], v[198:201], v[20:23]
	v_mfma_f32_16x16x32_bf16 v[16:19], v[182:185], v[198:201], v[16:19]
	v_mfma_f32_16x16x32_bf16 v[12:15], v[174:177], v[206:209], v[12:15]
	v_mfma_f32_16x16x32_bf16 v[8:11], v[182:185], v[206:209], v[8:11]
	v_mfma_f32_16x16x32_bf16 v[4:7], v[174:177], v[214:217], v[4:7]
	v_mfma_f32_16x16x32_bf16 v[0:3], v[182:185], v[214:217], v[0:3]
	s_nop 0
	s_barrier
	s_add_i32 s58, s58, 2
	s_add_u32 s36, s36, 0x100
	s_addc_u32 s37, s37, 0
	s_add_u32 s56, s56, 0x100
	s_addc_u32 s57, s57, 0
	s_cmp_gt_u32 s58, 29
	s_cbranch_scc0 .LBB0_1012
	s_and_b64 vcc, exec, s[10:11]
	s_cbranch_vccz .LBB0_1015
	s_barrier

; __device__ __forceinline__ unsigned xb_ld(unsigned* p)              { return __hip_atomic_load(p, __ATOMIC_RELAXED, __HIP_MEMORY_SCOPE_AGENT); }
; __device__ __forceinline__ void xcd_barrier_complete(unsigned* bar, unsigned x, unsigned& nloc, unsigned& nx) {
;     const unsigned G = gridDim.x * gridDim.y * gridDim.z;
;     unsigned sum, cnt, mine, sp = 0u;
;     for (;;) {
;         sum = 0u; cnt = 0u; mine = 0u;
; #pragma unroll
;         for (unsigned j = 0; j < 16; ++j) { const unsigned c = xb_ld(&bar[XB_XCNT(j)]); sum += c; cnt += (c > 0u) ? 1u : 0u; mine = (j == x) ? c : mine; }
; __device__ __forceinline__ void xcd_barrier(const XcdBarrier& b) {
;     asm volatile("s_waitcnt vmcnt(0)" ::: "memory");
;     __syncthreads();
;     if (threadIdx.x == 0) {
;         unsigned* bar = b.bar;
;         __builtin_amdgcn_s_waitcnt(0);
;         unsigned nloc = b.st[0], nx = b.st[1];
;         if (nloc == 0u) { xcd_barrier_complete(bar, b.x, nloc, nx); b.st[0] = nloc; b.st[1] = nx; }
.LBB0_1019:
	s_setprio 0
	s_cmp_gt_i32 s81, 10
	s_cselect_b64 s[0:1], -1, 0
	s_and_b64 s[4:5], s[4:5], s[0:1]
	s_andn2_b64 vcc, exec, s[4:5]
	s_cbranch_vccnz .LBB0_1069
	s_waitcnt vmcnt(0)
	v_cmp_eq_u32_e32 vcc, 0, v146
	s_waitcnt vmcnt(0) lgkmcnt(0)
	s_barrier
	s_and_saveexec_b64 s[4:5], vcc
	s_cbranch_execz .LBB0_1068
	s_add_i32 s3, 0, 0x20040
	v_mov_b32_e32 v0, s3
	s_waitcnt vmcnt(0) expcnt(0) lgkmcnt(0)
	ds_read_b32 v2, v0
	s_add_i32 s3, 0, 0x20044
	v_mov_b32_e32 v0, s3
	ds_read_b32 v0, v0
	s_waitcnt lgkmcnt(1)
	v_cmp_ne_u32_e32 vcc, 0, v2
	s_cbranch_vccnz .LBB0_1036
	v_readlane_b32 s2, v231, 0
	v_readlane_b32 s3, v231, 1
	s_load_dwordx2 s[10:11], s[2:3], 0x4
	s_add_u32 s6, s22, 0x1000
	s_addc_u32 s7, s23, 0
	s_add_u32 s8, s22, 0x1100
	s_addc_u32 s9, s23, 0
	s_waitcnt lgkmcnt(0)
	s_mul_i32 s3, s10, s18
	s_add_u32 s10, s22, 0x1200
	s_mul_i32 s3, s3, s11
	s_addc_u32 s11, s23, 0
	s_add_u32 s12, s22, 0x1300
	s_addc_u32 s13, s23, 0
	s_mov_b32 s30, 1
	v_mov_b32_e32 v16, 0
	s_branch .LBB0_1024

; #define SEAM(k) do { if (IN(k) && IN((k) + 1)) { if ((k) == 0) { cg::this_grid().sync(); bar = xcd_barrier_post(barw, MISC); } else { xcd_barrier(bar); } } } while (0)
; template <class Epi, class Sched, bool ALIGN_EPI = false, bool SP2 = false>
; __device__ __forceinline__ void gemm_phase(PG8_LAS unsigned char* lds, const Gemm g, const Sched& S, const Epi& E) {
;     ...
;     if (!S.next(0, cur)) return;
; __global__ void __launch_bounds__(NTHR, 2) fwd(Args args) {
;     ...
;     if (IN(12)) { gemm_res_ln(F, XB, WOUT, DM, F.out, F.in[10], F.in[11]); } SEAM(12);
.LBB0_1251:
	s_cmp_lt_i32 s80, 13
	s_cselect_b64 s[4:5], -1, 0
	s_and_b64 s[4:5], s[4:5], s[0:1]
	s_andn2_b64 vcc, exec, s[4:5]
	s_cbranch_vccnz .LBB0_1276
	s_cmp_lt_u32 s82, 4
	s_cbranch_scc1 .Lprio_g12
	s_setprio 1

; #define PG8_STAGE(bufoff, gbase, voff) do { _Pragma("unroll") for (int _i = 0; _i < 2; ++_i) \
;         __builtin_amdgcn_global_load_lds((const unsigned*)((const char*)(gbase) + (voff)[_i]), (PG8_LAS unsigned*)(lds + (bufoff) + ldsw + _i * 8192), 16, 0, 0); } while (0)
; #define PG8_LDA(dst, b, h) do { _Pragma("unroll") for (int m = 0; m < 4; ++m) _Pragma("unroll") for (int k = 0; k < 2; ++k) dst[m][k] = *(const PG8_LAS bf16x8*)(lds + PG8_SA(b, h) + aoff + m * 2048 + k * 1024); } while (0)
; #define PG8_LDB(dst, b, h) do { _Pragma("unroll") for (int n = 0; n < 2; ++n) _Pragma("unroll") for (int k = 0; k < 2; ++k) dst[n][k] = *(const PG8_LAS bf16x8*)(lds + PG8_SB(b, h) + boff + n * 2048 + k * 1024); } while (0)
; #define PG8_MMA(ai, bj, At, Bt) do { __builtin_amdgcn_s_setprio(1); _Pragma("unroll") for (int m = 0; m < 4; ++m) _Pragma("unroll") for (int n = 0; n < 2; ++n) _Pragma("unroll") for (int k = 0; k < 2; ++k) \
;         acc[ai][bj][m][n] = __builtin_amdgcn_mfma_f32_16x16x32_bf16(Bt[n][k], At[m][k], acc[ai][bj][m][n], 0, 0, 0); __builtin_amdgcn_s_setprio(0); } while (0)
; #define PG8_WAIT_V(n) asm volatile("s_waitcnt vmcnt(" #n ")" ::: "memory")
; #define PG8_WAIT_L(n) asm volatile("s_waitcnt lgkmcnt(" #n ")" ::: "memory")
; #define PG8_BAR __builtin_amdgcn_s_barrier()
; #define PG8_SCHED __builtin_amdgcn_sched_barrier(0)
; template <class Epi, class Sched, bool ALIGN_EPI = false, bool SP2 = false>
; __device__ __forceinline__ void gemm_phase(PG8_LAS unsigned char* lds, const Gemm g, const Sched& S, const Epi& E) {
;     ...
;         for (int t = 0; t < nt; t += 2) {
;             const bool last = (t == nt - 2);
;             const char* a1 = cA + (size_t)(t + 1) * kstep;
;             const char* a2 = last ? nA : cA + (size_t)(t + 2) * kstep; const char* b2 = last ? nB : cB + (size_t)(t + 2) * kstep;
;             const char* a3 = a2 + kstep; const char* b3 = b2 + kstep;
;             if (last && has_next) S.a_ready(nxt);
;             if constexpr (SP2) {
;             PG8_LDB(B0, 0, 0); PG8_LDB(B1, 0, 1); PG8_SCHED; PG8_LDA(At, 0, 0); PG8_STAGE(PG8_SA(1, 1), a1 + hstep, voffA);
;             PG8_WAIT_V(8); PG8_WAIT_L(0); PG8_BAR; PG8_MMA(0, 0, At, B0); PG8_MMA(0, 1, At, B1); PG8_BAR; PG8_SCHED;
;             PG8_LDA(At, 0, 1); PG8_STAGE(PG8_SB(0, 0), b2, voffB); PG8_STAGE(PG8_SB(0, 1), b2 + hstep, voffB); PG8_STAGE(PG8_SA(0, 0), a2, voffA);
.LBB0_1269:
	ds_read_b128 v[128:131], v181
	ds_read_b128 v[132:135], v181 offset:1024
	ds_read_b128 v[136:139], v181 offset:2048
	ds_read_b128 v[140:143], v181 offset:3072
	ds_read_b128 v[164:167], v182
	ds_read_b128 v[168:171], v182 offset:1024
	ds_read_b128 v[172:175], v182 offset:2048
	ds_read_b128 v[176:179], v182 offset:3072
	s_add_u32 s40, s38, 0xfff80080
	s_addc_u32 s41, s39, -1
	s_cmp_eq_u32 s56, 28
	s_cselect_b32 s43, s29, s41
	s_cselect_b32 s42, s52, s40
	s_cselect_b32 s41, s17, s55
	s_cselect_b32 s40, s53, s54
	v_lshl_add_u64 v[216:217], s[38:39], 0, v[156:157]
	s_add_i32 m0, s19, 0xc000
	ds_read_b128 v[184:187], v183
	ds_read_b128 v[188:191], v183 offset:1024
	ds_read_b128 v[192:195], v183 offset:2048
	ds_read_b128 v[196:199], v183 offset:3072
	ds_read_b128 v[200:203], v183 offset:4096
	ds_read_b128 v[204:207], v183 offset:5120
	ds_read_b128 v[208:211], v183 offset:6144
	ds_read_b128 v[212:215], v183 offset:7168
	global_load_lds_dwordx4 v[216:217], off
	v_lshl_add_u64 v[216:217], s[38:39], 0, v[158:159]
	s_add_i32 m0, s19, 0xe000
	s_nop 0
	global_load_lds_dwordx4 v[216:217], off
	s_waitcnt vmcnt(8)
	s_waitcnt lgkmcnt(0)
	s_barrier
	s_nop 0
	s_waitcnt lgkmcnt(0)
	v_mfma_f32_16x16x32_bf16 v[124:127], v[128:131], v[184:187], v[124:127]
	v_mfma_f32_16x16x32_bf16 v[120:123], v[136:139], v[184:187], v[120:123]
	v_mfma_f32_16x16x32_bf16 v[116:119], v[128:131], v[192:195], v[116:119]
	v_mfma_f32_16x16x32_bf16 v[112:115], v[136:139], v[192:195], v[112:115]
	v_mfma_f32_16x16x32_bf16 v[108:111], v[128:131], v[200:203], v[108:111]
	v_mfma_f32_16x16x32_bf16 v[104:107], v[136:139], v[200:203], v[104:107]
	v_mfma_f32_16x16x32_bf16 v[100:103], v[128:131], v[208:211], v[100:103]
	v_mfma_f32_16x16x32_bf16 v[96:99], v[136:139], v[208:211], v[96:99]
	v_mfma_f32_16x16x32_bf16 v[124:127], v[132:135], v[188:191], v[124:127]
	v_mfma_f32_16x16x32_bf16 v[120:123], v[140:143], v[188:191], v[120:123]
	v_mfma_f32_16x16x32_bf16 v[116:119], v[132:135], v[196:199], v[116:119]
	v_mfma_f32_16x16x32_bf16 v[112:115], v[140:143], v[196:199], v[112:115]
	v_mfma_f32_16x16x32_bf16 v[108:111], v[132:135], v[204:207], v[108:111]
	v_mfma_f32_16x16x32_bf16 v[104:107], v[140:143], v[204:207], v[104:107]
	v_mfma_f32_16x16x32_bf16 v[100:103], v[132:135], v[212:215], v[100:103]
	v_mfma_f32_16x16x32_bf16 v[96:99], v[140:143], v[212:215], v[96:99]
	s_nop 0
	s_nop 0
	v_mfma_f32_16x16x32_bf16 v[64:67], v[164:167], v[184:187], v[64:67]
	v_mfma_f32_16x16x32_bf16 v[56:59], v[172:175], v[184:187], v[56:59]
	v_mfma_f32_16x16x32_bf16 v[52:55], v[164:167], v[192:195], v[52:55]
	v_mfma_f32_16x16x32_bf16 v[48:51], v[172:175], v[192:195], v[48:51]
	v_mfma_f32_16x16x32_bf16 v[44:47], v[164:167], v[200:203], v[44:47]
	v_mfma_f32_16x16x32_bf16 v[40:43], v[172:175], v[200:203], v[40:43]
	v_mfma_f32_16x16x32_bf16 v[36:39], v[164:167], v[208:211], v[36:39]
	v_mfma_f32_16x16x32_bf16 v[32:35], v[172:175], v[208:211], v[32:35]
	v_mfma_f32_16x16x32_bf16 v[64:67], v[168:171], v[188:191], v[64:67]
	v_mfma_f32_16x16x32_bf16 v[56:59], v[176:179], v[188:191], v[56:59]
	v_mfma_f32_16x16x32_bf16 v[52:55], v[168:171], v[196:199], v[52:55]
	v_mfma_f32_16x16x32_bf16 v[48:51], v[176:179], v[196:199], v[48:51]
	v_mfma_f32_16x16x32_bf16 v[44:47], v[168:171], v[204:207], v[44:47]
	v_mfma_f32_16x16x32_bf16 v[40:43], v[176:179], v[204:207], v[40:43]
	v_mfma_f32_16x16x32_bf16 v[36:39], v[168:171], v[212:215], v[36:39]
	v_mfma_f32_16x16x32_bf16 v[32:35], v[176:179], v[212:215], v[32:35]
	s_nop 0
	s_barrier
	s_add_i32 s57, s49, s15
	v_lshl_add_u64 v[216:217], s[40:41], 0, v[150:151]
	s_mov_b32 m0, s57
	ds_read_b128 v[184:187], v183 offset:16384
	ds_read_b128 v[188:191], v183 offset:17408
	ds_read_b128 v[192:195], v183 offset:18432
	ds_read_b128 v[196:199], v183 offset:19456
	ds_read_b128 v[200:203], v183 offset:20480
	ds_read_b128 v[204:207], v183 offset:21504
	ds_read_b128 v[208:211], v183 offset:22528
	ds_read_b128 v[212:215], v183 offset:23552
	global_load_lds_dwordx4 v[216:217], off
	s_add_i32 m0, s57, 0x2000
	s_add_u32 s58, s40, 0x80000
	v_lshl_add_u64 v[218:219], s[40:41], 0, v[154:155]
	s_addc_u32 s59, s41, 0
	s_add_i32 s57, s50, s15
	global_load_lds_dwordx4 v[218:219], off
	v_lshl_add_u64 v[220:221], s[58:59], 0, v[150:151]
	s_mov_b32 m0, s57
	v_lshl_add_u64 v[222:223], s[42:43], 0, v[152:153]
	global_load_lds_dwordx4 v[220:221], off
	v_lshl_add_u64 v[220:221], s[58:59], 0, v[154:155]
	s_add_i32 m0, s57, 0x2000
	s_nop 0
	global_load_lds_dwordx4 v[220:221], off
	v_lshl_add_u64 v[220:221], s[42:43], 0, v[148:149]
	s_mov_b32 m0, s19
	s_nop 0
	global_load_lds_dwordx4 v[220:221], off
	s_mov_b32 m0, s33
	s_nop 0
	global_load_lds_dwordx4 v[222:223], off
	s_waitcnt vmcnt(8)
	s_waitcnt lgkmcnt(0)
	s_barrier
; #define PG8_STAGE(bufoff, gbase, voff) do { _Pragma("unroll") for (int _i = 0; _i < 2; ++_i) \
;         __builtin_amdgcn_global_load_lds((const unsigned*)((const char*)(gbase) + (voff)[_i]), (PG8_LAS unsigned*)(lds + (bufoff) + ldsw + _i * 8192), 16, 0, 0); } while (0)
; #define PG8_LDA(dst, b, h) do { _Pragma("unroll") for (int m = 0; m < 4; ++m) _Pragma("unroll") for (int k = 0; k < 2; ++k) dst[m][k] = *(const PG8_LAS bf16x8*)(lds + PG8_SA(b, h) + aoff + m * 2048 + k * 1024); } while (0)
; #define PG8_LDB(dst, b, h) do { _Pragma("unroll") for (int n = 0; n < 2; ++n) _Pragma("unroll") for (int k = 0; k < 2; ++k) dst[n][k] = *(const PG8_LAS bf16x8*)(lds + PG8_SB(b, h) + boff + n * 2048 + k * 1024); } while (0)
; #define PG8_MMA(ai, bj, At, Bt) do { __builtin_amdgcn_s_setprio(1); _Pragma("unroll") for (int m = 0; m < 4; ++m) _Pragma("unroll") for (int n = 0; n < 2; ++n) _Pragma("unroll") for (int k = 0; k < 2; ++k) \
;         acc[ai][bj][m][n] = __builtin_amdgcn_mfma_f32_16x16x32_bf16(Bt[n][k], At[m][k], acc[ai][bj][m][n], 0, 0, 0); __builtin_amdgcn_s_setprio(0); } while (0)
; #define PG8_WAIT_V(n) asm volatile("s_waitcnt vmcnt(" #n ")" ::: "memory")
; #define PG8_WAIT_L(n) asm volatile("s_waitcnt lgkmcnt(" #n ")" ::: "memory")
; #define PG8_BAR __builtin_amdgcn_s_barrier()
; #define PG8_SCHED __builtin_amdgcn_sched_barrier(0)
; template <class Epi, class Sched, bool ALIGN_EPI = false, bool SP2 = false>
; __device__ __forceinline__ void gemm_phase(PG8_LAS unsigned char* lds, const Gemm g, const Sched& S, const Epi& E) {
;     ...
;             PG8_WAIT_V(8); PG8_WAIT_L(0); PG8_BAR; PG8_MMA(1, 0, At, B0); PG8_MMA(1, 1, At, B1); PG8_BAR; PG8_SCHED;
;             PG8_LDB(B0, 1, 0); PG8_LDB(B1, 1, 1); PG8_SCHED; PG8_LDA(At, 1, 0); PG8_STAGE(PG8_SA(0, 1), a2 + hstep, voffA);
;             PG8_WAIT_V(8); PG8_WAIT_L(0); PG8_BAR; PG8_MMA(0, 0, At, B0); PG8_MMA(0, 1, At, B1); PG8_BAR; PG8_SCHED;
	s_nop 0
	s_waitcnt lgkmcnt(0)
	v_mfma_f32_16x16x32_bf16 v[92:95], v[128:131], v[184:187], v[92:95]
	v_mfma_f32_16x16x32_bf16 v[88:91], v[136:139], v[184:187], v[88:91]
	v_mfma_f32_16x16x32_bf16 v[84:87], v[128:131], v[192:195], v[84:87]
	v_mfma_f32_16x16x32_bf16 v[80:83], v[136:139], v[192:195], v[80:83]
	v_mfma_f32_16x16x32_bf16 v[76:79], v[128:131], v[200:203], v[76:79]
	v_mfma_f32_16x16x32_bf16 v[72:75], v[136:139], v[200:203], v[72:75]
	v_mfma_f32_16x16x32_bf16 v[68:71], v[128:131], v[208:211], v[68:71]
	v_mfma_f32_16x16x32_bf16 v[60:63], v[136:139], v[208:211], v[60:63]
	v_mfma_f32_16x16x32_bf16 v[92:95], v[132:135], v[188:191], v[92:95]
	v_mfma_f32_16x16x32_bf16 v[88:91], v[140:143], v[188:191], v[88:91]
	v_mfma_f32_16x16x32_bf16 v[84:87], v[132:135], v[196:199], v[84:87]
	v_mfma_f32_16x16x32_bf16 v[80:83], v[140:143], v[196:199], v[80:83]
	v_mfma_f32_16x16x32_bf16 v[76:79], v[132:135], v[204:207], v[76:79]
	v_mfma_f32_16x16x32_bf16 v[72:75], v[140:143], v[204:207], v[72:75]
	v_mfma_f32_16x16x32_bf16 v[68:71], v[132:135], v[212:215], v[68:71]
	v_mfma_f32_16x16x32_bf16 v[60:63], v[140:143], v[212:215], v[60:63]
	s_nop 0
	s_nop 0
	v_mfma_f32_16x16x32_bf16 v[28:31], v[164:167], v[184:187], v[28:31]
	v_mfma_f32_16x16x32_bf16 v[24:27], v[172:175], v[184:187], v[24:27]
	v_mfma_f32_16x16x32_bf16 v[20:23], v[164:167], v[192:195], v[20:23]
	v_mfma_f32_16x16x32_bf16 v[16:19], v[172:175], v[192:195], v[16:19]
	v_mfma_f32_16x16x32_bf16 v[12:15], v[164:167], v[200:203], v[12:15]
	v_mfma_f32_16x16x32_bf16 v[8:11], v[172:175], v[200:203], v[8:11]
	v_mfma_f32_16x16x32_bf16 v[4:7], v[164:167], v[208:211], v[4:7]
	v_mfma_f32_16x16x32_bf16 v[0:3], v[172:175], v[208:211], v[0:3]
	v_mfma_f32_16x16x32_bf16 v[28:31], v[168:171], v[188:191], v[28:31]
	v_mfma_f32_16x16x32_bf16 v[24:27], v[176:179], v[188:191], v[24:27]
	v_mfma_f32_16x16x32_bf16 v[20:23], v[168:171], v[196:199], v[20:23]
	v_mfma_f32_16x16x32_bf16 v[16:19], v[176:179], v[196:199], v[16:19]
	v_mfma_f32_16x16x32_bf16 v[12:15], v[168:171], v[204:207], v[12:15]
	v_mfma_f32_16x16x32_bf16 v[8:11], v[176:179], v[204:207], v[8:11]
	v_mfma_f32_16x16x32_bf16 v[4:7], v[168:171], v[212:215], v[4:7]
	v_mfma_f32_16x16x32_bf16 v[0:3], v[176:179], v[212:215], v[0:3]
	s_nop 0
	s_barrier
	s_add_i32 s57, 0, 0x18000
	s_add_i32 s58, 0, 0x1c000
	v_add_u32_e32 v140, s57, v147
	v_add_u32_e32 v176, s58, v147
	ds_read_b128 v[128:131], v140
	ds_read_b128 v[132:135], v140 offset:1024
	ds_read_b128 v[136:139], v140 offset:2048
	ds_read_b128 v[140:143], v140 offset:3072
	ds_read_b128 v[164:167], v176
	ds_read_b128 v[168:171], v176 offset:1024
	ds_read_b128 v[172:175], v176 offset:2048
	ds_read_b128 v[176:179], v176 offset:3072
	s_add_u32 s42, s42, 0x80000
	s_addc_u32 s43, s43, 0
	s_mov_b32 m0, s37
	v_lshl_add_u64 v[224:225], s[42:43], 0, v[148:149]
	ds_read_b128 v[184:187], v183 offset:32768
	ds_read_b128 v[188:191], v183 offset:33792
	ds_read_b128 v[192:195], v183 offset:34816
	ds_read_b128 v[196:199], v183 offset:35840
	ds_read_b128 v[200:203], v183 offset:36864
	ds_read_b128 v[204:207], v183 offset:37888
	ds_read_b128 v[208:211], v183 offset:38912
	ds_read_b128 v[212:215], v183 offset:39936
	global_load_lds_dwordx4 v[224:225], off
	v_lshl_add_u64 v[224:225], s[42:43], 0, v[152:153]
	s_mov_b32 m0, s44
	s_nop 0
	global_load_lds_dwordx4 v[224:225], off
	s_waitcnt vmcnt(8)
	s_waitcnt lgkmcnt(0)
	s_barrier
	s_nop 0
	s_waitcnt lgkmcnt(0)
	v_mfma_f32_16x16x32_bf16 v[124:127], v[128:131], v[184:187], v[124:127]
	v_mfma_f32_16x16x32_bf16 v[120:123], v[136:139], v[184:187], v[120:123]
	v_mfma_f32_16x16x32_bf16 v[116:119], v[128:131], v[192:195], v[116:119]
	v_mfma_f32_16x16x32_bf16 v[112:115], v[136:139], v[192:195], v[112:115]
	v_mfma_f32_16x16x32_bf16 v[108:111], v[128:131], v[200:203], v[108:111]
	v_mfma_f32_16x16x32_bf16 v[104:107], v[136:139], v[200:203], v[104:107]
	v_mfma_f32_16x16x32_bf16 v[100:103], v[128:131], v[208:211], v[100:103]
	v_mfma_f32_16x16x32_bf16 v[96:99], v[136:139], v[208:211], v[96:99]
	v_mfma_f32_16x16x32_bf16 v[124:127], v[132:135], v[188:191], v[124:127]
	v_mfma_f32_16x16x32_bf16 v[120:123], v[140:143], v[188:191], v[120:123]
	v_mfma_f32_16x16x32_bf16 v[116:119], v[132:135], v[196:199], v[116:119]
	v_mfma_f32_16x16x32_bf16 v[112:115], v[140:143], v[196:199], v[112:115]
	v_mfma_f32_16x16x32_bf16 v[108:111], v[132:135], v[204:207], v[108:111]
	v_mfma_f32_16x16x32_bf16 v[104:107], v[140:143], v[204:207], v[104:107]
	v_mfma_f32_16x16x32_bf16 v[100:103], v[132:135], v[212:215], v[100:103]
	v_mfma_f32_16x16x32_bf16 v[96:99], v[140:143], v[212:215], v[96:99]
	s_nop 0
	s_nop 0
	v_mfma_f32_16x16x32_bf16 v[64:67], v[164:167], v[184:187], v[64:67]
	v_mfma_f32_16x16x32_bf16 v[56:59], v[172:175], v[184:187], v[56:59]
	v_mfma_f32_16x16x32_bf16 v[52:55], v[164:167], v[192:195], v[52:55]
	v_mfma_f32_16x16x32_bf16 v[48:51], v[172:175], v[192:195], v[48:51]
	v_mfma_f32_16x16x32_bf16 v[44:47], v[164:167], v[200:203], v[44:47]
	v_mfma_f32_16x16x32_bf16 v[40:43], v[172:175], v[200:203], v[40:43]
	v_mfma_f32_16x16x32_bf16 v[36:39], v[164:167], v[208:211], v[36:39]
	v_mfma_f32_16x16x32_bf16 v[32:35], v[172:175], v[208:211], v[32:35]
	v_mfma_f32_16x16x32_bf16 v[64:67], v[168:171], v[188:191], v[64:67]
	v_mfma_f32_16x16x32_bf16 v[56:59], v[176:179], v[188:191], v[56:59]
	v_mfma_f32_16x16x32_bf16 v[52:55], v[168:171], v[196:199], v[52:55]
	v_mfma_f32_16x16x32_bf16 v[48:51], v[176:179], v[196:199], v[48:51]
	v_mfma_f32_16x16x32_bf16 v[44:47], v[168:171], v[204:207], v[44:47]
	v_mfma_f32_16x16x32_bf16 v[40:43], v[176:179], v[204:207], v[40:43]
	v_mfma_f32_16x16x32_bf16 v[36:39], v[168:171], v[212:215], v[36:39]
	v_mfma_f32_16x16x32_bf16 v[32:35], v[176:179], v[212:215], v[32:35]
	s_nop 0
	s_barrier
; #define PG8_STAGE(bufoff, gbase, voff) do { _Pragma("unroll") for (int _i = 0; _i < 2; ++_i) \
;         __builtin_amdgcn_global_load_lds((const unsigned*)((const char*)(gbase) + (voff)[_i]), (PG8_LAS unsigned*)(lds + (bufoff) + ldsw + _i * 8192), 16, 0, 0); } while (0)
; #define PG8_LDA(dst, b, h) do { _Pragma("unroll") for (int m = 0; m < 4; ++m) _Pragma("unroll") for (int k = 0; k < 2; ++k) dst[m][k] = *(const PG8_LAS bf16x8*)(lds + PG8_SA(b, h) + aoff + m * 2048 + k * 1024); } while (0)
; #define PG8_MMA(ai, bj, At, Bt) do { __builtin_amdgcn_s_setprio(1); _Pragma("unroll") for (int m = 0; m < 4; ++m) _Pragma("unroll") for (int n = 0; n < 2; ++n) _Pragma("unroll") for (int k = 0; k < 2; ++k) \
;         acc[ai][bj][m][n] = __builtin_amdgcn_mfma_f32_16x16x32_bf16(Bt[n][k], At[m][k], acc[ai][bj][m][n], 0, 0, 0); __builtin_amdgcn_s_setprio(0); } while (0)
; #define PG8_WAIT_V(n) asm volatile("s_waitcnt vmcnt(" #n ")" ::: "memory")
; #define PG8_WAIT_L(n) asm volatile("s_waitcnt lgkmcnt(" #n ")" ::: "memory")
; #define PG8_BAR __builtin_amdgcn_s_barrier()
; #define PG8_SCHED __builtin_amdgcn_sched_barrier(0)
; template <class Epi, class Sched, bool ALIGN_EPI = false, bool SP2 = false>
; __device__ __forceinline__ void gemm_phase(PG8_LAS unsigned char* lds, const Gemm g, const Sched& S, const Epi& E) {
;     ...
;         for (int t = 0; t < nt; t += 2) {
;             const bool last = (t == nt - 2);
;     ...
;             PG8_LDA(At, 1, 1); PG8_STAGE(PG8_SB(1, 0), b3, voffB); PG8_STAGE(PG8_SB(1, 1), b3 + hstep, voffB); PG8_STAGE(PG8_SA(1, 0), a3, voffA);
;             PG8_WAIT_V(8); PG8_WAIT_L(0); PG8_BAR; PG8_MMA(1, 0, At, B0); PG8_MMA(1, 1, At, B1); PG8_BAR; PG8_SCHED;
	s_add_i32 s42, s57, s15
	v_lshl_add_u64 v[216:217], v[216:217], 0, s[10:11]
	s_mov_b32 m0, s42
	ds_read_b128 v[184:187], v183 offset:49152
	ds_read_b128 v[188:191], v183 offset:50176
	ds_read_b128 v[192:195], v183 offset:51200
	ds_read_b128 v[196:199], v183 offset:52224
	ds_read_b128 v[200:203], v183 offset:53248
	ds_read_b128 v[204:207], v183 offset:54272
	ds_read_b128 v[208:211], v183 offset:55296
	ds_read_b128 v[212:215], v183 offset:56320
	global_load_lds_dwordx4 v[216:217], off
	s_add_i32 m0, s42, 0x2000
	s_add_u32 s40, s40, 0x80080
	v_lshl_add_u64 v[216:217], v[218:219], 0, s[10:11]
	s_addc_u32 s41, s41, 0
	s_add_i32 s42, s58, s15
	global_load_lds_dwordx4 v[216:217], off
	v_lshl_add_u64 v[216:217], s[40:41], 0, v[150:151]
	s_mov_b32 m0, s42
	s_nop 0
	global_load_lds_dwordx4 v[216:217], off
	v_lshl_add_u64 v[216:217], s[40:41], 0, v[154:155]
	s_add_i32 m0, s42, 0x2000
	s_nop 0
	global_load_lds_dwordx4 v[216:217], off
	v_lshl_add_u64 v[216:217], v[220:221], 0, s[10:11]
	s_mov_b32 m0, s46
	s_nop 0
	global_load_lds_dwordx4 v[216:217], off
	v_lshl_add_u64 v[216:217], v[222:223], 0, s[10:11]
	s_mov_b32 m0, s47
	s_nop 0
	global_load_lds_dwordx4 v[216:217], off
	s_waitcnt vmcnt(8)
	s_waitcnt lgkmcnt(0)
	s_barrier
	s_nop 0
	s_waitcnt lgkmcnt(0)
	v_mfma_f32_16x16x32_bf16 v[92:95], v[128:131], v[184:187], v[92:95]
	v_mfma_f32_16x16x32_bf16 v[88:91], v[136:139], v[184:187], v[88:91]
	v_mfma_f32_16x16x32_bf16 v[84:87], v[128:131], v[192:195], v[84:87]
	v_mfma_f32_16x16x32_bf16 v[80:83], v[136:139], v[192:195], v[80:83]
	v_mfma_f32_16x16x32_bf16 v[76:79], v[128:131], v[200:203], v[76:79]
	v_mfma_f32_16x16x32_bf16 v[72:75], v[136:139], v[200:203], v[72:75]
	v_mfma_f32_16x16x32_bf16 v[68:71], v[128:131], v[208:211], v[68:71]
	v_mfma_f32_16x16x32_bf16 v[60:63], v[136:139], v[208:211], v[60:63]
	v_mfma_f32_16x16x32_bf16 v[92:95], v[132:135], v[188:191], v[92:95]
	v_mfma_f32_16x16x32_bf16 v[88:91], v[140:143], v[188:191], v[88:91]
	v_mfma_f32_16x16x32_bf16 v[84:87], v[132:135], v[196:199], v[84:87]
	v_mfma_f32_16x16x32_bf16 v[80:83], v[140:143], v[196:199], v[80:83]
	v_mfma_f32_16x16x32_bf16 v[76:79], v[132:135], v[204:207], v[76:79]
	v_mfma_f32_16x16x32_bf16 v[72:75], v[140:143], v[204:207], v[72:75]
	v_mfma_f32_16x16x32_bf16 v[68:71], v[132:135], v[212:215], v[68:71]
	v_mfma_f32_16x16x32_bf16 v[60:63], v[140:143], v[212:215], v[60:63]
	s_nop 0
	s_nop 0
	v_mfma_f32_16x16x32_bf16 v[28:31], v[164:167], v[184:187], v[28:31]
	v_mfma_f32_16x16x32_bf16 v[24:27], v[172:175], v[184:187], v[24:27]
	v_mfma_f32_16x16x32_bf16 v[20:23], v[164:167], v[192:195], v[20:23]
	v_mfma_f32_16x16x32_bf16 v[16:19], v[172:175], v[192:195], v[16:19]
	v_mfma_f32_16x16x32_bf16 v[12:15], v[164:167], v[200:203], v[12:15]
	v_mfma_f32_16x16x32_bf16 v[8:11], v[172:175], v[200:203], v[8:11]
	v_mfma_f32_16x16x32_bf16 v[4:7], v[164:167], v[208:211], v[4:7]
	v_mfma_f32_16x16x32_bf16 v[0:3], v[172:175], v[208:211], v[0:3]
	v_mfma_f32_16x16x32_bf16 v[28:31], v[168:171], v[188:191], v[28:31]
	v_mfma_f32_16x16x32_bf16 v[24:27], v[176:179], v[188:191], v[24:27]
	v_mfma_f32_16x16x32_bf16 v[20:23], v[168:171], v[196:199], v[20:23]
	v_mfma_f32_16x16x32_bf16 v[16:19], v[176:179], v[196:199], v[16:19]
	v_mfma_f32_16x16x32_bf16 v[12:15], v[168:171], v[204:207], v[12:15]
	v_mfma_f32_16x16x32_bf16 v[8:11], v[176:179], v[204:207], v[8:11]
	v_mfma_f32_16x16x32_bf16 v[4:7], v[168:171], v[212:215], v[4:7]
	v_mfma_f32_16x16x32_bf16 v[0:3], v[176:179], v[212:215], v[0:3]
	s_nop 0
	s_barrier
	s_add_i32 s56, s56, 2
	s_add_u32 s38, s38, 0x100
	s_addc_u32 s39, s39, 0
	s_add_u32 s54, s54, 0x100
	s_addc_u32 s55, s55, 0
	s_cmp_gt_u32 s56, 29
	s_cbranch_scc0 .LBB0_1269
	s_and_b64 vcc, exec, s[12:13]
	s_cbranch_vccz .LBB0_1272
	s_barrier

; __device__ __forceinline__ unsigned xb_ld(unsigned* p)              { return __hip_atomic_load(p, __ATOMIC_RELAXED, __HIP_MEMORY_SCOPE_AGENT); }
; __device__ __forceinline__ void xcd_barrier_complete(unsigned* bar, unsigned x, unsigned& nloc, unsigned& nx) {
;     const unsigned G = gridDim.x * gridDim.y * gridDim.z;
;     unsigned sum, cnt, mine, sp = 0u;
;     for (;;) {
;         sum = 0u; cnt = 0u; mine = 0u;
; #pragma unroll
;         for (unsigned j = 0; j < 16; ++j) { const unsigned c = xb_ld(&bar[XB_XCNT(j)]); sum += c; cnt += (c > 0u) ? 1u : 0u; mine = (j == x) ? c : mine; }
; __device__ __forceinline__ void xcd_barrier(const XcdBarrier& b) {
;     asm volatile("s_waitcnt vmcnt(0)" ::: "memory");
;     __syncthreads();
;     if (threadIdx.x == 0) {
;         unsigned* bar = b.bar;
;         __builtin_amdgcn_s_waitcnt(0);
;         unsigned nloc = b.st[0], nx = b.st[1];
;         if (nloc == 0u) { xcd_barrier_complete(bar, b.x, nloc, nx); b.st[0] = nloc; b.st[1] = nx; }
.LBB0_1276:
	s_setprio 0
	s_cmp_gt_i32 s81, 13
	s_cselect_b64 s[0:1], -1, 0
	s_and_b64 s[4:5], s[4:5], s[0:1]
	s_andn2_b64 vcc, exec, s[4:5]
	s_cbranch_vccnz .LBB0_1326
	s_waitcnt vmcnt(0)
	v_cmp_eq_u32_e32 vcc, 0, v146
	s_waitcnt vmcnt(0) lgkmcnt(0)
	s_barrier
	s_and_saveexec_b64 s[4:5], vcc
	s_cbranch_execz .LBB0_1325
	s_add_i32 s3, 0, 0x20040
	v_mov_b32_e32 v0, s3
	s_waitcnt vmcnt(0) expcnt(0) lgkmcnt(0)
	ds_read_b32 v2, v0
	s_add_i32 s3, 0, 0x20044
	v_mov_b32_e32 v0, s3
	ds_read_b32 v0, v0
	s_waitcnt lgkmcnt(1)
	v_cmp_ne_u32_e32 vcc, 0, v2
	s_cbranch_vccnz .LBB0_1293
	v_readlane_b32 s2, v231, 0
	v_readlane_b32 s3, v231, 1
	s_load_dwordx2 s[10:11], s[2:3], 0x4
	s_add_u32 s6, s22, 0x1000
	s_addc_u32 s7, s23, 0
	s_add_u32 s8, s22, 0x1100
	s_addc_u32 s9, s23, 0
	s_waitcnt lgkmcnt(0)
	s_mul_i32 s3, s10, s18
	s_add_u32 s10, s22, 0x1200
	s_mul_i32 s3, s3, s11
	s_addc_u32 s11, s23, 0
	s_add_u32 s12, s22, 0x1300
	s_addc_u32 s13, s23, 0
	s_mov_b32 s19, 1
	v_mov_b32_e32 v16, 0
	s_branch .LBB0_1281

; #define PG8_STAGE(bufoff, gbase, voff) do { _Pragma("unroll") for (int _i = 0; _i < 2; ++_i) \
;         __builtin_amdgcn_global_load_lds((const unsigned*)((const char*)(gbase) + (voff)[_i]), (PG8_LAS unsigned*)(lds + (bufoff) + ldsw + _i * 8192), 16, 0, 0); } while (0)
; #define PG8_WAIT_V(n) asm volatile("s_waitcnt vmcnt(" #n ")" ::: "memory")
; #define PG8_BAR __builtin_amdgcn_s_barrier()
; template <class Epi, class Sched, bool ALIGN_EPI = false, bool SP2 = false>
; __device__ __forceinline__ void gemm_phase(PG8_LAS unsigned char* lds, const Gemm g, const Sched& S, const Epi& E) {
;     const int tid = threadIdx.x, wid = __builtin_amdgcn_readfirstlane(tid >> 6), lane = tid & 63, wr = wid >> 2, wc = wid & 3, fr = lane & 15, fq = lane >> 4;
;     const int K = g.K, nt = K / BK;
;     unsigned voffA[2], voffB[2];
; #pragma unroll
;     for (int i = 0; i < 2; ++i) { int R, C; stage_rc(tid * 16 + i * 8192, R, C); const int Rb = Epi::PERM ? ((R & ~31) + perm32(R & 31)) : R;
;         voffA[i] = (unsigned)(R * K + C) * 2u; voffB[i] = (unsigned)(Rb * K + C) * 2u; }
;     const size_t kstep = (size_t)(BK * 2);
;     const size_t hstep = (size_t)HALF * K * 2;
;     const size_t tstep = 2 * hstep;
;     const unsigned ldsw = (unsigned)wid * 1024u;
;     const int aoff = lds_byte(wr * 64 + fr, fq * 8), boff = lds_byte(wc * 32 + fr, fq * 8);
;     ...
;     Unit cur, nxt; int ui = 0;
;     if (!S.next(0, cur)) return;
;     f32x4 acc[2][2][4][2];
; #pragma unroll
;     for (int a = 0; a < 2; ++a)
; #pragma unroll
;         for (int b = 0; b < 2; ++b)
; #pragma unroll
;             for (int m = 0; m < 4; ++m)
; #pragma unroll
;                 for (int n = 0; n < 2; ++n) acc[a][b][m][n] = (f32x4){0.f, 0.f, 0.f, 0.f};
;     bf16x8 At[4][2], B0[2][2], B1[2][2];
;     const char* cA = (const char*)g.A + (size_t)cur.pm * tstep; const char* cB = (const char*)g.Bt + (size_t)cur.pn * tstep;
;     S.a_ready(cur);
;     if constexpr (SP2) {
;         PG8_STAGE(PG8_SB(0, 0), cB, voffB); PG8_STAGE(PG8_SB(0, 1), cB + hstep, voffB); PG8_STAGE(PG8_SA(0, 0), cA, voffA); PG8_STAGE(PG8_SA(0, 1), cA + hstep, voffA);
;         if (wr == 1) PG8_BAR;
;         PG8_WAIT_V(2); PG8_BAR;
;         PG8_STAGE(PG8_SB(1, 0), cB + kstep, voffB); PG8_STAGE(PG8_SA(1, 0), cA + kstep, voffA); PG8_STAGE(PG8_SB(1, 1), cB + hstep + kstep, voffB);
;         PG8_WAIT_V(6); PG8_BAR;
.LBB0_1384:
	s_cmp_lt_i32 s80, 15
	s_cselect_b64 s[4:5], -1, 0
	s_and_b64 s[4:5], s[4:5], s[0:1]
	s_andn2_b64 vcc, exec, s[4:5]
	s_cbranch_vccnz .LBB0_1401
	s_cmp_lt_u32 s82, 4
	s_cbranch_scc1 .Lprio_g14
	s_setprio 1
.Lprio_g14:
	s_cmpk_gt_i32 s84, 0x7ff
	v_readfirstlane_b32 s1, v146
	s_cbranch_scc1 .LBB0_1401
	v_lshrrev_b32_e32 v0, 5, v146
	v_lshrrev_b32_e32 v2, 1, v146
	v_and_b32_e32 v0, 4, v0
	v_bfe_u32 v1, v146, 2, 2
	v_and_b32_e32 v11, 24, v2
	v_or3_b32 v0, v0, v1, v11
	v_lshlrev_b32_e32 v1, 4, v146
	s_waitcnt lgkmcnt(0)
	v_add_u32_e32 v8, 0x2000, v1
	v_lshrrev_b32_e32 v2, 7, v8
	s_movk_i32 s0, 0xe0
	v_and_b32_e32 v4, 32, v146
	v_and_or_b32 v3, v2, s0, v0
	v_bitop3_b32 v9, v1, v4, 48 bitop3:0x6c
	v_and_b32_e32 v10, 64, v146
	v_bfe_u32 v12, v146, 2, 4
	s_movk_i32 s0, 0xf0
	v_or_b32_e32 v1, v9, v10
	v_and_or_b32 v2, v2, s0, v12
	s_waitcnt vmcnt(0)
	v_lshl_or_b32 v130, v2, 12, v1
	v_lshrrev_b32_e32 v2, 3, v146
	s_movk_i32 s0, 0x60
	v_and_or_b32 v0, v2, s0, v0
	s_movk_i32 s0, 0x70
	s_ashr_i32 s19, s84, 31
	v_lshl_or_b32 v132, v0, 12, v1
	v_and_or_b32 v0, v2, s0, v12
	s_lshr_b32 s0, s19, 29
	s_add_i32 s0, s84, s0
	s_lshr_b32 s8, s1, 6
	s_ashr_i32 s6, s0, 3
	s_and_b32 s0, s0, -8
	s_lshr_b32 s10, s1, 8
	s_lshl_b32 s3, s8, 10
	s_sub_i32 s0, s84, s0
	s_cmp_lt_i32 s0, 0
	s_movk_i32 s33, 0x101
	s_cselect_b32 s7, s33, 0x100
	s_mul_i32 s0, s7, s0
	s_add_i32 s0, s0, s6
	s_ashr_i32 s6, s0, 31
	s_lshr_b32 s6, s6, 24
	s_add_i32 s6, s0, s6
	s_ashr_i32 s7, s6, 8
	s_and_b32 s6, s6, 0xffffff00
	s_sub_i32 s6, s0, s6
	s_sext_i32_i16 s0, s6
	s_bfe_u32 s0, s0, 0x3001c
	s_add_i32 s9, s6, s0
	s_sext_i32_i16 s0, s9
	s_and_b32 s9, s9, 0xfff8
	s_sub_i32 s6, s6, s9
	s_lshl_b32 s7, s7, 3
	s_sext_i32_i16 s6, s6
	s_lshr_b32 s0, s0, 3
	s_add_i32 s40, s7, s6
	s_ashr_i32 s41, s40, 31
	s_bfe_i64 s[12:13], s[0:1], 0x100000
	s_lshl_b64 s[6:7], s[40:41], 20
	s_lshl_b64 s[12:13], s[12:13], 20
	v_readlane_b32 s14, v231, 22
	v_readlane_b32 s15, v231, 23
	s_add_u32 s44, s14, s12
	s_addc_u32 s45, s15, s13
	s_add_i32 s41, s3, 0
	s_add_i32 m0, s41, 0x10000
	v_lshl_or_b32 v128, v3, 12, v1
	global_load_lds_dwordx4 v132, s[44:45]
	s_add_i32 m0, s41, 0x12000
	s_add_u32 s12, s44, 0x80000
	global_load_lds_dwordx4 v128, s[44:45]
	s_addc_u32 s13, s45, 0
	s_add_i32 m0, s41, 0x14000
	v_lshl_or_b32 v134, v0, 12, v1
	global_load_lds_dwordx4 v132, s[12:13]
	s_add_i32 m0, s41, 0x16000
	s_add_u32 s42, s96, s6
	s_addc_u32 s43, s97, s7
	s_add_i32 s48, s41, 0x2000
	global_load_lds_dwordx4 v128, s[12:13]
	s_mov_b32 m0, s41
	s_add_u32 s6, s42, 0x80000
	global_load_lds_dwordx4 v134, s[42:43]
	s_mov_b32 m0, s48
	s_addc_u32 s7, s43, 0
	s_add_i32 s49, s41, 0x4000
	global_load_lds_dwordx4 v130, s[42:43]
	s_mov_b32 m0, s49
	s_add_i32 s50, s41, 0x6000
	global_load_lds_dwordx4 v134, s[6:7]
	s_mov_b32 m0, s50
	v_mov_b32_e32 v133, 0
	global_load_lds_dwordx4 v130, s[6:7]
	v_mov_b32_e32 v129, v133
	v_mov_b32_e32 v135, v133
	v_mov_b32_e32 v131, v133
	s_cmp_eq_u32 s10, 1
	s_mov_b32 s51, 0
	v_lshl_add_u64 v[6:7], s[44:45], 0, v[132:133]
	v_lshl_add_u64 v[4:5], s[44:45], 0, v[128:129]
	v_lshl_add_u64 v[0:1], s[42:43], 0, v[134:135]
	s_cselect_b64 s[6:7], -1, 0
	s_cmp_lg_u32 s10, 1
	v_lshl_add_u64 v[2:3], s[42:43], 0, v[130:131]
	s_cbranch_scc1 .LBB0_1388
	s_barrier

; #define PG8_STAGE(bufoff, gbase, voff) do { _Pragma("unroll") for (int _i = 0; _i < 2; ++_i) \
;         __builtin_amdgcn_global_load_lds((const unsigned*)((const char*)(gbase) + (voff)[_i]), (PG8_LAS unsigned*)(lds + (bufoff) + ldsw + _i * 8192), 16, 0, 0); } while (0)
; #define PG8_LDA(dst, b, h) do { _Pragma("unroll") for (int m = 0; m < 4; ++m) _Pragma("unroll") for (int k = 0; k < 2; ++k) dst[m][k] = *(const PG8_LAS bf16x8*)(lds + PG8_SA(b, h) + aoff + m * 2048 + k * 1024); } while (0)
; #define PG8_LDB(dst, b, h) do { _Pragma("unroll") for (int n = 0; n < 2; ++n) _Pragma("unroll") for (int k = 0; k < 2; ++k) dst[n][k] = *(const PG8_LAS bf16x8*)(lds + PG8_SB(b, h) + boff + n * 2048 + k * 1024); } while (0)
; #define PG8_MMA(ai, bj, At, Bt) do { __builtin_amdgcn_s_setprio(1); _Pragma("unroll") for (int m = 0; m < 4; ++m) _Pragma("unroll") for (int n = 0; n < 2; ++n) _Pragma("unroll") for (int k = 0; k < 2; ++k) \
;         acc[ai][bj][m][n] = __builtin_amdgcn_mfma_f32_16x16x32_bf16(Bt[n][k], At[m][k], acc[ai][bj][m][n], 0, 0, 0); __builtin_amdgcn_s_setprio(0); } while (0)
; #define PG8_WAIT_V(n) asm volatile("s_waitcnt vmcnt(" #n ")" ::: "memory")
; #define PG8_WAIT_L(n) asm volatile("s_waitcnt lgkmcnt(" #n ")" ::: "memory")
; #define PG8_BAR __builtin_amdgcn_s_barrier()
; #define PG8_SCHED __builtin_amdgcn_sched_barrier(0)
; template <class Epi, class Sched, bool ALIGN_EPI = false, bool SP2 = false>
; __device__ __forceinline__ void gemm_phase(PG8_LAS unsigned char* lds, const Gemm g, const Sched& S, const Epi& E) {
;     ...
;         for (int t = 0; t < nt; t += 2) {
;             const bool last = (t == nt - 2);
;             const char* a1 = cA + (size_t)(t + 1) * kstep;
;             const char* a2 = last ? nA : cA + (size_t)(t + 2) * kstep; const char* b2 = last ? nB : cB + (size_t)(t + 2) * kstep;
;             const char* a3 = a2 + kstep; const char* b3 = b2 + kstep;
;             if (last && has_next) S.a_ready(nxt);
;             if constexpr (SP2) {
;             PG8_LDB(B0, 0, 0); PG8_LDB(B1, 0, 1); PG8_SCHED; PG8_LDA(At, 0, 0); PG8_STAGE(PG8_SA(1, 1), a1 + hstep, voffA);
;             PG8_WAIT_V(8); PG8_WAIT_L(0); PG8_BAR; PG8_MMA(0, 0, At, B0); PG8_MMA(0, 1, At, B1); PG8_BAR; PG8_SCHED;
;             PG8_LDA(At, 0, 1); PG8_STAGE(PG8_SB(0, 0), b2, voffB); PG8_STAGE(PG8_SB(0, 1), b2 + hstep, voffB); PG8_STAGE(PG8_SA(0, 0), a2, voffA);
.LBB0_1394:
	ds_read_b128 v[154:157], v151
	ds_read_b128 v[158:161], v151 offset:1024
	ds_read_b128 v[162:165], v151 offset:2048
	ds_read_b128 v[166:169], v151 offset:3072
	ds_read_b128 v[170:173], v152
	ds_read_b128 v[174:177], v152 offset:1024
	ds_read_b128 v[178:181], v152 offset:2048
	ds_read_b128 v[182:185], v152 offset:3072
	s_add_u32 s44, s42, 0xfff80080
	s_addc_u32 s45, s43, -1
	s_cmp_eq_u32 s66, 28
	s_cselect_b32 s47, s35, s45
	s_cselect_b32 s46, s62, s44
	s_cselect_b32 s45, s31, s65
	s_cselect_b32 s44, s63, s64
	v_lshl_add_u64 v[148:149], s[42:43], 0, v[136:137]
	s_add_i32 m0, s41, 0xc000
	ds_read_b128 v[186:189], v153
	ds_read_b128 v[190:193], v153 offset:1024
	ds_read_b128 v[194:197], v153 offset:2048
	ds_read_b128 v[198:201], v153 offset:3072
	ds_read_b128 v[202:205], v153 offset:4096
	ds_read_b128 v[206:209], v153 offset:5120
	ds_read_b128 v[210:213], v153 offset:6144
	ds_read_b128 v[214:217], v153 offset:7168
	global_load_lds_dwordx4 v[148:149], off
	v_lshl_add_u64 v[148:149], s[42:43], 0, v[138:139]
	s_add_i32 m0, s41, 0xe000
	s_nop 0
	global_load_lds_dwordx4 v[148:149], off
	s_waitcnt vmcnt(8)
	s_waitcnt lgkmcnt(0)
	s_barrier
	s_nop 0
	s_waitcnt lgkmcnt(0)
	v_mfma_f32_16x16x32_bf16 v[124:127], v[154:157], v[186:189], v[124:127]
	v_mfma_f32_16x16x32_bf16 v[120:123], v[162:165], v[186:189], v[120:123]
	v_mfma_f32_16x16x32_bf16 v[108:111], v[154:157], v[194:197], v[108:111]
	v_mfma_f32_16x16x32_bf16 v[104:107], v[162:165], v[194:197], v[104:107]
	v_mfma_f32_16x16x32_bf16 v[92:95], v[154:157], v[202:205], v[92:95]
	v_mfma_f32_16x16x32_bf16 v[88:91], v[162:165], v[202:205], v[88:91]
	v_mfma_f32_16x16x32_bf16 v[76:79], v[154:157], v[210:213], v[76:79]
	v_mfma_f32_16x16x32_bf16 v[72:75], v[162:165], v[210:213], v[72:75]
	v_mfma_f32_16x16x32_bf16 v[124:127], v[158:161], v[190:193], v[124:127]
	v_mfma_f32_16x16x32_bf16 v[120:123], v[166:169], v[190:193], v[120:123]
	v_mfma_f32_16x16x32_bf16 v[108:111], v[158:161], v[198:201], v[108:111]
	v_mfma_f32_16x16x32_bf16 v[104:107], v[166:169], v[198:201], v[104:107]
	v_mfma_f32_16x16x32_bf16 v[92:95], v[158:161], v[206:209], v[92:95]
	v_mfma_f32_16x16x32_bf16 v[88:91], v[166:169], v[206:209], v[88:91]
	v_mfma_f32_16x16x32_bf16 v[76:79], v[158:161], v[214:217], v[76:79]
	v_mfma_f32_16x16x32_bf16 v[72:75], v[166:169], v[214:217], v[72:75]
	s_nop 0
	s_nop 0
	v_mfma_f32_16x16x32_bf16 v[116:119], v[170:173], v[186:189], v[116:119]
	v_mfma_f32_16x16x32_bf16 v[112:115], v[178:181], v[186:189], v[112:115]
	v_mfma_f32_16x16x32_bf16 v[100:103], v[170:173], v[194:197], v[100:103]
	v_mfma_f32_16x16x32_bf16 v[96:99], v[178:181], v[194:197], v[96:99]
	v_mfma_f32_16x16x32_bf16 v[84:87], v[170:173], v[202:205], v[84:87]
	v_mfma_f32_16x16x32_bf16 v[80:83], v[178:181], v[202:205], v[80:83]
	v_mfma_f32_16x16x32_bf16 v[68:71], v[170:173], v[210:213], v[68:71]
	v_mfma_f32_16x16x32_bf16 v[64:67], v[178:181], v[210:213], v[64:67]
	v_mfma_f32_16x16x32_bf16 v[116:119], v[174:177], v[190:193], v[116:119]
	v_mfma_f32_16x16x32_bf16 v[112:115], v[182:185], v[190:193], v[112:115]
	v_mfma_f32_16x16x32_bf16 v[100:103], v[174:177], v[198:201], v[100:103]
	v_mfma_f32_16x16x32_bf16 v[96:99], v[182:185], v[198:201], v[96:99]
	v_mfma_f32_16x16x32_bf16 v[84:87], v[174:177], v[206:209], v[84:87]
	v_mfma_f32_16x16x32_bf16 v[80:83], v[182:185], v[206:209], v[80:83]
	v_mfma_f32_16x16x32_bf16 v[68:71], v[174:177], v[214:217], v[68:71]
	v_mfma_f32_16x16x32_bf16 v[64:67], v[182:185], v[214:217], v[64:67]
	s_nop 0
	s_barrier
	s_add_i32 s67, s55, s3
	v_lshl_add_u64 v[148:149], s[44:45], 0, v[132:133]
	s_mov_b32 m0, s67
	ds_read_b128 v[186:189], v153 offset:16384
	ds_read_b128 v[190:193], v153 offset:17408
	ds_read_b128 v[194:197], v153 offset:18432
	ds_read_b128 v[198:201], v153 offset:19456
	ds_read_b128 v[202:205], v153 offset:20480
	ds_read_b128 v[206:209], v153 offset:21504
	ds_read_b128 v[210:213], v153 offset:22528
	ds_read_b128 v[214:217], v153 offset:23552
	global_load_lds_dwordx4 v[148:149], off
	s_add_i32 m0, s67, 0x2000
	s_add_u32 s68, s44, 0x80000
	v_lshl_add_u64 v[218:219], s[44:45], 0, v[128:129]
	s_addc_u32 s69, s45, 0
	s_add_i32 s67, s56, s3
	global_load_lds_dwordx4 v[218:219], off
	v_lshl_add_u64 v[220:221], s[68:69], 0, v[132:133]
	s_mov_b32 m0, s67
	v_lshl_add_u64 v[222:223], s[46:47], 0, v[130:131]
	global_load_lds_dwordx4 v[220:221], off
	v_lshl_add_u64 v[220:221], s[68:69], 0, v[128:129]
	s_add_i32 m0, s67, 0x2000
	s_nop 0
	global_load_lds_dwordx4 v[220:221], off
	v_lshl_add_u64 v[220:221], s[46:47], 0, v[134:135]
	s_mov_b32 m0, s41
	s_nop 0
	global_load_lds_dwordx4 v[220:221], off
	s_mov_b32 m0, s48
	s_nop 0
	global_load_lds_dwordx4 v[222:223], off
	s_waitcnt vmcnt(8)
	s_waitcnt lgkmcnt(0)
	s_barrier
; #define PG8_STAGE(bufoff, gbase, voff) do { _Pragma("unroll") for (int _i = 0; _i < 2; ++_i) \
;         __builtin_amdgcn_global_load_lds((const unsigned*)((const char*)(gbase) + (voff)[_i]), (PG8_LAS unsigned*)(lds + (bufoff) + ldsw + _i * 8192), 16, 0, 0); } while (0)
; #define PG8_LDA(dst, b, h) do { _Pragma("unroll") for (int m = 0; m < 4; ++m) _Pragma("unroll") for (int k = 0; k < 2; ++k) dst[m][k] = *(const PG8_LAS bf16x8*)(lds + PG8_SA(b, h) + aoff + m * 2048 + k * 1024); } while (0)
; #define PG8_LDB(dst, b, h) do { _Pragma("unroll") for (int n = 0; n < 2; ++n) _Pragma("unroll") for (int k = 0; k < 2; ++k) dst[n][k] = *(const PG8_LAS bf16x8*)(lds + PG8_SB(b, h) + boff + n * 2048 + k * 1024); } while (0)
; #define PG8_MMA(ai, bj, At, Bt) do { __builtin_amdgcn_s_setprio(1); _Pragma("unroll") for (int m = 0; m < 4; ++m) _Pragma("unroll") for (int n = 0; n < 2; ++n) _Pragma("unroll") for (int k = 0; k < 2; ++k) \
;         acc[ai][bj][m][n] = __builtin_amdgcn_mfma_f32_16x16x32_bf16(Bt[n][k], At[m][k], acc[ai][bj][m][n], 0, 0, 0); __builtin_amdgcn_s_setprio(0); } while (0)
; #define PG8_WAIT_V(n) asm volatile("s_waitcnt vmcnt(" #n ")" ::: "memory")
; #define PG8_WAIT_L(n) asm volatile("s_waitcnt lgkmcnt(" #n ")" ::: "memory")
; #define PG8_BAR __builtin_amdgcn_s_barrier()
; #define PG8_SCHED __builtin_amdgcn_sched_barrier(0)
; template <class Epi, class Sched, bool ALIGN_EPI = false, bool SP2 = false>
; __device__ __forceinline__ void gemm_phase(PG8_LAS unsigned char* lds, const Gemm g, const Sched& S, const Epi& E) {
;     ...
;             PG8_WAIT_V(8); PG8_WAIT_L(0); PG8_BAR; PG8_MMA(1, 0, At, B0); PG8_MMA(1, 1, At, B1); PG8_BAR; PG8_SCHED;
;             PG8_LDB(B0, 1, 0); PG8_LDB(B1, 1, 1); PG8_SCHED; PG8_LDA(At, 1, 0); PG8_STAGE(PG8_SA(0, 1), a2 + hstep, voffA);
;             PG8_WAIT_V(8); PG8_WAIT_L(0); PG8_BAR; PG8_MMA(0, 0, At, B0); PG8_MMA(0, 1, At, B1); PG8_BAR; PG8_SCHED;
	s_nop 0
	s_waitcnt lgkmcnt(0)
	v_mfma_f32_16x16x32_bf16 v[60:63], v[154:157], v[186:189], v[60:63]
	v_mfma_f32_16x16x32_bf16 v[56:59], v[162:165], v[186:189], v[56:59]
	v_mfma_f32_16x16x32_bf16 v[44:47], v[154:157], v[194:197], v[44:47]
	v_mfma_f32_16x16x32_bf16 v[40:43], v[162:165], v[194:197], v[40:43]
	v_mfma_f32_16x16x32_bf16 v[28:31], v[154:157], v[202:205], v[28:31]
	v_mfma_f32_16x16x32_bf16 v[24:27], v[162:165], v[202:205], v[24:27]
	v_mfma_f32_16x16x32_bf16 v[12:15], v[154:157], v[210:213], v[12:15]
	v_mfma_f32_16x16x32_bf16 v[8:11], v[162:165], v[210:213], v[8:11]
	v_mfma_f32_16x16x32_bf16 v[60:63], v[158:161], v[190:193], v[60:63]
	v_mfma_f32_16x16x32_bf16 v[56:59], v[166:169], v[190:193], v[56:59]
	v_mfma_f32_16x16x32_bf16 v[44:47], v[158:161], v[198:201], v[44:47]
	v_mfma_f32_16x16x32_bf16 v[40:43], v[166:169], v[198:201], v[40:43]
	v_mfma_f32_16x16x32_bf16 v[28:31], v[158:161], v[206:209], v[28:31]
	v_mfma_f32_16x16x32_bf16 v[24:27], v[166:169], v[206:209], v[24:27]
	v_mfma_f32_16x16x32_bf16 v[12:15], v[158:161], v[214:217], v[12:15]
	v_mfma_f32_16x16x32_bf16 v[8:11], v[166:169], v[214:217], v[8:11]
	s_nop 0
	s_nop 0
	v_mfma_f32_16x16x32_bf16 v[52:55], v[170:173], v[186:189], v[52:55]
	v_mfma_f32_16x16x32_bf16 v[48:51], v[178:181], v[186:189], v[48:51]
	v_mfma_f32_16x16x32_bf16 v[36:39], v[170:173], v[194:197], v[36:39]
	v_mfma_f32_16x16x32_bf16 v[32:35], v[178:181], v[194:197], v[32:35]
	v_mfma_f32_16x16x32_bf16 v[20:23], v[170:173], v[202:205], v[20:23]
	v_mfma_f32_16x16x32_bf16 v[16:19], v[178:181], v[202:205], v[16:19]
	v_mfma_f32_16x16x32_bf16 v[4:7], v[170:173], v[210:213], v[4:7]
	v_mfma_f32_16x16x32_bf16 v[0:3], v[178:181], v[210:213], v[0:3]
	v_mfma_f32_16x16x32_bf16 v[52:55], v[174:177], v[190:193], v[52:55]
	v_mfma_f32_16x16x32_bf16 v[48:51], v[182:185], v[190:193], v[48:51]
	v_mfma_f32_16x16x32_bf16 v[36:39], v[174:177], v[198:201], v[36:39]
	v_mfma_f32_16x16x32_bf16 v[32:35], v[182:185], v[198:201], v[32:35]
	v_mfma_f32_16x16x32_bf16 v[20:23], v[174:177], v[206:209], v[20:23]
	v_mfma_f32_16x16x32_bf16 v[16:19], v[182:185], v[206:209], v[16:19]
	v_mfma_f32_16x16x32_bf16 v[4:7], v[174:177], v[214:217], v[4:7]
	v_mfma_f32_16x16x32_bf16 v[0:3], v[182:185], v[214:217], v[0:3]
	s_nop 0
	s_barrier
	s_add_i32 s67, 0, 0x18000
	s_add_i32 s68, 0, 0x1c000
	v_add_u32_e32 v166, s67, v147
	v_add_u32_e32 v182, s68, v147
	ds_read_b128 v[154:157], v166
	ds_read_b128 v[158:161], v166 offset:1024
	ds_read_b128 v[162:165], v166 offset:2048
	ds_read_b128 v[166:169], v166 offset:3072
	ds_read_b128 v[170:173], v182
	ds_read_b128 v[174:177], v182 offset:1024
	ds_read_b128 v[178:181], v182 offset:2048
	ds_read_b128 v[182:185], v182 offset:3072
	s_add_u32 s46, s46, 0x80000
	s_addc_u32 s47, s47, 0
	s_mov_b32 m0, s49
	v_lshl_add_u64 v[224:225], s[46:47], 0, v[134:135]
	ds_read_b128 v[186:189], v153 offset:32768
	ds_read_b128 v[190:193], v153 offset:33792
	ds_read_b128 v[194:197], v153 offset:34816
	ds_read_b128 v[198:201], v153 offset:35840
	ds_read_b128 v[202:205], v153 offset:36864
	ds_read_b128 v[206:209], v153 offset:37888
	ds_read_b128 v[210:213], v153 offset:38912
	ds_read_b128 v[214:217], v153 offset:39936
	global_load_lds_dwordx4 v[224:225], off
	v_lshl_add_u64 v[224:225], s[46:47], 0, v[130:131]
	s_mov_b32 m0, s50
	s_nop 0
	global_load_lds_dwordx4 v[224:225], off
	s_waitcnt vmcnt(8)
	s_waitcnt lgkmcnt(0)
	s_barrier
	s_nop 0
	s_waitcnt lgkmcnt(0)
	v_mfma_f32_16x16x32_bf16 v[124:127], v[154:157], v[186:189], v[124:127]
	v_mfma_f32_16x16x32_bf16 v[120:123], v[162:165], v[186:189], v[120:123]
	v_mfma_f32_16x16x32_bf16 v[108:111], v[154:157], v[194:197], v[108:111]
	v_mfma_f32_16x16x32_bf16 v[104:107], v[162:165], v[194:197], v[104:107]
	v_mfma_f32_16x16x32_bf16 v[92:95], v[154:157], v[202:205], v[92:95]
	v_mfma_f32_16x16x32_bf16 v[88:91], v[162:165], v[202:205], v[88:91]
	v_mfma_f32_16x16x32_bf16 v[76:79], v[154:157], v[210:213], v[76:79]
	v_mfma_f32_16x16x32_bf16 v[72:75], v[162:165], v[210:213], v[72:75]
	v_mfma_f32_16x16x32_bf16 v[124:127], v[158:161], v[190:193], v[124:127]
	v_mfma_f32_16x16x32_bf16 v[120:123], v[166:169], v[190:193], v[120:123]
	v_mfma_f32_16x16x32_bf16 v[108:111], v[158:161], v[198:201], v[108:111]
	v_mfma_f32_16x16x32_bf16 v[104:107], v[166:169], v[198:201], v[104:107]
	v_mfma_f32_16x16x32_bf16 v[92:95], v[158:161], v[206:209], v[92:95]
	v_mfma_f32_16x16x32_bf16 v[88:91], v[166:169], v[206:209], v[88:91]
	v_mfma_f32_16x16x32_bf16 v[76:79], v[158:161], v[214:217], v[76:79]
	v_mfma_f32_16x16x32_bf16 v[72:75], v[166:169], v[214:217], v[72:75]
	s_nop 0
	s_nop 0
	v_mfma_f32_16x16x32_bf16 v[116:119], v[170:173], v[186:189], v[116:119]
	v_mfma_f32_16x16x32_bf16 v[112:115], v[178:181], v[186:189], v[112:115]
	v_mfma_f32_16x16x32_bf16 v[100:103], v[170:173], v[194:197], v[100:103]
	v_mfma_f32_16x16x32_bf16 v[96:99], v[178:181], v[194:197], v[96:99]
	v_mfma_f32_16x16x32_bf16 v[84:87], v[170:173], v[202:205], v[84:87]
	v_mfma_f32_16x16x32_bf16 v[80:83], v[178:181], v[202:205], v[80:83]
	v_mfma_f32_16x16x32_bf16 v[68:71], v[170:173], v[210:213], v[68:71]
	v_mfma_f32_16x16x32_bf16 v[64:67], v[178:181], v[210:213], v[64:67]
	v_mfma_f32_16x16x32_bf16 v[116:119], v[174:177], v[190:193], v[116:119]
	v_mfma_f32_16x16x32_bf16 v[112:115], v[182:185], v[190:193], v[112:115]
	v_mfma_f32_16x16x32_bf16 v[100:103], v[174:177], v[198:201], v[100:103]
	v_mfma_f32_16x16x32_bf16 v[96:99], v[182:185], v[198:201], v[96:99]
	v_mfma_f32_16x16x32_bf16 v[84:87], v[174:177], v[206:209], v[84:87]
	v_mfma_f32_16x16x32_bf16 v[80:83], v[182:185], v[206:209], v[80:83]
	v_mfma_f32_16x16x32_bf16 v[68:71], v[174:177], v[214:217], v[68:71]
	v_mfma_f32_16x16x32_bf16 v[64:67], v[182:185], v[214:217], v[64:67]
	s_nop 0
	s_barrier
; #define PG8_STAGE(bufoff, gbase, voff) do { _Pragma("unroll") for (int _i = 0; _i < 2; ++_i) \
;         __builtin_amdgcn_global_load_lds((const unsigned*)((const char*)(gbase) + (voff)[_i]), (PG8_LAS unsigned*)(lds + (bufoff) + ldsw + _i * 8192), 16, 0, 0); } while (0)
; #define PG8_LDA(dst, b, h) do { _Pragma("unroll") for (int m = 0; m < 4; ++m) _Pragma("unroll") for (int k = 0; k < 2; ++k) dst[m][k] = *(const PG8_LAS bf16x8*)(lds + PG8_SA(b, h) + aoff + m * 2048 + k * 1024); } while (0)
; #define PG8_MMA(ai, bj, At, Bt) do { __builtin_amdgcn_s_setprio(1); _Pragma("unroll") for (int m = 0; m < 4; ++m) _Pragma("unroll") for (int n = 0; n < 2; ++n) _Pragma("unroll") for (int k = 0; k < 2; ++k) \
;         acc[ai][bj][m][n] = __builtin_amdgcn_mfma_f32_16x16x32_bf16(Bt[n][k], At[m][k], acc[ai][bj][m][n], 0, 0, 0); __builtin_amdgcn_s_setprio(0); } while (0)
; #define PG8_WAIT_V(n) asm volatile("s_waitcnt vmcnt(" #n ")" ::: "memory")
; #define PG8_WAIT_L(n) asm volatile("s_waitcnt lgkmcnt(" #n ")" ::: "memory")
; #define PG8_BAR __builtin_amdgcn_s_barrier()
; #define PG8_SCHED __builtin_amdgcn_sched_barrier(0)
; template <class Epi, class Sched, bool ALIGN_EPI = false, bool SP2 = false>
; __device__ __forceinline__ void gemm_phase(PG8_LAS unsigned char* lds, const Gemm g, const Sched& S, const Epi& E) {
;     ...
;         for (int t = 0; t < nt; t += 2) {
;             const bool last = (t == nt - 2);
;     ...
;             PG8_LDA(At, 1, 1); PG8_STAGE(PG8_SB(1, 0), b3, voffB); PG8_STAGE(PG8_SB(1, 1), b3 + hstep, voffB); PG8_STAGE(PG8_SA(1, 0), a3, voffA);
;             PG8_WAIT_V(8); PG8_WAIT_L(0); PG8_BAR; PG8_MMA(1, 0, At, B0); PG8_MMA(1, 1, At, B1); PG8_BAR; PG8_SCHED;
	s_add_i32 s46, s67, s3
	v_lshl_add_u64 v[148:149], v[148:149], 0, s[8:9]
	s_mov_b32 m0, s46
	ds_read_b128 v[186:189], v153 offset:49152
	ds_read_b128 v[190:193], v153 offset:50176
	ds_read_b128 v[194:197], v153 offset:51200
	ds_read_b128 v[198:201], v153 offset:52224
	ds_read_b128 v[202:205], v153 offset:53248
	ds_read_b128 v[206:209], v153 offset:54272
	ds_read_b128 v[210:213], v153 offset:55296
	ds_read_b128 v[214:217], v153 offset:56320
	global_load_lds_dwordx4 v[148:149], off
	s_add_i32 m0, s46, 0x2000
	s_add_u32 s44, s44, 0x80080
	v_lshl_add_u64 v[148:149], v[218:219], 0, s[8:9]
	s_addc_u32 s45, s45, 0
	s_add_i32 s46, s68, s3
	global_load_lds_dwordx4 v[148:149], off
	v_lshl_add_u64 v[148:149], s[44:45], 0, v[132:133]
	s_mov_b32 m0, s46
	s_nop 0
	global_load_lds_dwordx4 v[148:149], off
	v_lshl_add_u64 v[148:149], s[44:45], 0, v[128:129]
	s_add_i32 m0, s46, 0x2000
	s_nop 0
	global_load_lds_dwordx4 v[148:149], off
	v_lshl_add_u64 v[148:149], v[220:221], 0, s[8:9]
	s_mov_b32 m0, s52
	s_nop 0
	global_load_lds_dwordx4 v[148:149], off
	v_lshl_add_u64 v[148:149], v[222:223], 0, s[8:9]
	s_mov_b32 m0, s53
	s_nop 0
	global_load_lds_dwordx4 v[148:149], off
	s_waitcnt vmcnt(8)
	s_waitcnt lgkmcnt(0)
	s_barrier
	s_nop 0
	s_waitcnt lgkmcnt(0)
	v_mfma_f32_16x16x32_bf16 v[60:63], v[154:157], v[186:189], v[60:63]
	v_mfma_f32_16x16x32_bf16 v[56:59], v[162:165], v[186:189], v[56:59]
	v_mfma_f32_16x16x32_bf16 v[44:47], v[154:157], v[194:197], v[44:47]
	v_mfma_f32_16x16x32_bf16 v[40:43], v[162:165], v[194:197], v[40:43]
	v_mfma_f32_16x16x32_bf16 v[28:31], v[154:157], v[202:205], v[28:31]
	v_mfma_f32_16x16x32_bf16 v[24:27], v[162:165], v[202:205], v[24:27]
	v_mfma_f32_16x16x32_bf16 v[12:15], v[154:157], v[210:213], v[12:15]
	v_mfma_f32_16x16x32_bf16 v[8:11], v[162:165], v[210:213], v[8:11]
	v_mfma_f32_16x16x32_bf16 v[60:63], v[158:161], v[190:193], v[60:63]
	v_mfma_f32_16x16x32_bf16 v[56:59], v[166:169], v[190:193], v[56:59]
	v_mfma_f32_16x16x32_bf16 v[44:47], v[158:161], v[198:201], v[44:47]
	v_mfma_f32_16x16x32_bf16 v[40:43], v[166:169], v[198:201], v[40:43]
	v_mfma_f32_16x16x32_bf16 v[28:31], v[158:161], v[206:209], v[28:31]
	v_mfma_f32_16x16x32_bf16 v[24:27], v[166:169], v[206:209], v[24:27]
	v_mfma_f32_16x16x32_bf16 v[12:15], v[158:161], v[214:217], v[12:15]
	v_mfma_f32_16x16x32_bf16 v[8:11], v[166:169], v[214:217], v[8:11]
	s_nop 0
	s_nop 0
	v_mfma_f32_16x16x32_bf16 v[52:55], v[170:173], v[186:189], v[52:55]
	v_mfma_f32_16x16x32_bf16 v[48:51], v[178:181], v[186:189], v[48:51]
	v_mfma_f32_16x16x32_bf16 v[36:39], v[170:173], v[194:197], v[36:39]
	v_mfma_f32_16x16x32_bf16 v[32:35], v[178:181], v[194:197], v[32:35]
	v_mfma_f32_16x16x32_bf16 v[20:23], v[170:173], v[202:205], v[20:23]
	v_mfma_f32_16x16x32_bf16 v[16:19], v[178:181], v[202:205], v[16:19]
	v_mfma_f32_16x16x32_bf16 v[4:7], v[170:173], v[210:213], v[4:7]
	v_mfma_f32_16x16x32_bf16 v[0:3], v[178:181], v[210:213], v[0:3]
	v_mfma_f32_16x16x32_bf16 v[52:55], v[174:177], v[190:193], v[52:55]
	v_mfma_f32_16x16x32_bf16 v[48:51], v[182:185], v[190:193], v[48:51]
	v_mfma_f32_16x16x32_bf16 v[36:39], v[174:177], v[198:201], v[36:39]
	v_mfma_f32_16x16x32_bf16 v[32:35], v[182:185], v[198:201], v[32:35]
	v_mfma_f32_16x16x32_bf16 v[20:23], v[174:177], v[206:209], v[20:23]
	v_mfma_f32_16x16x32_bf16 v[16:19], v[182:185], v[206:209], v[16:19]
	v_mfma_f32_16x16x32_bf16 v[4:7], v[174:177], v[214:217], v[4:7]
	v_mfma_f32_16x16x32_bf16 v[0:3], v[182:185], v[214:217], v[0:3]
	s_nop 0
	s_barrier
	s_add_i32 s66, s66, 2
	s_add_u32 s42, s42, 0x100
	s_addc_u32 s43, s43, 0
	s_add_u32 s64, s64, 0x100
	s_addc_u32 s65, s65, 0
	s_cmp_gt_u32 s66, 29
	s_cbranch_scc0 .LBB0_1394
	s_and_b64 vcc, exec, s[10:11]
	s_cbranch_vccz .LBB0_1397
	s_barrier

; __device__ __forceinline__ unsigned xb_ld(unsigned* p)              { return __hip_atomic_load(p, __ATOMIC_RELAXED, __HIP_MEMORY_SCOPE_AGENT); }
; __device__ __forceinline__ void xcd_barrier_complete(unsigned* bar, unsigned x, unsigned& nloc, unsigned& nx) {
;     const unsigned G = gridDim.x * gridDim.y * gridDim.z;
;     unsigned sum, cnt, mine, sp = 0u;
;     for (;;) {
;         sum = 0u; cnt = 0u; mine = 0u;
; #pragma unroll
;         for (unsigned j = 0; j < 16; ++j) { const unsigned c = xb_ld(&bar[XB_XCNT(j)]); sum += c; cnt += (c > 0u) ? 1u : 0u; mine = (j == x) ? c : mine; }
; __device__ __forceinline__ void xcd_barrier(const XcdBarrier& b) {
;     asm volatile("s_waitcnt vmcnt(0)" ::: "memory");
;     __syncthreads();
;     if (threadIdx.x == 0) {
;         unsigned* bar = b.bar;
;         __builtin_amdgcn_s_waitcnt(0);
;         unsigned nloc = b.st[0], nx = b.st[1];
;         if (nloc == 0u) { xcd_barrier_complete(bar, b.x, nloc, nx); b.st[0] = nloc; b.st[1] = nx; }
.LBB0_1401:
	s_setprio 0
	s_cmp_gt_i32 s81, 15
	s_cselect_b64 s[0:1], -1, 0
	s_and_b64 s[4:5], s[4:5], s[0:1]
	s_andn2_b64 vcc, exec, s[4:5]
	s_cbranch_vccnz .LBB0_1451
	s_waitcnt vmcnt(0)
	v_cmp_eq_u32_e32 vcc, 0, v146
	s_waitcnt vmcnt(0) lgkmcnt(0)
	s_barrier
	s_and_saveexec_b64 s[4:5], vcc
	s_cbranch_execz .LBB0_1450
	s_add_i32 s3, 0, 0x20040
	v_mov_b32_e32 v0, s3
	s_waitcnt vmcnt(0) expcnt(0) lgkmcnt(0)
	ds_read_b32 v2, v0
	s_add_i32 s3, 0, 0x20044
	v_mov_b32_e32 v0, s3
	ds_read_b32 v0, v0
	s_waitcnt lgkmcnt(1)
	v_cmp_ne_u32_e32 vcc, 0, v2
	s_cbranch_vccnz .LBB0_1418
	v_readlane_b32 s2, v231, 0
	v_readlane_b32 s3, v231, 1
	s_load_dwordx2 s[10:11], s[2:3], 0x4
	s_add_u32 s6, s22, 0x1000
	s_addc_u32 s7, s23, 0
	s_add_u32 s8, s22, 0x1100
	s_addc_u32 s9, s23, 0
	s_waitcnt lgkmcnt(0)
	s_mul_i32 s3, s10, s18
	s_add_u32 s10, s22, 0x1200
	s_mul_i32 s3, s3, s11
	s_addc_u32 s11, s23, 0
	s_add_u32 s12, s22, 0x1300
	s_addc_u32 s13, s23, 0
	s_mov_b32 s19, 1
	v_mov_b32_e32 v16, 0
	s_branch .LBB0_1406

; #define SEAM(k) do { if (IN(k) && IN((k) + 1)) { if ((k) == 0) { cg::this_grid().sync(); bar = xcd_barrier_post(barw, MISC); } else { xcd_barrier(bar); } } } while (0)
;     __host__ __device__ bool next(int i, Unit& u) const {
;         const long L = (long)i * G + c; if (L >= nwg) return false;
;         int wgid = (int)L; { const int q = nwg / NXCD, r = nwg % NXCD, xcd = wgid % NXCD, off = wgid / NXCD; wgid = (xcd < r ? xcd * (q + 1) : r * (q + 1) + (xcd - r) * q) + off; }
; __global__ void __launch_bounds__(NTHR, 2) fwd(Args args) {
;     ...
;     if (IN(15)) { gemm_res_ln(F, BIG, W2, DFF, F.out, F.in[6] + DM, F.in[7] + DM); } SEAM(15);
.LBB0_1451:
	s_cmp_lt_i32 s80, 16
	s_cselect_b64 s[4:5], -1, 0
	s_and_b64 s[4:5], s[4:5], s[0:1]
	s_andn2_b64 vcc, exec, s[4:5]
	s_cbranch_vccnz .LBB0_1476
	s_cmp_lt_u32 s82, 4
	s_cbranch_scc1 .Lprio_g15
	s_setprio 1
.Lprio_g15:
	s_cmpk_gt_i32 s84, 0x1ff
	v_readfirstlane_b32 s16, v146
	s_cbranch_scc1 .LBB0_1476
	s_ashr_i32 s3, s84, 31
	s_lshr_b32 s0, s3, 29
	s_add_i32 s8, s84, s0
	s_and_b32 s0, s8, -8
	s_sub_i32 s7, s84, s0
	s_cmp_gt_i32 s7, -1
	s_cbranch_scc0 .LBB0_1455
	s_lshl_b32 s6, s7, 6
	s_ashr_i32 s0, s8, 3
	s_cbranch_execz .LBB0_1456
	s_branch .LBB0_1457

; #define PG8_STAGE(bufoff, gbase, voff) do { _Pragma("unroll") for (int _i = 0; _i < 2; ++_i) \
;         __builtin_amdgcn_global_load_lds((const unsigned*)((const char*)(gbase) + (voff)[_i]), (PG8_LAS unsigned*)(lds + (bufoff) + ldsw + _i * 8192), 16, 0, 0); } while (0)
; #define PG8_LDA(dst, b, h) do { _Pragma("unroll") for (int m = 0; m < 4; ++m) _Pragma("unroll") for (int k = 0; k < 2; ++k) dst[m][k] = *(const PG8_LAS bf16x8*)(lds + PG8_SA(b, h) + aoff + m * 2048 + k * 1024); } while (0)
; #define PG8_LDB(dst, b, h) do { _Pragma("unroll") for (int n = 0; n < 2; ++n) _Pragma("unroll") for (int k = 0; k < 2; ++k) dst[n][k] = *(const PG8_LAS bf16x8*)(lds + PG8_SB(b, h) + boff + n * 2048 + k * 1024); } while (0)
; #define PG8_MMA(ai, bj, At, Bt) do { __builtin_amdgcn_s_setprio(1); _Pragma("unroll") for (int m = 0; m < 4; ++m) _Pragma("unroll") for (int n = 0; n < 2; ++n) _Pragma("unroll") for (int k = 0; k < 2; ++k) \
;         acc[ai][bj][m][n] = __builtin_amdgcn_mfma_f32_16x16x32_bf16(Bt[n][k], At[m][k], acc[ai][bj][m][n], 0, 0, 0); __builtin_amdgcn_s_setprio(0); } while (0)
; #define PG8_WAIT_V(n) asm volatile("s_waitcnt vmcnt(" #n ")" ::: "memory")
; #define PG8_WAIT_L(n) asm volatile("s_waitcnt lgkmcnt(" #n ")" ::: "memory")
; #define PG8_BAR __builtin_amdgcn_s_barrier()
; #define PG8_SCHED __builtin_amdgcn_sched_barrier(0)
; template <class Epi, class Sched, bool ALIGN_EPI = false, bool SP2 = false>
; __device__ __forceinline__ void gemm_phase(PG8_LAS unsigned char* lds, const Gemm g, const Sched& S, const Epi& E) {
;     ...
;         for (int t = 0; t < nt; t += 2) {
;             const bool last = (t == nt - 2);
;             const char* a1 = cA + (size_t)(t + 1) * kstep;
;             const char* a2 = last ? nA : cA + (size_t)(t + 2) * kstep; const char* b2 = last ? nB : cB + (size_t)(t + 2) * kstep;
;             const char* a3 = a2 + kstep; const char* b3 = b2 + kstep;
;             if (last && has_next) S.a_ready(nxt);
;             if constexpr (SP2) {
;             PG8_LDB(B0, 0, 0); PG8_LDB(B1, 0, 1); PG8_SCHED; PG8_LDA(At, 0, 0); PG8_STAGE(PG8_SA(1, 1), a1 + hstep, voffA);
;             PG8_WAIT_V(8); PG8_WAIT_L(0); PG8_BAR; PG8_MMA(0, 0, At, B0); PG8_MMA(0, 1, At, B1); PG8_BAR; PG8_SCHED;
;             PG8_LDA(At, 0, 1); PG8_STAGE(PG8_SB(0, 0), b2, voffB); PG8_STAGE(PG8_SB(0, 1), b2 + hstep, voffB); PG8_STAGE(PG8_SA(0, 0), a2, voffA);
.LBB0_1469:
	ds_read_b128 v[128:131], v181
	ds_read_b128 v[132:135], v181 offset:1024
	ds_read_b128 v[136:139], v181 offset:2048
	ds_read_b128 v[140:143], v181 offset:3072
	ds_read_b128 v[164:167], v182
	ds_read_b128 v[168:171], v182 offset:1024
	ds_read_b128 v[172:175], v182 offset:2048
	ds_read_b128 v[176:179], v182 offset:3072
	s_add_u32 s42, s40, 0xffe00080
	s_addc_u32 s43, s41, -1
	s_cmpk_eq_i32 s58, 0x7c
	s_cselect_b32 s45, s31, s43
	s_cselect_b32 s44, s54, s42
	s_cselect_b32 s43, s29, s57
	s_cselect_b32 s42, s55, s56
	v_lshl_add_u64 v[216:217], s[40:41], 0, v[156:157]
	s_add_i32 m0, s27, 0xc000
	ds_read_b128 v[184:187], v183
	ds_read_b128 v[188:191], v183 offset:1024
	ds_read_b128 v[192:195], v183 offset:2048
	ds_read_b128 v[196:199], v183 offset:3072
	ds_read_b128 v[200:203], v183 offset:4096
	ds_read_b128 v[204:207], v183 offset:5120
	ds_read_b128 v[208:211], v183 offset:6144
	ds_read_b128 v[212:215], v183 offset:7168
	global_load_lds_dwordx4 v[216:217], off
	v_lshl_add_u64 v[216:217], s[40:41], 0, v[158:159]
	s_add_i32 m0, s27, 0xe000
	s_nop 0
	global_load_lds_dwordx4 v[216:217], off
	s_waitcnt vmcnt(8)
	s_waitcnt lgkmcnt(0)
	s_barrier
	s_nop 0
	s_waitcnt lgkmcnt(0)
	v_mfma_f32_16x16x32_bf16 v[124:127], v[128:131], v[184:187], v[124:127]
	v_mfma_f32_16x16x32_bf16 v[120:123], v[136:139], v[184:187], v[120:123]
	v_mfma_f32_16x16x32_bf16 v[116:119], v[128:131], v[192:195], v[116:119]
	v_mfma_f32_16x16x32_bf16 v[112:115], v[136:139], v[192:195], v[112:115]
	v_mfma_f32_16x16x32_bf16 v[108:111], v[128:131], v[200:203], v[108:111]
	v_mfma_f32_16x16x32_bf16 v[104:107], v[136:139], v[200:203], v[104:107]
	v_mfma_f32_16x16x32_bf16 v[100:103], v[128:131], v[208:211], v[100:103]
	v_mfma_f32_16x16x32_bf16 v[96:99], v[136:139], v[208:211], v[96:99]
	v_mfma_f32_16x16x32_bf16 v[124:127], v[132:135], v[188:191], v[124:127]
	v_mfma_f32_16x16x32_bf16 v[120:123], v[140:143], v[188:191], v[120:123]
	v_mfma_f32_16x16x32_bf16 v[116:119], v[132:135], v[196:199], v[116:119]
	v_mfma_f32_16x16x32_bf16 v[112:115], v[140:143], v[196:199], v[112:115]
	v_mfma_f32_16x16x32_bf16 v[108:111], v[132:135], v[204:207], v[108:111]
	v_mfma_f32_16x16x32_bf16 v[104:107], v[140:143], v[204:207], v[104:107]
	v_mfma_f32_16x16x32_bf16 v[100:103], v[132:135], v[212:215], v[100:103]
	v_mfma_f32_16x16x32_bf16 v[96:99], v[140:143], v[212:215], v[96:99]
	s_nop 0
	s_nop 0
	v_mfma_f32_16x16x32_bf16 v[64:67], v[164:167], v[184:187], v[64:67]
	v_mfma_f32_16x16x32_bf16 v[56:59], v[172:175], v[184:187], v[56:59]
	v_mfma_f32_16x16x32_bf16 v[52:55], v[164:167], v[192:195], v[52:55]
	v_mfma_f32_16x16x32_bf16 v[48:51], v[172:175], v[192:195], v[48:51]
	v_mfma_f32_16x16x32_bf16 v[44:47], v[164:167], v[200:203], v[44:47]
	v_mfma_f32_16x16x32_bf16 v[40:43], v[172:175], v[200:203], v[40:43]
	v_mfma_f32_16x16x32_bf16 v[36:39], v[164:167], v[208:211], v[36:39]
	v_mfma_f32_16x16x32_bf16 v[32:35], v[172:175], v[208:211], v[32:35]
	v_mfma_f32_16x16x32_bf16 v[64:67], v[168:171], v[188:191], v[64:67]
	v_mfma_f32_16x16x32_bf16 v[56:59], v[176:179], v[188:191], v[56:59]
	v_mfma_f32_16x16x32_bf16 v[52:55], v[168:171], v[196:199], v[52:55]
	v_mfma_f32_16x16x32_bf16 v[48:51], v[176:179], v[196:199], v[48:51]
	v_mfma_f32_16x16x32_bf16 v[44:47], v[168:171], v[204:207], v[44:47]
	v_mfma_f32_16x16x32_bf16 v[40:43], v[176:179], v[204:207], v[40:43]
	v_mfma_f32_16x16x32_bf16 v[36:39], v[168:171], v[212:215], v[36:39]
	v_mfma_f32_16x16x32_bf16 v[32:35], v[176:179], v[212:215], v[32:35]
	s_nop 0
	s_barrier
	s_add_i32 s59, s51, s19
	v_lshl_add_u64 v[216:217], s[42:43], 0, v[150:151]
	s_mov_b32 m0, s59
	ds_read_b128 v[184:187], v183 offset:16384
	ds_read_b128 v[188:191], v183 offset:17408
	ds_read_b128 v[192:195], v183 offset:18432
	ds_read_b128 v[196:199], v183 offset:19456
	ds_read_b128 v[200:203], v183 offset:20480
	ds_read_b128 v[204:207], v183 offset:21504
	ds_read_b128 v[208:211], v183 offset:22528
	ds_read_b128 v[212:215], v183 offset:23552
	global_load_lds_dwordx4 v[216:217], off
	s_add_i32 m0, s59, 0x2000
	s_add_u32 s60, s42, 0x200000
	v_lshl_add_u64 v[218:219], s[42:43], 0, v[154:155]
	s_addc_u32 s61, s43, 0
	s_add_i32 s59, s52, s19
	global_load_lds_dwordx4 v[218:219], off
	v_lshl_add_u64 v[220:221], s[60:61], 0, v[150:151]
	s_mov_b32 m0, s59
	v_lshl_add_u64 v[222:223], s[44:45], 0, v[152:153]
	global_load_lds_dwordx4 v[220:221], off
	v_lshl_add_u64 v[220:221], s[60:61], 0, v[154:155]
	s_add_i32 m0, s59, 0x2000
	s_nop 0
	global_load_lds_dwordx4 v[220:221], off
	v_lshl_add_u64 v[220:221], s[44:45], 0, v[148:149]
	s_mov_b32 m0, s27
	s_nop 0
	global_load_lds_dwordx4 v[220:221], off
	s_mov_b32 m0, s33
	s_nop 0
	global_load_lds_dwordx4 v[222:223], off
	s_waitcnt vmcnt(8)
	s_waitcnt lgkmcnt(0)
	s_barrier
; #define PG8_STAGE(bufoff, gbase, voff) do { _Pragma("unroll") for (int _i = 0; _i < 2; ++_i) \
;         __builtin_amdgcn_global_load_lds((const unsigned*)((const char*)(gbase) + (voff)[_i]), (PG8_LAS unsigned*)(lds + (bufoff) + ldsw + _i * 8192), 16, 0, 0); } while (0)
; #define PG8_LDA(dst, b, h) do { _Pragma("unroll") for (int m = 0; m < 4; ++m) _Pragma("unroll") for (int k = 0; k < 2; ++k) dst[m][k] = *(const PG8_LAS bf16x8*)(lds + PG8_SA(b, h) + aoff + m * 2048 + k * 1024); } while (0)
; #define PG8_LDB(dst, b, h) do { _Pragma("unroll") for (int n = 0; n < 2; ++n) _Pragma("unroll") for (int k = 0; k < 2; ++k) dst[n][k] = *(const PG8_LAS bf16x8*)(lds + PG8_SB(b, h) + boff + n * 2048 + k * 1024); } while (0)
; #define PG8_MMA(ai, bj, At, Bt) do { __builtin_amdgcn_s_setprio(1); _Pragma("unroll") for (int m = 0; m < 4; ++m) _Pragma("unroll") for (int n = 0; n < 2; ++n) _Pragma("unroll") for (int k = 0; k < 2; ++k) \
;         acc[ai][bj][m][n] = __builtin_amdgcn_mfma_f32_16x16x32_bf16(Bt[n][k], At[m][k], acc[ai][bj][m][n], 0, 0, 0); __builtin_amdgcn_s_setprio(0); } while (0)
; #define PG8_WAIT_V(n) asm volatile("s_waitcnt vmcnt(" #n ")" ::: "memory")
; #define PG8_WAIT_L(n) asm volatile("s_waitcnt lgkmcnt(" #n ")" ::: "memory")
; #define PG8_BAR __builtin_amdgcn_s_barrier()
; #define PG8_SCHED __builtin_amdgcn_sched_barrier(0)
; template <class Epi, class Sched, bool ALIGN_EPI = false, bool SP2 = false>
; __device__ __forceinline__ void gemm_phase(PG8_LAS unsigned char* lds, const Gemm g, const Sched& S, const Epi& E) {
;     ...
;             PG8_WAIT_V(8); PG8_WAIT_L(0); PG8_BAR; PG8_MMA(1, 0, At, B0); PG8_MMA(1, 1, At, B1); PG8_BAR; PG8_SCHED;
;             PG8_LDB(B0, 1, 0); PG8_LDB(B1, 1, 1); PG8_SCHED; PG8_LDA(At, 1, 0); PG8_STAGE(PG8_SA(0, 1), a2 + hstep, voffA);
;             PG8_WAIT_V(8); PG8_WAIT_L(0); PG8_BAR; PG8_MMA(0, 0, At, B0); PG8_MMA(0, 1, At, B1); PG8_BAR; PG8_SCHED;
	s_nop 0
	s_waitcnt lgkmcnt(0)
	v_mfma_f32_16x16x32_bf16 v[92:95], v[128:131], v[184:187], v[92:95]
	v_mfma_f32_16x16x32_bf16 v[88:91], v[136:139], v[184:187], v[88:91]
	v_mfma_f32_16x16x32_bf16 v[84:87], v[128:131], v[192:195], v[84:87]
	v_mfma_f32_16x16x32_bf16 v[80:83], v[136:139], v[192:195], v[80:83]
	v_mfma_f32_16x16x32_bf16 v[76:79], v[128:131], v[200:203], v[76:79]
	v_mfma_f32_16x16x32_bf16 v[72:75], v[136:139], v[200:203], v[72:75]
	v_mfma_f32_16x16x32_bf16 v[68:71], v[128:131], v[208:211], v[68:71]
	v_mfma_f32_16x16x32_bf16 v[60:63], v[136:139], v[208:211], v[60:63]
	v_mfma_f32_16x16x32_bf16 v[92:95], v[132:135], v[188:191], v[92:95]
	v_mfma_f32_16x16x32_bf16 v[88:91], v[140:143], v[188:191], v[88:91]
	v_mfma_f32_16x16x32_bf16 v[84:87], v[132:135], v[196:199], v[84:87]
	v_mfma_f32_16x16x32_bf16 v[80:83], v[140:143], v[196:199], v[80:83]
	v_mfma_f32_16x16x32_bf16 v[76:79], v[132:135], v[204:207], v[76:79]
	v_mfma_f32_16x16x32_bf16 v[72:75], v[140:143], v[204:207], v[72:75]
	v_mfma_f32_16x16x32_bf16 v[68:71], v[132:135], v[212:215], v[68:71]
	v_mfma_f32_16x16x32_bf16 v[60:63], v[140:143], v[212:215], v[60:63]
	s_nop 0
	s_nop 0
	v_mfma_f32_16x16x32_bf16 v[28:31], v[164:167], v[184:187], v[28:31]
	v_mfma_f32_16x16x32_bf16 v[24:27], v[172:175], v[184:187], v[24:27]
	v_mfma_f32_16x16x32_bf16 v[20:23], v[164:167], v[192:195], v[20:23]
	v_mfma_f32_16x16x32_bf16 v[16:19], v[172:175], v[192:195], v[16:19]
	v_mfma_f32_16x16x32_bf16 v[12:15], v[164:167], v[200:203], v[12:15]
	v_mfma_f32_16x16x32_bf16 v[8:11], v[172:175], v[200:203], v[8:11]
	v_mfma_f32_16x16x32_bf16 v[4:7], v[164:167], v[208:211], v[4:7]
	v_mfma_f32_16x16x32_bf16 v[0:3], v[172:175], v[208:211], v[0:3]
	v_mfma_f32_16x16x32_bf16 v[28:31], v[168:171], v[188:191], v[28:31]
	v_mfma_f32_16x16x32_bf16 v[24:27], v[176:179], v[188:191], v[24:27]
	v_mfma_f32_16x16x32_bf16 v[20:23], v[168:171], v[196:199], v[20:23]
	v_mfma_f32_16x16x32_bf16 v[16:19], v[176:179], v[196:199], v[16:19]
	v_mfma_f32_16x16x32_bf16 v[12:15], v[168:171], v[204:207], v[12:15]
	v_mfma_f32_16x16x32_bf16 v[8:11], v[176:179], v[204:207], v[8:11]
	v_mfma_f32_16x16x32_bf16 v[4:7], v[168:171], v[212:215], v[4:7]
	v_mfma_f32_16x16x32_bf16 v[0:3], v[176:179], v[212:215], v[0:3]
	s_nop 0
	s_barrier
	s_add_i32 s59, 0, 0x18000
	s_add_i32 s60, 0, 0x1c000
	v_add_u32_e32 v140, s59, v147
	v_add_u32_e32 v176, s60, v147
	ds_read_b128 v[128:131], v140
	ds_read_b128 v[132:135], v140 offset:1024
	ds_read_b128 v[136:139], v140 offset:2048
	ds_read_b128 v[140:143], v140 offset:3072
	ds_read_b128 v[164:167], v176
	ds_read_b128 v[168:171], v176 offset:1024
	ds_read_b128 v[172:175], v176 offset:2048
	ds_read_b128 v[176:179], v176 offset:3072
	s_add_u32 s44, s44, 0x200000
	s_addc_u32 s45, s45, 0
	s_mov_b32 m0, s39
	v_lshl_add_u64 v[224:225], s[44:45], 0, v[148:149]
	ds_read_b128 v[184:187], v183 offset:32768
	ds_read_b128 v[188:191], v183 offset:33792
	ds_read_b128 v[192:195], v183 offset:34816
	ds_read_b128 v[196:199], v183 offset:35840
	ds_read_b128 v[200:203], v183 offset:36864
	ds_read_b128 v[204:207], v183 offset:37888
	ds_read_b128 v[208:211], v183 offset:38912
	ds_read_b128 v[212:215], v183 offset:39936
	global_load_lds_dwordx4 v[224:225], off
	v_lshl_add_u64 v[224:225], s[44:45], 0, v[152:153]
	s_mov_b32 m0, s46
	s_nop 0
	global_load_lds_dwordx4 v[224:225], off
	s_waitcnt vmcnt(8)
	s_waitcnt lgkmcnt(0)
	s_barrier
	s_nop 0
	s_waitcnt lgkmcnt(0)
	v_mfma_f32_16x16x32_bf16 v[124:127], v[128:131], v[184:187], v[124:127]
	v_mfma_f32_16x16x32_bf16 v[120:123], v[136:139], v[184:187], v[120:123]
	v_mfma_f32_16x16x32_bf16 v[116:119], v[128:131], v[192:195], v[116:119]
	v_mfma_f32_16x16x32_bf16 v[112:115], v[136:139], v[192:195], v[112:115]
	v_mfma_f32_16x16x32_bf16 v[108:111], v[128:131], v[200:203], v[108:111]
	v_mfma_f32_16x16x32_bf16 v[104:107], v[136:139], v[200:203], v[104:107]
	v_mfma_f32_16x16x32_bf16 v[100:103], v[128:131], v[208:211], v[100:103]
	v_mfma_f32_16x16x32_bf16 v[96:99], v[136:139], v[208:211], v[96:99]
	v_mfma_f32_16x16x32_bf16 v[124:127], v[132:135], v[188:191], v[124:127]
	v_mfma_f32_16x16x32_bf16 v[120:123], v[140:143], v[188:191], v[120:123]
	v_mfma_f32_16x16x32_bf16 v[116:119], v[132:135], v[196:199], v[116:119]
	v_mfma_f32_16x16x32_bf16 v[112:115], v[140:143], v[196:199], v[112:115]
	v_mfma_f32_16x16x32_bf16 v[108:111], v[132:135], v[204:207], v[108:111]
	v_mfma_f32_16x16x32_bf16 v[104:107], v[140:143], v[204:207], v[104:107]
	v_mfma_f32_16x16x32_bf16 v[100:103], v[132:135], v[212:215], v[100:103]
	v_mfma_f32_16x16x32_bf16 v[96:99], v[140:143], v[212:215], v[96:99]
	s_nop 0
	s_nop 0
	v_mfma_f32_16x16x32_bf16 v[64:67], v[164:167], v[184:187], v[64:67]
	v_mfma_f32_16x16x32_bf16 v[56:59], v[172:175], v[184:187], v[56:59]
	v_mfma_f32_16x16x32_bf16 v[52:55], v[164:167], v[192:195], v[52:55]
	v_mfma_f32_16x16x32_bf16 v[48:51], v[172:175], v[192:195], v[48:51]
	v_mfma_f32_16x16x32_bf16 v[44:47], v[164:167], v[200:203], v[44:47]
	v_mfma_f32_16x16x32_bf16 v[40:43], v[172:175], v[200:203], v[40:43]
	v_mfma_f32_16x16x32_bf16 v[36:39], v[164:167], v[208:211], v[36:39]
	v_mfma_f32_16x16x32_bf16 v[32:35], v[172:175], v[208:211], v[32:35]
	v_mfma_f32_16x16x32_bf16 v[64:67], v[168:171], v[188:191], v[64:67]
	v_mfma_f32_16x16x32_bf16 v[56:59], v[176:179], v[188:191], v[56:59]
	v_mfma_f32_16x16x32_bf16 v[52:55], v[168:171], v[196:199], v[52:55]
	v_mfma_f32_16x16x32_bf16 v[48:51], v[176:179], v[196:199], v[48:51]
	v_mfma_f32_16x16x32_bf16 v[44:47], v[168:171], v[204:207], v[44:47]
	v_mfma_f32_16x16x32_bf16 v[40:43], v[176:179], v[204:207], v[40:43]
	v_mfma_f32_16x16x32_bf16 v[36:39], v[168:171], v[212:215], v[36:39]
	v_mfma_f32_16x16x32_bf16 v[32:35], v[176:179], v[212:215], v[32:35]
	s_nop 0
	s_barrier
; #define PG8_STAGE(bufoff, gbase, voff) do { _Pragma("unroll") for (int _i = 0; _i < 2; ++_i) \
;         __builtin_amdgcn_global_load_lds((const unsigned*)((const char*)(gbase) + (voff)[_i]), (PG8_LAS unsigned*)(lds + (bufoff) + ldsw + _i * 8192), 16, 0, 0); } while (0)
; #define PG8_LDA(dst, b, h) do { _Pragma("unroll") for (int m = 0; m < 4; ++m) _Pragma("unroll") for (int k = 0; k < 2; ++k) dst[m][k] = *(const PG8_LAS bf16x8*)(lds + PG8_SA(b, h) + aoff + m * 2048 + k * 1024); } while (0)
; #define PG8_MMA(ai, bj, At, Bt) do { __builtin_amdgcn_s_setprio(1); _Pragma("unroll") for (int m = 0; m < 4; ++m) _Pragma("unroll") for (int n = 0; n < 2; ++n) _Pragma("unroll") for (int k = 0; k < 2; ++k) \
;         acc[ai][bj][m][n] = __builtin_amdgcn_mfma_f32_16x16x32_bf16(Bt[n][k], At[m][k], acc[ai][bj][m][n], 0, 0, 0); __builtin_amdgcn_s_setprio(0); } while (0)
; #define PG8_WAIT_V(n) asm volatile("s_waitcnt vmcnt(" #n ")" ::: "memory")
; #define PG8_WAIT_L(n) asm volatile("s_waitcnt lgkmcnt(" #n ")" ::: "memory")
; #define PG8_BAR __builtin_amdgcn_s_barrier()
; #define PG8_SCHED __builtin_amdgcn_sched_barrier(0)
; template <class Epi, class Sched, bool ALIGN_EPI = false, bool SP2 = false>
; __device__ __forceinline__ void gemm_phase(PG8_LAS unsigned char* lds, const Gemm g, const Sched& S, const Epi& E) {
;     ...
;         for (int t = 0; t < nt; t += 2) {
;             const bool last = (t == nt - 2);
;     ...
;             PG8_LDA(At, 1, 1); PG8_STAGE(PG8_SB(1, 0), b3, voffB); PG8_STAGE(PG8_SB(1, 1), b3 + hstep, voffB); PG8_STAGE(PG8_SA(1, 0), a3, voffA);
;             PG8_WAIT_V(8); PG8_WAIT_L(0); PG8_BAR; PG8_MMA(1, 0, At, B0); PG8_MMA(1, 1, At, B1); PG8_BAR; PG8_SCHED;
	s_add_i32 s44, s59, s19
	v_lshl_add_u64 v[216:217], v[216:217], 0, s[14:15]
	s_mov_b32 m0, s44
	ds_read_b128 v[184:187], v183 offset:49152
	ds_read_b128 v[188:191], v183 offset:50176
	ds_read_b128 v[192:195], v183 offset:51200
	ds_read_b128 v[196:199], v183 offset:52224
	ds_read_b128 v[200:203], v183 offset:53248
	ds_read_b128 v[204:207], v183 offset:54272
	ds_read_b128 v[208:211], v183 offset:55296
	ds_read_b128 v[212:215], v183 offset:56320
	global_load_lds_dwordx4 v[216:217], off
	s_add_i32 m0, s44, 0x2000
	s_add_u32 s42, s42, 0x200080
	v_lshl_add_u64 v[216:217], v[218:219], 0, s[14:15]
	s_addc_u32 s43, s43, 0
	s_add_i32 s44, s60, s19
	global_load_lds_dwordx4 v[216:217], off
	v_lshl_add_u64 v[216:217], s[42:43], 0, v[150:151]
	s_mov_b32 m0, s44
	s_nop 0
	global_load_lds_dwordx4 v[216:217], off
	v_lshl_add_u64 v[216:217], s[42:43], 0, v[154:155]
	s_add_i32 m0, s44, 0x2000
	s_nop 0
	global_load_lds_dwordx4 v[216:217], off
	v_lshl_add_u64 v[216:217], v[220:221], 0, s[14:15]
	s_mov_b32 m0, s48
	s_nop 0
	global_load_lds_dwordx4 v[216:217], off
	v_lshl_add_u64 v[216:217], v[222:223], 0, s[14:15]
	s_mov_b32 m0, s49
	s_nop 0
	global_load_lds_dwordx4 v[216:217], off
	s_waitcnt vmcnt(8)
	s_waitcnt lgkmcnt(0)
	s_barrier
	s_nop 0
	s_waitcnt lgkmcnt(0)
	v_mfma_f32_16x16x32_bf16 v[92:95], v[128:131], v[184:187], v[92:95]
	v_mfma_f32_16x16x32_bf16 v[88:91], v[136:139], v[184:187], v[88:91]
	v_mfma_f32_16x16x32_bf16 v[84:87], v[128:131], v[192:195], v[84:87]
	v_mfma_f32_16x16x32_bf16 v[80:83], v[136:139], v[192:195], v[80:83]
	v_mfma_f32_16x16x32_bf16 v[76:79], v[128:131], v[200:203], v[76:79]
	v_mfma_f32_16x16x32_bf16 v[72:75], v[136:139], v[200:203], v[72:75]
	v_mfma_f32_16x16x32_bf16 v[68:71], v[128:131], v[208:211], v[68:71]
	v_mfma_f32_16x16x32_bf16 v[60:63], v[136:139], v[208:211], v[60:63]
	v_mfma_f32_16x16x32_bf16 v[92:95], v[132:135], v[188:191], v[92:95]
	v_mfma_f32_16x16x32_bf16 v[88:91], v[140:143], v[188:191], v[88:91]
	v_mfma_f32_16x16x32_bf16 v[84:87], v[132:135], v[196:199], v[84:87]
	v_mfma_f32_16x16x32_bf16 v[80:83], v[140:143], v[196:199], v[80:83]
	v_mfma_f32_16x16x32_bf16 v[76:79], v[132:135], v[204:207], v[76:79]
	v_mfma_f32_16x16x32_bf16 v[72:75], v[140:143], v[204:207], v[72:75]
	v_mfma_f32_16x16x32_bf16 v[68:71], v[132:135], v[212:215], v[68:71]
	v_mfma_f32_16x16x32_bf16 v[60:63], v[140:143], v[212:215], v[60:63]
	s_nop 0
	s_nop 0
	v_mfma_f32_16x16x32_bf16 v[28:31], v[164:167], v[184:187], v[28:31]
	v_mfma_f32_16x16x32_bf16 v[24:27], v[172:175], v[184:187], v[24:27]
	v_mfma_f32_16x16x32_bf16 v[20:23], v[164:167], v[192:195], v[20:23]
	v_mfma_f32_16x16x32_bf16 v[16:19], v[172:175], v[192:195], v[16:19]
	v_mfma_f32_16x16x32_bf16 v[12:15], v[164:167], v[200:203], v[12:15]
	v_mfma_f32_16x16x32_bf16 v[8:11], v[172:175], v[200:203], v[8:11]
	v_mfma_f32_16x16x32_bf16 v[4:7], v[164:167], v[208:211], v[4:7]
	v_mfma_f32_16x16x32_bf16 v[0:3], v[172:175], v[208:211], v[0:3]
	v_mfma_f32_16x16x32_bf16 v[28:31], v[168:171], v[188:191], v[28:31]
	v_mfma_f32_16x16x32_bf16 v[24:27], v[176:179], v[188:191], v[24:27]
	v_mfma_f32_16x16x32_bf16 v[20:23], v[168:171], v[196:199], v[20:23]
	v_mfma_f32_16x16x32_bf16 v[16:19], v[176:179], v[196:199], v[16:19]
	v_mfma_f32_16x16x32_bf16 v[12:15], v[168:171], v[204:207], v[12:15]
	v_mfma_f32_16x16x32_bf16 v[8:11], v[176:179], v[204:207], v[8:11]
	v_mfma_f32_16x16x32_bf16 v[4:7], v[168:171], v[212:215], v[4:7]
	v_mfma_f32_16x16x32_bf16 v[0:3], v[176:179], v[212:215], v[0:3]
	s_nop 0
	s_barrier
	s_add_i32 s58, s58, 2
	s_add_u32 s40, s40, 0x100
	s_addc_u32 s41, s41, 0
	s_add_u32 s56, s56, 0x100
	s_addc_u32 s57, s57, 0
	s_cmpk_gt_u32 s58, 0x7d
	s_cbranch_scc0 .LBB0_1469
	s_and_b64 vcc, exec, s[16:17]
	s_cbranch_vccz .LBB0_1472
	s_barrier

; __device__ __forceinline__ unsigned xb_ld(unsigned* p)              { return __hip_atomic_load(p, __ATOMIC_RELAXED, __HIP_MEMORY_SCOPE_AGENT); }
; __device__ __forceinline__ void xcd_barrier_complete(unsigned* bar, unsigned x, unsigned& nloc, unsigned& nx) {
;     const unsigned G = gridDim.x * gridDim.y * gridDim.z;
;     unsigned sum, cnt, mine, sp = 0u;
;     for (;;) {
;         sum = 0u; cnt = 0u; mine = 0u;
; #pragma unroll
;         for (unsigned j = 0; j < 16; ++j) { const unsigned c = xb_ld(&bar[XB_XCNT(j)]); sum += c; cnt += (c > 0u) ? 1u : 0u; mine = (j == x) ? c : mine; }
; __device__ __forceinline__ void xcd_barrier(const XcdBarrier& b) {
;     asm volatile("s_waitcnt vmcnt(0)" ::: "memory");
;     __syncthreads();
;     if (threadIdx.x == 0) {
;         unsigned* bar = b.bar;
;         __builtin_amdgcn_s_waitcnt(0);
;         unsigned nloc = b.st[0], nx = b.st[1];
;         if (nloc == 0u) { xcd_barrier_complete(bar, b.x, nloc, nx); b.st[0] = nloc; b.st[1] = nx; }
.LBB0_1476:
	s_setprio 0
	s_cmp_gt_i32 s81, 16
	s_cselect_b64 s[0:1], -1, 0
	s_and_b64 s[4:5], s[4:5], s[0:1]
	s_andn2_b64 vcc, exec, s[4:5]
	s_cbranch_vccnz .LBB0_1526
	s_waitcnt vmcnt(0)
	v_cmp_eq_u32_e32 vcc, 0, v146
	s_waitcnt vmcnt(0) lgkmcnt(0)
	s_barrier
	s_and_saveexec_b64 s[4:5], vcc
	s_cbranch_execz .LBB0_1525
	s_add_i32 s3, 0, 0x20040
	v_mov_b32_e32 v0, s3
	s_waitcnt vmcnt(0) expcnt(0) lgkmcnt(0)
	ds_read_b32 v2, v0
	s_add_i32 s3, 0, 0x20044
	v_mov_b32_e32 v0, s3
	ds_read_b32 v0, v0
	s_waitcnt lgkmcnt(1)
	v_cmp_ne_u32_e32 vcc, 0, v2
	s_cbranch_vccnz .LBB0_1493
	v_readlane_b32 s2, v231, 0
	v_readlane_b32 s3, v231, 1
	s_load_dwordx2 s[10:11], s[2:3], 0x4
	s_add_u32 s6, s22, 0x1000
	s_addc_u32 s7, s23, 0
	s_add_u32 s8, s22, 0x1100
	s_addc_u32 s9, s23, 0
	s_waitcnt lgkmcnt(0)
	s_mul_i32 s3, s10, s18
	s_add_u32 s10, s22, 0x1200
	s_mul_i32 s3, s3, s11
	s_addc_u32 s11, s23, 0
	s_add_u32 s12, s22, 0x1300
	s_addc_u32 s13, s23, 0
	s_mov_b32 s19, 1
	v_mov_b32_e32 v16, 0
	s_branch .LBB0_1481
